# attention: branch 0/1 as pairs of adjacent query tiles sharing K/V loads (streamed register windows), branch 2 single tiles; new K/V row permutation; pass1 prefetch
# speedup vs baseline: 1.0284x; 1.0284x over previous
.LBB0_330:
	s_cmpk_eq_i32 s22, 0x3c0
	s_cbranch_scc1 .Lp1_nopf
	s_add_i32 s40, s11, s22
	s_add_i32 s40, s40, 64
	s_add_i32 s41, s24, 15
	s_and_b64 s[42:43], s[12:13], exec
	s_cselect_b32 s40, s40, s41
	s_movk_i32 s42, 0x1400
	s_cselect_b32 s42, s42, 0xffffec00
	s_mul_hi_i32 s41, s40, 0x1400
	s_mulk_i32 s40, 0x1400
	s_add_u32 s40, s82, s40
	s_addc_u32 s41, s83, s41
	s_ashr_i32 s43, s42, 31
	global_load_ushort v206, v85, s[40:41] nt
	global_load_ushort v222, v86, s[40:41] offset:3072 nt
	s_add_u32 s40, s40, s42
	s_addc_u32 s41, s41, s43
	global_load_ushort v207, v85, s[40:41] nt
	global_load_ushort v223, v86, s[40:41] offset:3072 nt
	s_add_u32 s40, s40, s42
	s_addc_u32 s41, s41, s43
	global_load_ushort v208, v85, s[40:41] nt
	global_load_ushort v224, v86, s[40:41] offset:3072 nt
	s_add_u32 s40, s40, s42
	s_addc_u32 s41, s41, s43
	global_load_ushort v209, v85, s[40:41] nt
	global_load_ushort v225, v86, s[40:41] offset:3072 nt
	s_add_u32 s40, s40, s42
	s_addc_u32 s41, s41, s43
	global_load_ushort v210, v85, s[40:41] nt
	global_load_ushort v226, v86, s[40:41] offset:3072 nt
	s_add_u32 s40, s40, s42
	s_addc_u32 s41, s41, s43
	global_load_ushort v211, v85, s[40:41] nt
	global_load_ushort v227, v86, s[40:41] offset:3072 nt
	s_add_u32 s40, s40, s42
	s_addc_u32 s41, s41, s43
	global_load_ushort v212, v85, s[40:41] nt
	global_load_ushort v228, v86, s[40:41] offset:3072 nt
	s_add_u32 s40, s40, s42
	s_addc_u32 s41, s41, s43
	global_load_ushort v213, v85, s[40:41] nt
	global_load_ushort v229, v86, s[40:41] offset:3072 nt
	s_add_u32 s40, s40, s42
	s_addc_u32 s41, s41, s43
	global_load_ushort v214, v85, s[40:41] nt
	global_load_ushort v230, v86, s[40:41] offset:3072 nt
	s_add_u32 s40, s40, s42
	s_addc_u32 s41, s41, s43
	global_load_ushort v215, v85, s[40:41] nt
	global_load_ushort v231, v86, s[40:41] offset:3072 nt
	s_add_u32 s40, s40, s42
	s_addc_u32 s41, s41, s43
	global_load_ushort v216, v85, s[40:41] nt
	global_load_ushort v232, v86, s[40:41] offset:3072 nt
	s_add_u32 s40, s40, s42
	s_addc_u32 s41, s41, s43
	global_load_ushort v217, v85, s[40:41] nt
	global_load_ushort v233, v86, s[40:41] offset:3072 nt
	s_add_u32 s40, s40, s42
	s_addc_u32 s41, s41, s43
	global_load_ushort v218, v85, s[40:41] nt
	global_load_ushort v234, v86, s[40:41] offset:3072 nt
	s_add_u32 s40, s40, s42
	s_addc_u32 s41, s41, s43
	global_load_ushort v219, v85, s[40:41] nt
	global_load_ushort v235, v86, s[40:41] offset:3072 nt
	s_add_u32 s40, s40, s42
	s_addc_u32 s41, s41, s43
	global_load_ushort v220, v85, s[40:41] nt
	global_load_ushort v236, v86, s[40:41] offset:3072 nt
	s_add_u32 s40, s40, s42
	s_addc_u32 s41, s41, s43
	global_load_ushort v221, v85, s[40:41] nt
	global_load_ushort v237, v86, s[40:41] offset:3072 nt

.Latt_entry:
	s_mov_b64 exec, -1
	v_readlane_b32 s4, v254, 0
	v_readlane_b32 s5, v254, 1
	v_readlane_b32 s6, v254, 42
	v_readlane_b32 s7, v254, 43
	v_readlane_b32 s8, v254, 46
	v_readlane_b32 s10, v254, 53
	v_readfirstlane_b32 s0, v145
	s_movk_i32 s78, 0x90
	s_movk_i32 s79, 0x110
	s_mov_b32 s80, 0x12100
	s_movk_i32 s82, 0x4000
	s_movk_i32 s83, 0x1000
	s_mov_b32 s84, 0xc000
	s_mov_b32 s85, 0x7ffff000
	s_lshr_b32 s0, s0, 6
	s_mul_i32 s1, s0, 0x1200
	s_add_i32 s1, s1, 0x12500
	s_mov_b32 s37, 0
	v_and_b32_e32 v142, 63, v145
	v_and_b32_e32 v160, 15, v145
	v_bfe_u32 v134, v145, 4, 2
	v_lshlrev_b32_e32 v161, 4, v134
	v_lshlrev_b32_e32 v169, 2, v134
	v_and_b32_e32 v135, 7, v145
	v_lshlrev_b32_e32 v162, 4, v135
	v_bfe_u32 v164, v145, 3, 3
	v_mad_u32_u24 v165, v164, s78, v162
	v_add_u32_e32 v165, s1, v165
	v_bfe_u32 v134, v145, 2, 2
	v_add_u32_e32 v134, v134, v169
	v_and_b32_e32 v135, 3, v145
	v_lshlrev_b32_e32 v135, 3, v135
	v_mad_u32_u24 v166, v134, s78, v135
	v_add_u32_e32 v166, s1, v166
	v_xor_b32_e32 v134, 16, v142
	v_lshlrev_b32_e32 v167, 2, v134
	v_xor_b32_e32 v134, 32, v142
	v_lshlrev_b32_e32 v168, 2, v134
	v_sub_u32_e32 v134, v169, v160
	v_cmp_ge_i32_e64 s[54:55], v134, 0
	v_cmp_le_i32_e64 s[62:63], v134, 0
	v_cmp_ge_i32_e64 s[56:57], v134, -1
	v_cmp_le_i32_e64 s[64:65], v134, -1
	v_cmp_ge_i32_e64 s[58:59], v134, -2
	v_cmp_le_i32_e64 s[66:67], v134, -2
	v_cmp_ge_i32_e64 s[60:61], v134, -3
	v_cmp_le_i32_e64 s[68:69], v134, -3
	v_lshrrev_b32_e32 v134, 1, v145
	v_lshrrev_b32_e32 v135, 4, v134
	v_add_u32_e32 v135, v135, v134
	v_and_b32_e32 v136, 1, v145
	v_lshlrev_b32_e32 v137, 7, v136
	v_mad_u32_u24 v170, v135, s79, v137
	v_lshl_add_u32 v171, v134, 2, s80
	v_lshlrev_b32_e32 v135, 11, v134
	v_lshl_add_u32 v172, v136, 6, v135
	v_mov_b32_e32 v130, 0
	v_mov_b32_e32 v131, 0
	v_mov_b32_e32 v184, 0
	v_mov_b32_e32 v185, 0
	s_lshr_b32 s2, s10, 3
	s_and_b32 s3, s10, 7
	s_and_b32 s30, s2, 31
	s_lshl_b32 s31, s3, 5
	s_or_b32 s31, s31, s30
	s_lshr_b32 s30, s10, 8
	s_cmp_eq_u32 s8, 0x100
	s_cselect_b32 s2, s31, s2
	s_cselect_b32 s17, s30, s3
	s_lshl_b32 s16, s2, 8
	s_cmp_lt_u32 s2, 0x80
	s_cselect_b32 s12, s82, s83
	s_cselect_b32 s13, 12, 10
	s_cselect_b32 s3, s84, s85
	s_and_b32 s3, s16, s3
	s_sub_i32 s15, s16, s3
	s_lshr_b32 s30, s12, 4
	s_add_i32 s14, s30, -1
	s_lshl_b32 s30, s17, 23
	s_lshl_b32 s3, s3, 7
	s_add_u32 s30, s30, s3
	s_add_u32 s18, s4, s30
	s_addc_u32 s19, s5, 0
	s_add_u32 s20, s18, 0x4000000
	s_addc_u32 s21, s19, 0
	s_add_u32 s22, s18, 0x8000000
	s_addc_u32 s23, s19, 0
	s_lshl_b32 s2, s0, 5
	s_add_i32 s42, s15, s2
	s_mov_b32 s43, 0
	v_add_u32_e32 v134, s42, v160
	v_add_u32_e32 v134, s43, v134
	v_subrev_u32_e32 v135, s15, v134
	v_lshrrev_b32_e32 v136, 4, v135
	v_add_u32_e32 v136, v136, v135
	v_mad_u32_u24 v176, v136, s79, v161
	v_lshl_add_u32 v177, v135, 2, s80
	s_sub_i32 s2, s42, 64
	v_add_u32_e32 v178, s2, v169
	v_and_b32_e32 v135, 3, v134
	v_lshlrev_b32_e32 v135, s13, v135
	v_lshrrev_b32_e32 v136, 2, v134
	v_add_u32_e32 v135, v135, v136
	v_lshl_add_u32 v135, v135, 7, v161
	global_load_dwordx4 v[48:51], v135, s[18:19]
	global_load_dwordx4 v[52:55], v135, s[18:19] offset:64
	v_add_u32_e32 v137, 16, v134
	v_and_b32_e32 v135, 3, v137
	v_lshlrev_b32_e32 v135, s13, v135
	v_lshrrev_b32_e32 v136, 2, v137
	v_add_u32_e32 v135, v135, v136
	v_lshl_add_u32 v135, v135, 7, v161
	global_load_dwordx4 v[56:59], v135, s[18:19]
	global_load_dwordx4 v[60:63], v135, s[18:19] offset:64
	v_subrev_u32_e32 v134, 64, v134
	v_and_b32_e32 v137, 3, v134
	v_lshlrev_b32_e32 v137, s13, v137
	v_bfe_u32 v135, v134, 2, 2
	v_add_u32_e32 v137, v137, v135
	v_lshl_add_u32 v183, v137, 7, v161
	v_ashrrev_i32_e32 v252, 4, v134
	v_med3_i32 v136, v252, 0, s14
	v_lshl_add_u32 v136, v136, 9, v183
	global_load_dwordx4 v[0:3], v136, s[20:21]
	global_load_dwordx4 v[4:7], v136, s[20:21] offset:64
	v_add_u32_e32 v135, 1, v252
	v_med3_i32 v135, v135, 0, s14
	v_lshl_add_u32 v135, v135, 9, v183
	global_load_dwordx4 v[8:11], v135, s[20:21]
	global_load_dwordx4 v[12:15], v135, s[20:21] offset:64
	v_add_u32_e32 v136, 2, v252
	v_med3_i32 v136, v136, 0, s14
	v_lshl_add_u32 v136, v136, 9, v183
	global_load_dwordx4 v[16:19], v136, s[20:21]
	global_load_dwordx4 v[20:23], v136, s[20:21] offset:64
	v_add_u32_e32 v135, 3, v252
	v_med3_i32 v135, v135, 0, s14
	v_lshl_add_u32 v135, v135, 9, v183
	global_load_dwordx4 v[24:27], v135, s[20:21]
	global_load_dwordx4 v[28:31], v135, s[20:21] offset:64
	v_add_u32_e32 v136, 4, v252
	v_med3_i32 v136, v136, 0, s14
	v_lshl_add_u32 v136, v136, 9, v183
	global_load_dwordx4 v[32:35], v136, s[20:21]
	global_load_dwordx4 v[36:39], v136, s[20:21] offset:64
	v_add_u32_e32 v135, 5, v252
	v_med3_i32 v135, v135, 0, s14
	v_lshl_add_u32 v135, v135, 9, v183
	global_load_dwordx4 v[40:43], v135, s[20:21]
	global_load_dwordx4 v[44:47], v135, s[20:21] offset:64
	s_add_i32 s2, s42, -64
	v_add_u32_e32 v138, s2, v164
	v_add_u32_e32 v138, s43, v138
	v_and_b32_e32 v139, 3, v138
	v_lshlrev_b32_e32 v139, s13, v139
	v_bfe_u32 v140, v138, 2, 2
	v_add_u32_e32 v139, v139, v140
	v_lshl_add_u32 v139, v139, 7, v162
	v_ashrrev_i32_e32 v138, 4, v138
	v_med3_i32 v138, v138, 0, s14
	v_lshl_add_u32 v138, v138, 9, v139
	global_load_dwordx4 v[64:67], v138, s[22:23]
	s_add_i32 s2, s42, -56
	v_add_u32_e32 v138, s2, v164
	v_add_u32_e32 v138, s43, v138
	v_and_b32_e32 v139, 3, v138
	v_lshlrev_b32_e32 v139, s13, v139
	v_bfe_u32 v140, v138, 2, 2
	v_add_u32_e32 v139, v139, v140
	v_lshl_add_u32 v139, v139, 7, v162
	v_ashrrev_i32_e32 v138, 4, v138
	v_med3_i32 v138, v138, 0, s14
	v_lshl_add_u32 v138, v138, 9, v139
	global_load_dwordx4 v[68:71], v138, s[22:23]
	s_add_i32 s2, s42, -48
	v_add_u32_e32 v138, s2, v164
	v_add_u32_e32 v138, s43, v138
	v_and_b32_e32 v139, 3, v138
	v_lshlrev_b32_e32 v139, s13, v139
	v_bfe_u32 v140, v138, 2, 2
	v_add_u32_e32 v139, v139, v140
	v_lshl_add_u32 v139, v139, 7, v162
	v_ashrrev_i32_e32 v138, 4, v138
	v_med3_i32 v138, v138, 0, s14
	v_lshl_add_u32 v138, v138, 9, v139
	global_load_dwordx4 v[72:75], v138, s[22:23]
	s_add_i32 s2, s42, -40
	v_add_u32_e32 v138, s2, v164
	v_add_u32_e32 v138, s43, v138
	v_and_b32_e32 v139, 3, v138
	v_lshlrev_b32_e32 v139, s13, v139
	v_bfe_u32 v140, v138, 2, 2
	v_add_u32_e32 v139, v139, v140
	v_lshl_add_u32 v139, v139, 7, v162
	v_ashrrev_i32_e32 v138, 4, v138
	v_med3_i32 v138, v138, 0, s14
	v_lshl_add_u32 v138, v138, 9, v139
	global_load_dwordx4 v[76:79], v138, s[22:23]
	s_add_i32 s2, s42, -32
	v_add_u32_e32 v138, s2, v164
	v_add_u32_e32 v138, s43, v138
	v_and_b32_e32 v139, 3, v138
	v_lshlrev_b32_e32 v139, s13, v139
	v_bfe_u32 v140, v138, 2, 2
	v_add_u32_e32 v139, v139, v140
	v_lshl_add_u32 v139, v139, 7, v162
	v_ashrrev_i32_e32 v138, 4, v138
	v_med3_i32 v138, v138, 0, s14
	v_lshl_add_u32 v138, v138, 9, v139
	global_load_dwordx4 v[80:83], v138, s[22:23]
	s_add_i32 s2, s42, -24
	v_add_u32_e32 v138, s2, v164
	v_add_u32_e32 v138, s43, v138
	v_and_b32_e32 v139, 3, v138
	v_lshlrev_b32_e32 v139, s13, v139
	v_bfe_u32 v140, v138, 2, 2
	v_add_u32_e32 v139, v139, v140
	v_lshl_add_u32 v139, v139, 7, v162
	v_ashrrev_i32_e32 v138, 4, v138
	v_med3_i32 v138, v138, 0, s14
	v_lshl_add_u32 v138, v138, 9, v139
	global_load_dwordx4 v[84:87], v138, s[22:23]
	s_add_i32 s2, s42, -16
	v_add_u32_e32 v138, s2, v164
	v_add_u32_e32 v138, s43, v138
	v_and_b32_e32 v139, 3, v138
	v_lshlrev_b32_e32 v139, s13, v139
	v_bfe_u32 v140, v138, 2, 2
	v_add_u32_e32 v139, v139, v140
	v_lshl_add_u32 v139, v139, 7, v162
	v_ashrrev_i32_e32 v138, 4, v138
	v_med3_i32 v138, v138, 0, s14
	v_lshl_add_u32 v138, v138, 9, v139
	global_load_dwordx4 v[88:91], v138, s[22:23]
	s_add_i32 s2, s42, -8
	v_add_u32_e32 v138, s2, v164
	v_add_u32_e32 v138, s43, v138
	v_and_b32_e32 v139, 3, v138
	v_lshlrev_b32_e32 v139, s13, v139
	v_bfe_u32 v140, v138, 2, 2
	v_add_u32_e32 v139, v139, v140
	v_lshl_add_u32 v139, v139, 7, v162
	v_ashrrev_i32_e32 v138, 4, v138
	v_med3_i32 v138, v138, 0, s14
	v_lshl_add_u32 v138, v138, 9, v139
	global_load_dwordx4 v[92:95], v138, s[22:23]
	s_add_i32 s2, s42, 0
	v_add_u32_e32 v138, s2, v164
	v_add_u32_e32 v138, s43, v138
	v_and_b32_e32 v139, 3, v138
	v_lshlrev_b32_e32 v139, s13, v139
	v_bfe_u32 v140, v138, 2, 2
	v_add_u32_e32 v139, v139, v140
	v_lshl_add_u32 v139, v139, 7, v162
	v_ashrrev_i32_e32 v138, 4, v138
	v_med3_i32 v138, v138, 0, s14
	v_lshl_add_u32 v138, v138, 9, v139
	global_load_dwordx4 v[96:99], v138, s[22:23]
	s_add_i32 s2, s42, 8
	v_add_u32_e32 v138, s2, v164
	v_add_u32_e32 v138, s43, v138
	v_and_b32_e32 v139, 3, v138
	v_lshlrev_b32_e32 v139, s13, v139
	v_bfe_u32 v140, v138, 2, 2
	v_add_u32_e32 v139, v139, v140
	v_lshl_add_u32 v139, v139, 7, v162
	v_ashrrev_i32_e32 v138, 4, v138
	v_med3_i32 v138, v138, 0, s14
	v_lshl_add_u32 v138, v138, 9, v139
	global_load_dwordx4 v[100:103], v138, s[22:23]
	s_add_i32 s2, s42, 16
	v_add_u32_e32 v138, s2, v164
	v_add_u32_e32 v138, s43, v138
	v_and_b32_e32 v139, 3, v138
	v_lshlrev_b32_e32 v139, s13, v139
	v_bfe_u32 v140, v138, 2, 2
	v_add_u32_e32 v139, v139, v140
	v_lshl_add_u32 v139, v139, 7, v162
	v_ashrrev_i32_e32 v138, 4, v138
	v_med3_i32 v138, v138, 0, s14
	v_lshl_add_u32 v138, v138, 9, v139
	global_load_dwordx4 v[104:107], v138, s[22:23]
	s_add_i32 s2, s42, 24
	v_add_u32_e32 v138, s2, v164
	v_add_u32_e32 v138, s43, v138
	v_and_b32_e32 v139, 3, v138
	v_lshlrev_b32_e32 v139, s13, v139
	v_bfe_u32 v140, v138, 2, 2
	v_add_u32_e32 v139, v139, v140
	v_lshl_add_u32 v139, v139, 7, v162
	v_ashrrev_i32_e32 v138, 4, v138
	v_med3_i32 v138, v138, 0, s14
	v_lshl_add_u32 v138, v138, 9, v139
	global_load_dwordx4 v[108:111], v138, s[22:23]
.Latt_unit:
	s_mov_b32 s33, s12
	s_mov_b32 s34, s15
	s_mov_b32 s35, s16
	s_mov_b32 s36, s17
	s_mov_b32 s38, s14
	s_mov_b32 s39, s13
	s_mov_b32 s24, s20
	s_mov_b32 s25, s21
	s_mov_b32 s26, s22
	s_mov_b32 s27, s23
	s_mov_b32 s40, s42
	s_mov_b32 s41, s43
	v_mov_b32_e32 v173, v176
	v_mov_b32_e32 v174, v177
	v_mov_b32_e32 v175, v178
	v_mov_b32_e32 v179, v183
	v_mov_b32_e32 v182, v252
	s_lshr_b32 s44, s33, 0
	s_lshr_b32 s2, s0, 2
	s_lshl_b32 s2, s2, 5
	s_lshr_b32 s3, s15, 2
	s_add_i32 s42, s3, s2
	s_and_b32 s43, s0, 3
	s_waitcnt vmcnt(12)
	v_mov_b32_e32 v132, 0
	v_mov_b32_e32 v133, 0
	v_mfma_f32_16x16x32_bf16 v[236:239], v[0:3], v[48:51], 0
	v_mfma_f32_16x16x32_bf16 v[236:239], v[4:7], v[52:55], v[236:239]
	v_mfma_f32_16x16x32_bf16 v[240:243], v[8:11], v[48:51], 0
	v_mfma_f32_16x16x32_bf16 v[240:243], v[12:15], v[52:55], v[240:243]
	v_mfma_f32_16x16x32_bf16 v[248:251], v[8:11], v[56:59], 0
	v_mfma_f32_16x16x32_bf16 v[248:251], v[12:15], v[60:63], v[248:251]
	s_nop 7
	v_min_f32_e32 v152, 0x42a00000, v236
	v_min_f32_e32 v153, 0x42a00000, v237
	v_min_f32_e32 v154, 0x42a00000, v238
	v_min_f32_e32 v155, 0x42a00000, v239
	v_mfma_f32_16x16x32_bf16 v[236:239], v[16:19], v[48:51], 0
	v_mfma_f32_16x16x32_bf16 v[236:239], v[20:23], v[52:55], v[236:239]
	v_mfma_f32_16x16x32_bf16 v[244:247], v[16:19], v[56:59], 0
	v_mfma_f32_16x16x32_bf16 v[244:247], v[20:23], v[60:63], v[244:247]
	v_add_u32_e32 v136, 6, v182
	v_med3_i32 v136, v136, 0, s38
	v_lshl_add_u32 v136, v136, 9, v179
	global_load_dwordx4 v[0:3], v136, s[24:25]
	global_load_dwordx4 v[4:7], v136, s[24:25] offset:64
	v_mul_f32_e32 v152, 0x3fb8aa3b, v152
	v_mul_f32_e32 v153, 0x3fb8aa3b, v153
	v_mul_f32_e32 v154, 0x3fb8aa3b, v154
	v_mul_f32_e32 v155, 0x3fb8aa3b, v155
	v_exp_f32_e32 v152, v152
	v_exp_f32_e32 v153, v153
	v_exp_f32_e32 v154, v154
	v_exp_f32_e32 v155, v155
	v_add_u32_e32 v138, 0, v175
	v_add_u32_e32 v139, 1, v175
	v_add_u32_e32 v140, 2, v175
	v_add_u32_e32 v141, 3, v175
	v_cmp_gt_u32_e64 s[70:71], s44, v138
	v_cmp_gt_u32_e64 s[72:73], s44, v139
	v_cmp_gt_u32_e64 s[74:75], s44, v140
	v_cmp_gt_u32_e64 s[76:77], s44, v141
	v_cndmask_b32_e64 v152, 0, v152, s[54:55]
	v_cndmask_b32_e64 v153, 0, v153, s[56:57]
	v_cndmask_b32_e64 v154, 0, v154, s[58:59]
	v_cndmask_b32_e64 v155, 0, v155, s[60:61]
	v_cndmask_b32_e64 v152, 0, v152, s[70:71]
	v_cndmask_b32_e64 v153, 0, v153, s[72:73]
	v_cndmask_b32_e64 v154, 0, v154, s[74:75]
	v_cndmask_b32_e64 v155, 0, v155, s[76:77]
	v_add_f32_e32 v132, v132, v152
	v_add_f32_e32 v132, v132, v153
	v_add_f32_e32 v132, v132, v154
	v_add_f32_e32 v132, v132, v155
	v_cvt_pk_bf16_f32 v112, v152, v153
	v_cvt_pk_bf16_f32 v113, v154, v155
	v_min_f32_e32 v152, 0x42a00000, v240
	v_min_f32_e32 v153, 0x42a00000, v241
	v_min_f32_e32 v154, 0x42a00000, v242
	v_min_f32_e32 v155, 0x42a00000, v243
	v_min_f32_e32 v156, 0x42a00000, v248
	v_min_f32_e32 v157, 0x42a00000, v249
	v_min_f32_e32 v158, 0x42a00000, v250
	v_min_f32_e32 v159, 0x42a00000, v251
	v_mfma_f32_16x16x32_bf16 v[240:243], v[24:27], v[48:51], 0
	v_mfma_f32_16x16x32_bf16 v[240:243], v[28:31], v[52:55], v[240:243]
	v_mfma_f32_16x16x32_bf16 v[248:251], v[24:27], v[56:59], 0
	v_mfma_f32_16x16x32_bf16 v[248:251], v[28:31], v[60:63], v[248:251]
	v_add_u32_e32 v135, 7, v182
	v_med3_i32 v135, v135, 0, s38
	v_lshl_add_u32 v135, v135, 9, v179
	global_load_dwordx4 v[8:11], v135, s[24:25]
	global_load_dwordx4 v[12:15], v135, s[24:25] offset:64
	v_mul_f32_e32 v152, 0x3fb8aa3b, v152
	v_mul_f32_e32 v153, 0x3fb8aa3b, v153
	v_mul_f32_e32 v154, 0x3fb8aa3b, v154
	v_mul_f32_e32 v155, 0x3fb8aa3b, v155
	v_exp_f32_e32 v152, v152
	v_exp_f32_e32 v153, v153
	v_exp_f32_e32 v154, v154
	v_exp_f32_e32 v155, v155
	v_add_u32_e32 v138, 16, v175
	v_add_u32_e32 v139, 17, v175
	v_add_u32_e32 v140, 18, v175
	v_add_u32_e32 v141, 19, v175
	v_cmp_gt_u32_e64 s[70:71], s44, v138
	v_cmp_gt_u32_e64 s[72:73], s44, v139
	v_cmp_gt_u32_e64 s[74:75], s44, v140
	v_cmp_gt_u32_e64 s[76:77], s44, v141
	v_cndmask_b32_e64 v152, 0, v152, s[70:71]
	v_cndmask_b32_e64 v153, 0, v153, s[72:73]
	v_cndmask_b32_e64 v154, 0, v154, s[74:75]
	v_cndmask_b32_e64 v155, 0, v155, s[76:77]
	v_add_f32_e32 v132, v132, v152
	v_add_f32_e32 v132, v132, v153
	v_add_f32_e32 v132, v132, v154
	v_add_f32_e32 v132, v132, v155
	v_cvt_pk_bf16_f32 v114, v152, v153
	v_cvt_pk_bf16_f32 v115, v154, v155
	v_mul_f32_e32 v156, 0x3fb8aa3b, v156
	v_mul_f32_e32 v157, 0x3fb8aa3b, v157
	v_mul_f32_e32 v158, 0x3fb8aa3b, v158
	v_mul_f32_e32 v159, 0x3fb8aa3b, v159
	v_exp_f32_e32 v156, v156
	v_exp_f32_e32 v157, v157
	v_exp_f32_e32 v158, v158
	v_exp_f32_e32 v159, v159
	v_add_u32_e32 v138, 16, v175
	v_add_u32_e32 v139, 17, v175
	v_add_u32_e32 v140, 18, v175
	v_add_u32_e32 v141, 19, v175
	v_cmp_gt_u32_e64 s[70:71], s44, v138
	v_cmp_gt_u32_e64 s[72:73], s44, v139
	v_cmp_gt_u32_e64 s[74:75], s44, v140
	v_cmp_gt_u32_e64 s[76:77], s44, v141
	v_cndmask_b32_e64 v156, 0, v156, s[54:55]
	v_cndmask_b32_e64 v157, 0, v157, s[56:57]
	v_cndmask_b32_e64 v158, 0, v158, s[58:59]
	v_cndmask_b32_e64 v159, 0, v159, s[60:61]
	v_cndmask_b32_e64 v156, 0, v156, s[70:71]
	v_cndmask_b32_e64 v157, 0, v157, s[72:73]
	v_cndmask_b32_e64 v158, 0, v158, s[74:75]
	v_cndmask_b32_e64 v159, 0, v159, s[76:77]
	v_add_f32_e32 v133, v133, v156
	v_add_f32_e32 v133, v133, v157
	v_add_f32_e32 v133, v133, v158
	v_add_f32_e32 v133, v133, v159
	v_cvt_pk_bf16_f32 v186, v156, v157
	v_cvt_pk_bf16_f32 v187, v158, v159
	v_min_f32_e32 v152, 0x42a00000, v236
	v_min_f32_e32 v153, 0x42a00000, v237
	v_min_f32_e32 v154, 0x42a00000, v238
	v_min_f32_e32 v155, 0x42a00000, v239
	v_min_f32_e32 v156, 0x42a00000, v244
	v_min_f32_e32 v157, 0x42a00000, v245
	v_min_f32_e32 v158, 0x42a00000, v246
	v_min_f32_e32 v159, 0x42a00000, v247
	v_mfma_f32_16x16x32_bf16 v[236:239], v[32:35], v[48:51], 0
	v_mfma_f32_16x16x32_bf16 v[236:239], v[36:39], v[52:55], v[236:239]
	v_mfma_f32_16x16x32_bf16 v[244:247], v[32:35], v[56:59], 0
	v_mfma_f32_16x16x32_bf16 v[244:247], v[36:39], v[60:63], v[244:247]
	v_add_u32_e32 v136, 8, v182
	v_med3_i32 v136, v136, 0, s38
	v_lshl_add_u32 v136, v136, 9, v179
	global_load_dwordx4 v[16:19], v136, s[24:25]
	global_load_dwordx4 v[20:23], v136, s[24:25] offset:64
	v_mul_f32_e32 v152, 0x3fb8aa3b, v152
	v_mul_f32_e32 v153, 0x3fb8aa3b, v153
	v_mul_f32_e32 v154, 0x3fb8aa3b, v154
	v_mul_f32_e32 v155, 0x3fb8aa3b, v155
	v_exp_f32_e32 v152, v152
	v_exp_f32_e32 v153, v153
	v_exp_f32_e32 v154, v154
	v_exp_f32_e32 v155, v155
	v_add_u32_e32 v138, 32, v175
	v_add_u32_e32 v139, 33, v175
	v_add_u32_e32 v140, 34, v175
	v_add_u32_e32 v141, 35, v175
	v_cmp_gt_u32_e64 s[70:71], s44, v138
	v_cmp_gt_u32_e64 s[72:73], s44, v139
	v_cmp_gt_u32_e64 s[74:75], s44, v140
	v_cmp_gt_u32_e64 s[76:77], s44, v141
	v_cndmask_b32_e64 v152, 0, v152, s[70:71]
	v_cndmask_b32_e64 v153, 0, v153, s[72:73]
	v_cndmask_b32_e64 v154, 0, v154, s[74:75]
	v_cndmask_b32_e64 v155, 0, v155, s[76:77]
	v_add_f32_e32 v132, v132, v152
	v_add_f32_e32 v132, v132, v153
	v_add_f32_e32 v132, v132, v154
	v_add_f32_e32 v132, v132, v155
	v_cvt_pk_bf16_f32 v116, v152, v153
	v_cvt_pk_bf16_f32 v117, v154, v155
	v_mul_f32_e32 v156, 0x3fb8aa3b, v156
	v_mul_f32_e32 v157, 0x3fb8aa3b, v157
	v_mul_f32_e32 v158, 0x3fb8aa3b, v158
	v_mul_f32_e32 v159, 0x3fb8aa3b, v159
	v_exp_f32_e32 v156, v156
	v_exp_f32_e32 v157, v157
	v_exp_f32_e32 v158, v158
	v_exp_f32_e32 v159, v159
	v_add_u32_e32 v138, 32, v175
	v_add_u32_e32 v139, 33, v175
	v_add_u32_e32 v140, 34, v175
	v_add_u32_e32 v141, 35, v175
	v_cmp_gt_u32_e64 s[70:71], s44, v138
	v_cmp_gt_u32_e64 s[72:73], s44, v139
	v_cmp_gt_u32_e64 s[74:75], s44, v140
	v_cmp_gt_u32_e64 s[76:77], s44, v141
	v_cndmask_b32_e64 v156, 0, v156, s[70:71]
	v_cndmask_b32_e64 v157, 0, v157, s[72:73]
	v_cndmask_b32_e64 v158, 0, v158, s[74:75]
	v_cndmask_b32_e64 v159, 0, v159, s[76:77]
	v_add_f32_e32 v133, v133, v156
	v_add_f32_e32 v133, v133, v157
	v_add_f32_e32 v133, v133, v158
	v_add_f32_e32 v133, v133, v159
	v_cvt_pk_bf16_f32 v188, v156, v157
	v_cvt_pk_bf16_f32 v189, v158, v159
	v_min_f32_e32 v152, 0x42a00000, v240
	v_min_f32_e32 v153, 0x42a00000, v241
	v_min_f32_e32 v154, 0x42a00000, v242
	v_min_f32_e32 v155, 0x42a00000, v243
	v_min_f32_e32 v156, 0x42a00000, v248
	v_min_f32_e32 v157, 0x42a00000, v249
	v_min_f32_e32 v158, 0x42a00000, v250
	v_min_f32_e32 v159, 0x42a00000, v251
	v_mfma_f32_16x16x32_bf16 v[240:243], v[40:43], v[48:51], 0
	v_mfma_f32_16x16x32_bf16 v[240:243], v[44:47], v[52:55], v[240:243]
	v_mfma_f32_16x16x32_bf16 v[248:251], v[40:43], v[56:59], 0
	v_mfma_f32_16x16x32_bf16 v[248:251], v[44:47], v[60:63], v[248:251]
	v_add_u32_e32 v135, 9, v182
	v_med3_i32 v135, v135, 0, s38
	v_lshl_add_u32 v135, v135, 9, v179
	global_load_dwordx4 v[24:27], v135, s[24:25]
	global_load_dwordx4 v[28:31], v135, s[24:25] offset:64
	v_mul_f32_e32 v152, 0x3fb8aa3b, v152
	v_mul_f32_e32 v153, 0x3fb8aa3b, v153
	v_mul_f32_e32 v154, 0x3fb8aa3b, v154
	v_mul_f32_e32 v155, 0x3fb8aa3b, v155
	v_exp_f32_e32 v152, v152
	v_exp_f32_e32 v153, v153
	v_exp_f32_e32 v154, v154
	v_exp_f32_e32 v155, v155
	v_add_u32_e32 v138, 48, v175
	v_add_u32_e32 v139, 49, v175
	v_add_u32_e32 v140, 50, v175
	v_add_u32_e32 v141, 51, v175
	v_cmp_gt_u32_e64 s[70:71], s44, v138
	v_cmp_gt_u32_e64 s[72:73], s44, v139
	v_cmp_gt_u32_e64 s[74:75], s44, v140
	v_cmp_gt_u32_e64 s[76:77], s44, v141
	v_cndmask_b32_e64 v152, 0, v152, s[70:71]
	v_cndmask_b32_e64 v153, 0, v153, s[72:73]
	v_cndmask_b32_e64 v154, 0, v154, s[74:75]
	v_cndmask_b32_e64 v155, 0, v155, s[76:77]
	v_add_f32_e32 v132, v132, v152
	v_add_f32_e32 v132, v132, v153
	v_add_f32_e32 v132, v132, v154
	v_add_f32_e32 v132, v132, v155
	v_cvt_pk_bf16_f32 v118, v152, v153
	v_cvt_pk_bf16_f32 v119, v154, v155
	v_mul_f32_e32 v156, 0x3fb8aa3b, v156
	v_mul_f32_e32 v157, 0x3fb8aa3b, v157
	v_mul_f32_e32 v158, 0x3fb8aa3b, v158
	v_mul_f32_e32 v159, 0x3fb8aa3b, v159
	v_exp_f32_e32 v156, v156
	v_exp_f32_e32 v157, v157
	v_exp_f32_e32 v158, v158
	v_exp_f32_e32 v159, v159
	v_add_u32_e32 v138, 48, v175
	v_add_u32_e32 v139, 49, v175
	v_add_u32_e32 v140, 50, v175
	v_add_u32_e32 v141, 51, v175
	v_cmp_gt_u32_e64 s[70:71], s44, v138
	v_cmp_gt_u32_e64 s[72:73], s44, v139
	v_cmp_gt_u32_e64 s[74:75], s44, v140
	v_cmp_gt_u32_e64 s[76:77], s44, v141
	v_cndmask_b32_e64 v156, 0, v156, s[70:71]
	v_cndmask_b32_e64 v157, 0, v157, s[72:73]
	v_cndmask_b32_e64 v158, 0, v158, s[74:75]
	v_cndmask_b32_e64 v159, 0, v159, s[76:77]
	v_add_f32_e32 v133, v133, v156
	v_add_f32_e32 v133, v133, v157
	v_add_f32_e32 v133, v133, v158
	v_add_f32_e32 v133, v133, v159
	v_cvt_pk_bf16_f32 v190, v156, v157
	v_cvt_pk_bf16_f32 v191, v158, v159
	v_min_f32_e32 v152, 0x42a00000, v236
	v_min_f32_e32 v153, 0x42a00000, v237
	v_min_f32_e32 v154, 0x42a00000, v238
	v_min_f32_e32 v155, 0x42a00000, v239
	v_min_f32_e32 v156, 0x42a00000, v244
	v_min_f32_e32 v157, 0x42a00000, v245
	v_min_f32_e32 v158, 0x42a00000, v246
	v_min_f32_e32 v159, 0x42a00000, v247
	s_waitcnt vmcnt(6)
	v_mfma_f32_16x16x32_bf16 v[236:239], v[0:3], v[48:51], 0
	v_mfma_f32_16x16x32_bf16 v[236:239], v[4:7], v[52:55], v[236:239]
	v_mfma_f32_16x16x32_bf16 v[244:247], v[0:3], v[56:59], 0
	v_mfma_f32_16x16x32_bf16 v[244:247], v[4:7], v[60:63], v[244:247]
	v_mul_f32_e32 v152, 0x3fb8aa3b, v152
	v_mul_f32_e32 v153, 0x3fb8aa3b, v153
	v_mul_f32_e32 v154, 0x3fb8aa3b, v154
	v_mul_f32_e32 v155, 0x3fb8aa3b, v155
	v_exp_f32_e32 v152, v152
	v_exp_f32_e32 v153, v153
	v_exp_f32_e32 v154, v154
	v_exp_f32_e32 v155, v155
	v_add_u32_e32 v138, 64, v175
	v_add_u32_e32 v139, 0x41, v175
	v_add_u32_e32 v140, 0x42, v175
	v_add_u32_e32 v141, 0x43, v175
	v_cmp_gt_u32_e64 s[70:71], s44, v138
	v_cmp_gt_u32_e64 s[72:73], s44, v139
	v_cmp_gt_u32_e64 s[74:75], s44, v140
	v_cmp_gt_u32_e64 s[76:77], s44, v141
	v_cndmask_b32_e64 v152, 0, v152, s[70:71]
	v_cndmask_b32_e64 v153, 0, v153, s[72:73]
	v_cndmask_b32_e64 v154, 0, v154, s[74:75]
	v_cndmask_b32_e64 v155, 0, v155, s[76:77]
	v_add_f32_e32 v132, v132, v152
	v_add_f32_e32 v132, v132, v153
	v_add_f32_e32 v132, v132, v154
	v_add_f32_e32 v132, v132, v155
	v_cvt_pk_bf16_f32 v120, v152, v153
	v_cvt_pk_bf16_f32 v121, v154, v155
	v_mul_f32_e32 v156, 0x3fb8aa3b, v156
	v_mul_f32_e32 v157, 0x3fb8aa3b, v157
	v_mul_f32_e32 v158, 0x3fb8aa3b, v158
	v_mul_f32_e32 v159, 0x3fb8aa3b, v159
	v_exp_f32_e32 v156, v156
	v_exp_f32_e32 v157, v157
	v_exp_f32_e32 v158, v158
	v_exp_f32_e32 v159, v159
	v_add_u32_e32 v138, 64, v175
	v_add_u32_e32 v139, 0x41, v175
	v_add_u32_e32 v140, 0x42, v175
	v_add_u32_e32 v141, 0x43, v175
	v_cmp_gt_u32_e64 s[70:71], s44, v138
	v_cmp_gt_u32_e64 s[72:73], s44, v139
	v_cmp_gt_u32_e64 s[74:75], s44, v140
	v_cmp_gt_u32_e64 s[76:77], s44, v141
	v_cndmask_b32_e64 v156, 0, v156, s[70:71]
	v_cndmask_b32_e64 v157, 0, v157, s[72:73]
	v_cndmask_b32_e64 v158, 0, v158, s[74:75]
	v_cndmask_b32_e64 v159, 0, v159, s[76:77]
	v_add_f32_e32 v133, v133, v156
	v_add_f32_e32 v133, v133, v157
	v_add_f32_e32 v133, v133, v158
	v_add_f32_e32 v133, v133, v159
	v_cvt_pk_bf16_f32 v192, v156, v157
	v_cvt_pk_bf16_f32 v193, v158, v159
	v_min_f32_e32 v152, 0x42a00000, v240
	v_min_f32_e32 v153, 0x42a00000, v241
	v_min_f32_e32 v154, 0x42a00000, v242
	v_min_f32_e32 v155, 0x42a00000, v243
	v_min_f32_e32 v156, 0x42a00000, v248
	v_min_f32_e32 v157, 0x42a00000, v249
	v_min_f32_e32 v158, 0x42a00000, v250
	v_min_f32_e32 v159, 0x42a00000, v251
	s_waitcnt vmcnt(4)
	v_mfma_f32_16x16x32_bf16 v[240:243], v[8:11], v[48:51], 0
	v_mfma_f32_16x16x32_bf16 v[240:243], v[12:15], v[52:55], v[240:243]
	v_mfma_f32_16x16x32_bf16 v[248:251], v[8:11], v[56:59], 0
	v_mfma_f32_16x16x32_bf16 v[248:251], v[12:15], v[60:63], v[248:251]
	v_mul_f32_e32 v152, 0x3fb8aa3b, v152
	v_mul_f32_e32 v153, 0x3fb8aa3b, v153
	v_mul_f32_e32 v154, 0x3fb8aa3b, v154
	v_mul_f32_e32 v155, 0x3fb8aa3b, v155
	v_exp_f32_e32 v152, v152
	v_exp_f32_e32 v153, v153
	v_exp_f32_e32 v154, v154
	v_exp_f32_e32 v155, v155
	v_add_u32_e32 v138, 0x50, v175
	v_add_u32_e32 v139, 0x51, v175
	v_add_u32_e32 v140, 0x52, v175
	v_add_u32_e32 v141, 0x53, v175
	v_cmp_gt_u32_e64 s[70:71], s44, v138
	v_cmp_gt_u32_e64 s[72:73], s44, v139
	v_cmp_gt_u32_e64 s[74:75], s44, v140
	v_cmp_gt_u32_e64 s[76:77], s44, v141
	v_cndmask_b32_e64 v152, 0, v152, s[70:71]
	v_cndmask_b32_e64 v153, 0, v153, s[72:73]
	v_cndmask_b32_e64 v154, 0, v154, s[74:75]
	v_cndmask_b32_e64 v155, 0, v155, s[76:77]
	v_add_f32_e32 v132, v132, v152
	v_add_f32_e32 v132, v132, v153
	v_add_f32_e32 v132, v132, v154
	v_add_f32_e32 v132, v132, v155
	v_cvt_pk_bf16_f32 v122, v152, v153
	v_cvt_pk_bf16_f32 v123, v154, v155
	v_mul_f32_e32 v156, 0x3fb8aa3b, v156
	v_mul_f32_e32 v157, 0x3fb8aa3b, v157
	v_mul_f32_e32 v158, 0x3fb8aa3b, v158
	v_mul_f32_e32 v159, 0x3fb8aa3b, v159
	v_exp_f32_e32 v156, v156
	v_exp_f32_e32 v157, v157
	v_exp_f32_e32 v158, v158
	v_exp_f32_e32 v159, v159
	v_add_u32_e32 v138, 0x50, v175
	v_add_u32_e32 v139, 0x51, v175
	v_add_u32_e32 v140, 0x52, v175
	v_add_u32_e32 v141, 0x53, v175
	v_cmp_gt_u32_e64 s[70:71], s44, v138
	v_cmp_gt_u32_e64 s[72:73], s44, v139
	v_cmp_gt_u32_e64 s[74:75], s44, v140
	v_cmp_gt_u32_e64 s[76:77], s44, v141
	v_cndmask_b32_e64 v156, 0, v156, s[70:71]
	v_cndmask_b32_e64 v157, 0, v157, s[72:73]
	v_cndmask_b32_e64 v158, 0, v158, s[74:75]
	v_cndmask_b32_e64 v159, 0, v159, s[76:77]
	v_add_f32_e32 v133, v133, v156
	v_add_f32_e32 v133, v133, v157
	v_add_f32_e32 v133, v133, v158
	v_add_f32_e32 v133, v133, v159
	v_cvt_pk_bf16_f32 v194, v156, v157
	v_cvt_pk_bf16_f32 v195, v158, v159
	v_min_f32_e32 v152, 0x42a00000, v236
	v_min_f32_e32 v153, 0x42a00000, v237
	v_min_f32_e32 v154, 0x42a00000, v238
	v_min_f32_e32 v155, 0x42a00000, v239
	v_min_f32_e32 v156, 0x42a00000, v244
	v_min_f32_e32 v157, 0x42a00000, v245
	v_min_f32_e32 v158, 0x42a00000, v246
	v_min_f32_e32 v159, 0x42a00000, v247
	s_waitcnt vmcnt(2)
	v_mfma_f32_16x16x32_bf16 v[236:239], v[16:19], v[48:51], 0
	v_mfma_f32_16x16x32_bf16 v[236:239], v[20:23], v[52:55], v[236:239]
	v_mfma_f32_16x16x32_bf16 v[244:247], v[16:19], v[56:59], 0
	v_mfma_f32_16x16x32_bf16 v[244:247], v[20:23], v[60:63], v[244:247]
	v_mul_f32_e32 v152, 0x3fb8aa3b, v152
	v_mul_f32_e32 v153, 0x3fb8aa3b, v153
	v_mul_f32_e32 v154, 0x3fb8aa3b, v154
	v_mul_f32_e32 v155, 0x3fb8aa3b, v155
	v_exp_f32_e32 v152, v152
	v_exp_f32_e32 v153, v153
	v_exp_f32_e32 v154, v154
	v_exp_f32_e32 v155, v155
	v_add_u32_e32 v138, 0x60, v175
	v_add_u32_e32 v139, 0x61, v175
	v_add_u32_e32 v140, 0x62, v175
	v_add_u32_e32 v141, 0x63, v175
	v_cmp_gt_u32_e64 s[70:71], s44, v138
	v_cmp_gt_u32_e64 s[72:73], s44, v139
	v_cmp_gt_u32_e64 s[74:75], s44, v140
	v_cmp_gt_u32_e64 s[76:77], s44, v141
	v_cndmask_b32_e64 v152, 0, v152, s[70:71]
	v_cndmask_b32_e64 v153, 0, v153, s[72:73]
	v_cndmask_b32_e64 v154, 0, v154, s[74:75]
	v_cndmask_b32_e64 v155, 0, v155, s[76:77]
	v_add_f32_e32 v132, v132, v152
	v_add_f32_e32 v132, v132, v153
	v_add_f32_e32 v132, v132, v154
	v_add_f32_e32 v132, v132, v155
	v_cvt_pk_bf16_f32 v124, v152, v153
	v_cvt_pk_bf16_f32 v125, v154, v155
	v_mul_f32_e32 v156, 0x3fb8aa3b, v156
	v_mul_f32_e32 v157, 0x3fb8aa3b, v157
	v_mul_f32_e32 v158, 0x3fb8aa3b, v158
	v_mul_f32_e32 v159, 0x3fb8aa3b, v159
	v_exp_f32_e32 v156, v156
	v_exp_f32_e32 v157, v157
	v_exp_f32_e32 v158, v158
	v_exp_f32_e32 v159, v159
	v_add_u32_e32 v138, 0x60, v175
	v_add_u32_e32 v139, 0x61, v175
	v_add_u32_e32 v140, 0x62, v175
	v_add_u32_e32 v141, 0x63, v175
	v_cmp_gt_u32_e64 s[70:71], s44, v138
	v_cmp_gt_u32_e64 s[72:73], s44, v139
	v_cmp_gt_u32_e64 s[74:75], s44, v140
	v_cmp_gt_u32_e64 s[76:77], s44, v141
	v_cndmask_b32_e64 v156, 0, v156, s[70:71]
	v_cndmask_b32_e64 v157, 0, v157, s[72:73]
	v_cndmask_b32_e64 v158, 0, v158, s[74:75]
	v_cndmask_b32_e64 v159, 0, v159, s[76:77]
	v_add_f32_e32 v133, v133, v156
	v_add_f32_e32 v133, v133, v157
	v_add_f32_e32 v133, v133, v158
	v_add_f32_e32 v133, v133, v159
	v_cvt_pk_bf16_f32 v196, v156, v157
	v_cvt_pk_bf16_f32 v197, v158, v159
	v_min_f32_e32 v152, 0x42a00000, v240
	v_min_f32_e32 v153, 0x42a00000, v241
	v_min_f32_e32 v154, 0x42a00000, v242
	v_min_f32_e32 v155, 0x42a00000, v243
	v_min_f32_e32 v156, 0x42a00000, v248
	v_min_f32_e32 v157, 0x42a00000, v249
	v_min_f32_e32 v158, 0x42a00000, v250
	v_min_f32_e32 v159, 0x42a00000, v251
	s_waitcnt vmcnt(0)
	v_mfma_f32_16x16x32_bf16 v[248:251], v[24:27], v[56:59], 0
	v_mfma_f32_16x16x32_bf16 v[248:251], v[28:31], v[60:63], v[248:251]
	v_mul_f32_e32 v152, 0x3fb8aa3b, v152
	v_mul_f32_e32 v153, 0x3fb8aa3b, v153
	v_mul_f32_e32 v154, 0x3fb8aa3b, v154
	v_mul_f32_e32 v155, 0x3fb8aa3b, v155
	v_exp_f32_e32 v152, v152
	v_exp_f32_e32 v153, v153
	v_exp_f32_e32 v154, v154
	v_exp_f32_e32 v155, v155
	v_add_u32_e32 v138, 0x70, v175
	v_add_u32_e32 v139, 0x71, v175
	v_add_u32_e32 v140, 0x72, v175
	v_add_u32_e32 v141, 0x73, v175
	v_cmp_gt_u32_e64 s[70:71], s44, v138
	v_cmp_gt_u32_e64 s[72:73], s44, v139
	v_cmp_gt_u32_e64 s[74:75], s44, v140
	v_cmp_gt_u32_e64 s[76:77], s44, v141
	v_cndmask_b32_e64 v152, 0, v152, s[70:71]
	v_cndmask_b32_e64 v153, 0, v153, s[72:73]
	v_cndmask_b32_e64 v154, 0, v154, s[74:75]
	v_cndmask_b32_e64 v155, 0, v155, s[76:77]
	v_add_f32_e32 v132, v132, v152
	v_add_f32_e32 v132, v132, v153
	v_add_f32_e32 v132, v132, v154
	v_add_f32_e32 v132, v132, v155
	v_cvt_pk_bf16_f32 v126, v152, v153
	v_cvt_pk_bf16_f32 v127, v154, v155
	v_mul_f32_e32 v156, 0x3fb8aa3b, v156
	v_mul_f32_e32 v157, 0x3fb8aa3b, v157
	v_mul_f32_e32 v158, 0x3fb8aa3b, v158
	v_mul_f32_e32 v159, 0x3fb8aa3b, v159
	v_exp_f32_e32 v156, v156
	v_exp_f32_e32 v157, v157
	v_exp_f32_e32 v158, v158
	v_exp_f32_e32 v159, v159
	v_add_u32_e32 v138, 0x70, v175
	v_add_u32_e32 v139, 0x71, v175
	v_add_u32_e32 v140, 0x72, v175
	v_add_u32_e32 v141, 0x73, v175
	v_cmp_gt_u32_e64 s[70:71], s44, v138
	v_cmp_gt_u32_e64 s[72:73], s44, v139
	v_cmp_gt_u32_e64 s[74:75], s44, v140
	v_cmp_gt_u32_e64 s[76:77], s44, v141
	v_cndmask_b32_e64 v156, 0, v156, s[70:71]
	v_cndmask_b32_e64 v157, 0, v157, s[72:73]
	v_cndmask_b32_e64 v158, 0, v158, s[74:75]
	v_cndmask_b32_e64 v159, 0, v159, s[76:77]
	v_add_f32_e32 v133, v133, v156
	v_add_f32_e32 v133, v133, v157
	v_add_f32_e32 v133, v133, v158
	v_add_f32_e32 v133, v133, v159
	v_cvt_pk_bf16_f32 v198, v156, v157
	v_cvt_pk_bf16_f32 v199, v158, v159
	v_min_f32_e32 v152, 0x42a00000, v236
	v_min_f32_e32 v153, 0x42a00000, v237
	v_min_f32_e32 v154, 0x42a00000, v238
	v_min_f32_e32 v155, 0x42a00000, v239
	v_min_f32_e32 v156, 0x42a00000, v244
	v_min_f32_e32 v157, 0x42a00000, v245
	v_min_f32_e32 v158, 0x42a00000, v246
	v_min_f32_e32 v159, 0x42a00000, v247
	v_mul_f32_e32 v152, 0x3fb8aa3b, v152
	v_mul_f32_e32 v153, 0x3fb8aa3b, v153
	v_mul_f32_e32 v154, 0x3fb8aa3b, v154
	v_mul_f32_e32 v155, 0x3fb8aa3b, v155
	v_exp_f32_e32 v152, v152
	v_exp_f32_e32 v153, v153
	v_exp_f32_e32 v154, v154
	v_exp_f32_e32 v155, v155
	v_add_u32_e32 v138, 0x80, v175
	v_add_u32_e32 v139, 0x81, v175
	v_add_u32_e32 v140, 0x82, v175
	v_add_u32_e32 v141, 0x83, v175
	v_cmp_gt_u32_e64 s[70:71], s44, v138
	v_cmp_gt_u32_e64 s[72:73], s44, v139
	v_cmp_gt_u32_e64 s[74:75], s44, v140
	v_cmp_gt_u32_e64 s[76:77], s44, v141
	v_cndmask_b32_e64 v152, 0, v152, s[62:63]
	v_cndmask_b32_e64 v153, 0, v153, s[64:65]
	v_cndmask_b32_e64 v154, 0, v154, s[66:67]
	v_cndmask_b32_e64 v155, 0, v155, s[68:69]
	v_cndmask_b32_e64 v152, 0, v152, s[70:71]
	v_cndmask_b32_e64 v153, 0, v153, s[72:73]
	v_cndmask_b32_e64 v154, 0, v154, s[74:75]
	v_cndmask_b32_e64 v155, 0, v155, s[76:77]
	v_add_f32_e32 v132, v132, v152
	v_add_f32_e32 v132, v132, v153
	v_add_f32_e32 v132, v132, v154
	v_add_f32_e32 v132, v132, v155
	v_cvt_pk_bf16_f32 v128, v152, v153
	v_cvt_pk_bf16_f32 v129, v154, v155
	v_mul_f32_e32 v156, 0x3fb8aa3b, v156
	v_mul_f32_e32 v157, 0x3fb8aa3b, v157
	v_mul_f32_e32 v158, 0x3fb8aa3b, v158
	v_mul_f32_e32 v159, 0x3fb8aa3b, v159
	v_exp_f32_e32 v156, v156
	v_exp_f32_e32 v157, v157
	v_exp_f32_e32 v158, v158
	v_exp_f32_e32 v159, v159
	v_add_u32_e32 v138, 0x80, v175
	v_add_u32_e32 v139, 0x81, v175
	v_add_u32_e32 v140, 0x82, v175
	v_add_u32_e32 v141, 0x83, v175
	v_cmp_gt_u32_e64 s[70:71], s44, v138
	v_cmp_gt_u32_e64 s[72:73], s44, v139
	v_cmp_gt_u32_e64 s[74:75], s44, v140
	v_cmp_gt_u32_e64 s[76:77], s44, v141
	v_cndmask_b32_e64 v156, 0, v156, s[70:71]
	v_cndmask_b32_e64 v157, 0, v157, s[72:73]
	v_cndmask_b32_e64 v158, 0, v158, s[74:75]
	v_cndmask_b32_e64 v159, 0, v159, s[76:77]
	v_add_f32_e32 v133, v133, v156
	v_add_f32_e32 v133, v133, v157
	v_add_f32_e32 v133, v133, v158
	v_add_f32_e32 v133, v133, v159
	v_cvt_pk_bf16_f32 v200, v156, v157
	v_cvt_pk_bf16_f32 v201, v158, v159
	v_min_f32_e32 v156, 0x42a00000, v248
	v_min_f32_e32 v157, 0x42a00000, v249
	v_min_f32_e32 v158, 0x42a00000, v250
	v_min_f32_e32 v159, 0x42a00000, v251
	v_mul_f32_e32 v156, 0x3fb8aa3b, v156
	v_mul_f32_e32 v157, 0x3fb8aa3b, v157
	v_mul_f32_e32 v158, 0x3fb8aa3b, v158
	v_mul_f32_e32 v159, 0x3fb8aa3b, v159
	v_exp_f32_e32 v156, v156
	v_exp_f32_e32 v157, v157
	v_exp_f32_e32 v158, v158
	v_exp_f32_e32 v159, v159
	v_add_u32_e32 v138, 0x90, v175
	v_add_u32_e32 v139, 0x91, v175
	v_add_u32_e32 v140, 0x92, v175
	v_add_u32_e32 v141, 0x93, v175
	v_cmp_gt_u32_e64 s[70:71], s44, v138
	v_cmp_gt_u32_e64 s[72:73], s44, v139
	v_cmp_gt_u32_e64 s[74:75], s44, v140
	v_cmp_gt_u32_e64 s[76:77], s44, v141
	v_cndmask_b32_e64 v156, 0, v156, s[62:63]
	v_cndmask_b32_e64 v157, 0, v157, s[64:65]
	v_cndmask_b32_e64 v158, 0, v158, s[66:67]
	v_cndmask_b32_e64 v159, 0, v159, s[68:69]
	v_cndmask_b32_e64 v156, 0, v156, s[70:71]
	v_cndmask_b32_e64 v157, 0, v157, s[72:73]
	v_cndmask_b32_e64 v158, 0, v158, s[74:75]
	v_cndmask_b32_e64 v159, 0, v159, s[76:77]
	v_add_f32_e32 v133, v133, v156
	v_add_f32_e32 v133, v133, v157
	v_add_f32_e32 v133, v133, v158
	v_add_f32_e32 v133, v133, v159
	v_cvt_pk_bf16_f32 v202, v156, v157
	v_cvt_pk_bf16_f32 v203, v158, v159
	v_add_u32_e32 v134, s42, v160
	v_lshlrev_b32_e32 v134, 2, v134
	v_add_u32_e32 v134, s43, v134
	v_subrev_u32_e32 v135, s15, v134
	v_lshrrev_b32_e32 v136, 4, v135
	v_add_u32_e32 v136, v136, v135
	v_mad_u32_u24 v176, v136, s79, v161
	v_lshl_add_u32 v177, v135, 2, s80
	s_sub_i32 s2, s42, 64
	v_add_u32_e32 v178, s2, v169
	v_and_b32_e32 v135, 3, v134
	v_lshlrev_b32_e32 v135, s13, v135
	v_lshrrev_b32_e32 v136, 2, v134
	v_add_u32_e32 v135, v135, v136
	v_lshl_add_u32 v135, v135, 7, v161
	global_load_dwordx4 v[48:51], v135, s[18:19]
	global_load_dwordx4 v[52:55], v135, s[18:19] offset:64
	v_add_u32_e32 v137, 64, v134
	v_and_b32_e32 v135, 3, v137
	v_lshlrev_b32_e32 v135, s13, v135
	v_lshrrev_b32_e32 v136, 2, v137
	v_add_u32_e32 v135, v135, v136
	v_lshl_add_u32 v135, v135, 7, v161
	global_load_dwordx4 v[56:59], v135, s[18:19]
	global_load_dwordx4 v[60:63], v135, s[18:19] offset:64
	v_subrev_u32_e32 v134, 0x100, v134
	v_and_b32_e32 v137, 3, v134
	v_lshlrev_b32_e32 v137, s13, v137
	v_bfe_u32 v135, v134, 2, 2
	v_add_u32_e32 v137, v137, v135
	v_lshl_add_u32 v183, v137, 7, v161
	v_ashrrev_i32_e32 v252, 4, v134
	v_med3_i32 v136, v252, 0, s14
	v_lshl_add_u32 v136, v136, 9, v183
	global_load_dwordx4 v[0:3], v136, s[20:21]
	global_load_dwordx4 v[4:7], v136, s[20:21] offset:64
	v_add_u32_e32 v135, 4, v252
	v_med3_i32 v135, v135, 0, s14
	v_lshl_add_u32 v135, v135, 9, v183
	global_load_dwordx4 v[8:11], v135, s[20:21]
	global_load_dwordx4 v[12:15], v135, s[20:21] offset:64
	v_add_u32_e32 v136, 8, v252
	v_med3_i32 v136, v136, 0, s14
	v_lshl_add_u32 v136, v136, 9, v183
	global_load_dwordx4 v[16:19], v136, s[20:21]
	global_load_dwordx4 v[20:23], v136, s[20:21] offset:64
	v_add_u32_e32 v135, 12, v252
	v_med3_i32 v135, v135, 0, s14
	v_lshl_add_u32 v135, v135, 9, v183
	global_load_dwordx4 v[24:27], v135, s[20:21]
	global_load_dwordx4 v[28:31], v135, s[20:21] offset:64
	v_add_u32_e32 v136, 16, v252
	v_med3_i32 v136, v136, 0, s14
	v_lshl_add_u32 v136, v136, 9, v183
	global_load_dwordx4 v[32:35], v136, s[20:21]
	global_load_dwordx4 v[36:39], v136, s[20:21] offset:64
	v_add_u32_e32 v135, 20, v252
	v_med3_i32 v135, v135, 0, s14
	v_lshl_add_u32 v135, v135, 9, v183
	global_load_dwordx4 v[40:43], v135, s[20:21]
	global_load_dwordx4 v[44:47], v135, s[20:21] offset:64
	ds_bpermute_b32 v142, v167, v132
	s_waitcnt lgkmcnt(0)
	v_add_f32_e32 v132, v132, v142
	ds_bpermute_b32 v142, v168, v132
	s_waitcnt lgkmcnt(0)
	v_add_f32_e32 v132, v132, v142
	ds_bpermute_b32 v142, v167, v133
	s_waitcnt lgkmcnt(0)
	v_add_f32_e32 v133, v133, v142
	ds_bpermute_b32 v142, v168, v133
	s_waitcnt lgkmcnt(0)
	v_add_f32_e32 v133, v133, v142
	s_waitcnt vmcnt(16)
	ds_write_b128 v165, v[64:67]
	ds_write_b128 v165, v[68:71] offset:1152
	ds_write_b128 v165, v[72:75] offset:2304
	ds_write_b128 v165, v[76:79] offset:3456
	s_waitcnt lgkmcnt(0)
	ds_read_b64_tr_b16 v[236:237], v166
	ds_read_b64_tr_b16 v[238:239], v166 offset:2304
	ds_read_b64_tr_b16 v[240:241], v166 offset:32
	ds_read_b64_tr_b16 v[242:243], v166 offset:2336
	ds_read_b64_tr_b16 v[244:245], v166 offset:64
	ds_read_b64_tr_b16 v[246:247], v166 offset:2368
	ds_read_b64_tr_b16 v[248:249], v166 offset:96
	ds_read_b64_tr_b16 v[250:251], v166 offset:2400
	s_waitcnt lgkmcnt(0)
	s_add_i32 s2, s40, 32
	v_add_u32_e32 v138, s2, v164
	v_add_u32_e32 v138, s41, v138
	v_and_b32_e32 v139, 3, v138
	v_lshlrev_b32_e32 v139, s39, v139
	v_bfe_u32 v140, v138, 2, 2
	v_add_u32_e32 v139, v139, v140
	v_lshl_add_u32 v139, v139, 7, v162
	v_ashrrev_i32_e32 v138, 4, v138
	v_med3_i32 v138, v138, 0, s38
	v_lshl_add_u32 v138, v138, 9, v139
	global_load_dwordx4 v[64:67], v138, s[26:27]
	s_add_i32 s2, s40, 40
	v_add_u32_e32 v138, s2, v164
	v_add_u32_e32 v138, s41, v138
	v_and_b32_e32 v139, 3, v138
	v_lshlrev_b32_e32 v139, s39, v139
	v_bfe_u32 v140, v138, 2, 2
	v_add_u32_e32 v139, v139, v140
	v_lshl_add_u32 v139, v139, 7, v162
	v_ashrrev_i32_e32 v138, 4, v138
	v_med3_i32 v138, v138, 0, s38
	v_lshl_add_u32 v138, v138, 9, v139
	global_load_dwordx4 v[68:71], v138, s[26:27]
	s_add_i32 s2, s40, 48
	v_add_u32_e32 v138, s2, v164
	v_add_u32_e32 v138, s41, v138
	v_and_b32_e32 v139, 3, v138
	v_lshlrev_b32_e32 v139, s39, v139
	v_bfe_u32 v140, v138, 2, 2
	v_add_u32_e32 v139, v139, v140
	v_lshl_add_u32 v139, v139, 7, v162
	v_ashrrev_i32_e32 v138, 4, v138
	v_med3_i32 v138, v138, 0, s38
	v_lshl_add_u32 v138, v138, 9, v139
	global_load_dwordx4 v[72:75], v138, s[26:27]
	s_add_i32 s2, s40, 56
	v_add_u32_e32 v138, s2, v164
	v_add_u32_e32 v138, s41, v138
	v_and_b32_e32 v139, 3, v138
	v_lshlrev_b32_e32 v139, s39, v139
	v_bfe_u32 v140, v138, 2, 2
	v_add_u32_e32 v139, v139, v140
	v_lshl_add_u32 v139, v139, 7, v162
	v_ashrrev_i32_e32 v138, 4, v138
	v_med3_i32 v138, v138, 0, s38
	v_lshl_add_u32 v138, v138, 9, v139
	global_load_dwordx4 v[76:79], v138, s[26:27]
	ds_write_b128 v165, v[80:83]
	ds_write_b128 v165, v[84:87] offset:1152
	ds_write_b128 v165, v[88:91] offset:2304
	ds_write_b128 v165, v[92:95] offset:3456
	v_mfma_f32_16x16x32_bf16 v[204:207], v[236:239], v[112:115], 0
	v_mfma_f32_16x16x32_bf16 v[208:211], v[240:243], v[112:115], 0
	v_mfma_f32_16x16x32_bf16 v[212:215], v[244:247], v[112:115], 0
	v_mfma_f32_16x16x32_bf16 v[216:219], v[248:251], v[112:115], 0
	v_mfma_f32_16x16x32_bf16 v[220:223], v[236:239], v[184:187], 0
	v_mfma_f32_16x16x32_bf16 v[224:227], v[240:243], v[184:187], 0
	v_mfma_f32_16x16x32_bf16 v[228:231], v[244:247], v[184:187], 0
	v_mfma_f32_16x16x32_bf16 v[232:235], v[248:251], v[184:187], 0
	s_waitcnt lgkmcnt(0)
	ds_read_b64_tr_b16 v[236:237], v166
	ds_read_b64_tr_b16 v[238:239], v166 offset:2304
	ds_read_b64_tr_b16 v[240:241], v166 offset:32
	ds_read_b64_tr_b16 v[242:243], v166 offset:2336
	ds_read_b64_tr_b16 v[244:245], v166 offset:64
	ds_read_b64_tr_b16 v[246:247], v166 offset:2368
	ds_read_b64_tr_b16 v[248:249], v166 offset:96
	ds_read_b64_tr_b16 v[250:251], v166 offset:2400
	s_waitcnt lgkmcnt(0)
	s_add_i32 s2, s40, 64
	v_add_u32_e32 v138, s2, v164
	v_add_u32_e32 v138, s41, v138
	v_and_b32_e32 v139, 3, v138
	v_lshlrev_b32_e32 v139, s39, v139
	v_bfe_u32 v140, v138, 2, 2
	v_add_u32_e32 v139, v139, v140
	v_lshl_add_u32 v139, v139, 7, v162
	v_ashrrev_i32_e32 v138, 4, v138
	v_med3_i32 v138, v138, 0, s38
	v_lshl_add_u32 v138, v138, 9, v139
	global_load_dwordx4 v[80:83], v138, s[26:27]
	s_add_i32 s2, s40, 72
	v_add_u32_e32 v138, s2, v164
	v_add_u32_e32 v138, s41, v138
	v_and_b32_e32 v139, 3, v138
	v_lshlrev_b32_e32 v139, s39, v139
	v_bfe_u32 v140, v138, 2, 2
	v_add_u32_e32 v139, v139, v140
	v_lshl_add_u32 v139, v139, 7, v162
	v_ashrrev_i32_e32 v138, 4, v138
	v_med3_i32 v138, v138, 0, s38
	v_lshl_add_u32 v138, v138, 9, v139
	global_load_dwordx4 v[84:87], v138, s[26:27]
	s_add_i32 s2, s40, 80
	v_add_u32_e32 v138, s2, v164
	v_add_u32_e32 v138, s41, v138
	v_and_b32_e32 v139, 3, v138
	v_lshlrev_b32_e32 v139, s39, v139
	v_bfe_u32 v140, v138, 2, 2
	v_add_u32_e32 v139, v139, v140
	v_lshl_add_u32 v139, v139, 7, v162
	v_ashrrev_i32_e32 v138, 4, v138
	v_med3_i32 v138, v138, 0, s38
	v_lshl_add_u32 v138, v138, 9, v139
	global_load_dwordx4 v[88:91], v138, s[26:27]
	s_add_i32 s2, s40, 88
	v_add_u32_e32 v138, s2, v164
	v_add_u32_e32 v138, s41, v138
	v_and_b32_e32 v139, 3, v138
	v_lshlrev_b32_e32 v139, s39, v139
	v_bfe_u32 v140, v138, 2, 2
	v_add_u32_e32 v139, v139, v140
	v_lshl_add_u32 v139, v139, 7, v162
	v_ashrrev_i32_e32 v138, 4, v138
	v_med3_i32 v138, v138, 0, s38
	v_lshl_add_u32 v138, v138, 9, v139
	global_load_dwordx4 v[92:95], v138, s[26:27]
	ds_write_b128 v165, v[96:99]
	ds_write_b128 v165, v[100:103] offset:1152
	ds_write_b128 v165, v[104:107] offset:2304
	ds_write_b128 v165, v[108:111] offset:3456
	v_mfma_f32_16x16x32_bf16 v[204:207], v[236:239], v[116:119], v[204:207]
	v_mfma_f32_16x16x32_bf16 v[208:211], v[240:243], v[116:119], v[208:211]
	v_mfma_f32_16x16x32_bf16 v[212:215], v[244:247], v[116:119], v[212:215]
	v_mfma_f32_16x16x32_bf16 v[216:219], v[248:251], v[116:119], v[216:219]
	v_mfma_f32_16x16x32_bf16 v[220:223], v[236:239], v[188:191], v[220:223]
	v_mfma_f32_16x16x32_bf16 v[224:227], v[240:243], v[188:191], v[224:227]
	v_mfma_f32_16x16x32_bf16 v[228:231], v[244:247], v[188:191], v[228:231]
	v_mfma_f32_16x16x32_bf16 v[232:235], v[248:251], v[188:191], v[232:235]
	s_waitcnt lgkmcnt(0)
	ds_read_b64_tr_b16 v[236:237], v166
	ds_read_b64_tr_b16 v[238:239], v166 offset:2304
	ds_read_b64_tr_b16 v[240:241], v166 offset:32
	ds_read_b64_tr_b16 v[242:243], v166 offset:2336
	ds_read_b64_tr_b16 v[244:245], v166 offset:64
	ds_read_b64_tr_b16 v[246:247], v166 offset:2368
	ds_read_b64_tr_b16 v[248:249], v166 offset:96
	ds_read_b64_tr_b16 v[250:251], v166 offset:2400
	s_waitcnt lgkmcnt(0)
	s_waitcnt vmcnt(4)
	ds_write_b128 v165, v[64:67]
	ds_write_b128 v165, v[68:71] offset:1152
	ds_write_b128 v165, v[72:75] offset:2304
	ds_write_b128 v165, v[76:79] offset:3456
	v_mfma_f32_16x16x32_bf16 v[204:207], v[236:239], v[120:123], v[204:207]
	v_mfma_f32_16x16x32_bf16 v[208:211], v[240:243], v[120:123], v[208:211]
	v_mfma_f32_16x16x32_bf16 v[212:215], v[244:247], v[120:123], v[212:215]
	v_mfma_f32_16x16x32_bf16 v[216:219], v[248:251], v[120:123], v[216:219]
	v_mfma_f32_16x16x32_bf16 v[220:223], v[236:239], v[192:195], v[220:223]
	v_mfma_f32_16x16x32_bf16 v[224:227], v[240:243], v[192:195], v[224:227]
	v_mfma_f32_16x16x32_bf16 v[228:231], v[244:247], v[192:195], v[228:231]
	v_mfma_f32_16x16x32_bf16 v[232:235], v[248:251], v[192:195], v[232:235]
	s_waitcnt lgkmcnt(0)
	ds_read_b64_tr_b16 v[236:237], v166
	ds_read_b64_tr_b16 v[238:239], v166 offset:2304
	ds_read_b64_tr_b16 v[240:241], v166 offset:32
	ds_read_b64_tr_b16 v[242:243], v166 offset:2336
	ds_read_b64_tr_b16 v[244:245], v166 offset:64
	ds_read_b64_tr_b16 v[246:247], v166 offset:2368
	ds_read_b64_tr_b16 v[248:249], v166 offset:96
	ds_read_b64_tr_b16 v[250:251], v166 offset:2400
	s_waitcnt lgkmcnt(0)
	s_waitcnt vmcnt(0)
	ds_write_b128 v165, v[80:83]
	ds_write_b128 v165, v[84:87] offset:1152
	ds_write_b128 v165, v[88:91] offset:2304
	ds_write_b128 v165, v[92:95] offset:3456
	v_mfma_f32_16x16x32_bf16 v[204:207], v[236:239], v[124:127], v[204:207]
	v_mfma_f32_16x16x32_bf16 v[208:211], v[240:243], v[124:127], v[208:211]
	v_mfma_f32_16x16x32_bf16 v[212:215], v[244:247], v[124:127], v[212:215]
	v_mfma_f32_16x16x32_bf16 v[216:219], v[248:251], v[124:127], v[216:219]
	v_mfma_f32_16x16x32_bf16 v[220:223], v[236:239], v[196:199], v[220:223]
	v_mfma_f32_16x16x32_bf16 v[224:227], v[240:243], v[196:199], v[224:227]
	v_mfma_f32_16x16x32_bf16 v[228:231], v[244:247], v[196:199], v[228:231]
	v_mfma_f32_16x16x32_bf16 v[232:235], v[248:251], v[196:199], v[232:235]
	s_waitcnt lgkmcnt(0)
	ds_read_b64_tr_b16 v[236:237], v166
	ds_read_b64_tr_b16 v[238:239], v166 offset:2304
	ds_read_b64_tr_b16 v[240:241], v166 offset:32
	ds_read_b64_tr_b16 v[242:243], v166 offset:2336
	ds_read_b64_tr_b16 v[244:245], v166 offset:64
	ds_read_b64_tr_b16 v[246:247], v166 offset:2368
	ds_read_b64_tr_b16 v[248:249], v166 offset:96
	ds_read_b64_tr_b16 v[250:251], v166 offset:2400
	s_waitcnt lgkmcnt(0)
	v_mfma_f32_16x16x32_bf16 v[204:207], v[236:239], v[128:131], v[204:207]
	v_mfma_f32_16x16x32_bf16 v[208:211], v[240:243], v[128:131], v[208:211]
	v_mfma_f32_16x16x32_bf16 v[212:215], v[244:247], v[128:131], v[212:215]
	v_mfma_f32_16x16x32_bf16 v[216:219], v[248:251], v[128:131], v[216:219]
	v_mfma_f32_16x16x32_bf16 v[220:223], v[236:239], v[200:203], v[220:223]
	v_mfma_f32_16x16x32_bf16 v[224:227], v[240:243], v[200:203], v[224:227]
	v_mfma_f32_16x16x32_bf16 v[228:231], v[244:247], v[200:203], v[228:231]
	v_mfma_f32_16x16x32_bf16 v[232:235], v[248:251], v[200:203], v[232:235]
	s_add_i32 s2, s42, -64
	v_add_u32_e32 v138, s2, v164
	v_lshlrev_b32_e32 v138, 2, v138
	v_add_u32_e32 v138, s43, v138
	v_and_b32_e32 v139, 3, v138
	v_lshlrev_b32_e32 v139, s13, v139
	v_bfe_u32 v140, v138, 2, 2
	v_add_u32_e32 v139, v139, v140
	v_lshl_add_u32 v139, v139, 7, v162
	v_ashrrev_i32_e32 v138, 4, v138
	v_med3_i32 v138, v138, 0, s14
	v_lshl_add_u32 v138, v138, 9, v139
	global_load_dwordx4 v[64:67], v138, s[22:23]
	s_add_i32 s2, s42, -56
	v_add_u32_e32 v138, s2, v164
	v_lshlrev_b32_e32 v138, 2, v138
	v_add_u32_e32 v138, s43, v138
	v_and_b32_e32 v139, 3, v138
	v_lshlrev_b32_e32 v139, s13, v139
	v_bfe_u32 v140, v138, 2, 2
	v_add_u32_e32 v139, v139, v140
	v_lshl_add_u32 v139, v139, 7, v162
	v_ashrrev_i32_e32 v138, 4, v138
	v_med3_i32 v138, v138, 0, s14
	v_lshl_add_u32 v138, v138, 9, v139
	global_load_dwordx4 v[68:71], v138, s[22:23]
	s_add_i32 s2, s42, -48
	v_add_u32_e32 v138, s2, v164
	v_lshlrev_b32_e32 v138, 2, v138
	v_add_u32_e32 v138, s43, v138
	v_and_b32_e32 v139, 3, v138
	v_lshlrev_b32_e32 v139, s13, v139
	v_bfe_u32 v140, v138, 2, 2
	v_add_u32_e32 v139, v139, v140
	v_lshl_add_u32 v139, v139, 7, v162
	v_ashrrev_i32_e32 v138, 4, v138
	v_med3_i32 v138, v138, 0, s14
	v_lshl_add_u32 v138, v138, 9, v139
	global_load_dwordx4 v[72:75], v138, s[22:23]
	s_add_i32 s2, s42, -40
	v_add_u32_e32 v138, s2, v164
	v_lshlrev_b32_e32 v138, 2, v138
	v_add_u32_e32 v138, s43, v138
	v_and_b32_e32 v139, 3, v138
	v_lshlrev_b32_e32 v139, s13, v139
	v_bfe_u32 v140, v138, 2, 2
	v_add_u32_e32 v139, v139, v140
	v_lshl_add_u32 v139, v139, 7, v162
	v_ashrrev_i32_e32 v138, 4, v138
	v_med3_i32 v138, v138, 0, s14
	v_lshl_add_u32 v138, v138, 9, v139
	global_load_dwordx4 v[76:79], v138, s[22:23]
	s_add_i32 s2, s42, -32
	v_add_u32_e32 v138, s2, v164
	v_lshlrev_b32_e32 v138, 2, v138
	v_add_u32_e32 v138, s43, v138
	v_and_b32_e32 v139, 3, v138
	v_lshlrev_b32_e32 v139, s13, v139
	v_bfe_u32 v140, v138, 2, 2
	v_add_u32_e32 v139, v139, v140
	v_lshl_add_u32 v139, v139, 7, v162
	v_ashrrev_i32_e32 v138, 4, v138
	v_med3_i32 v138, v138, 0, s14
	v_lshl_add_u32 v138, v138, 9, v139
	global_load_dwordx4 v[80:83], v138, s[22:23]
	s_add_i32 s2, s42, -24
	v_add_u32_e32 v138, s2, v164
	v_lshlrev_b32_e32 v138, 2, v138
	v_add_u32_e32 v138, s43, v138
	v_and_b32_e32 v139, 3, v138
	v_lshlrev_b32_e32 v139, s13, v139
	v_bfe_u32 v140, v138, 2, 2
	v_add_u32_e32 v139, v139, v140
	v_lshl_add_u32 v139, v139, 7, v162
	v_ashrrev_i32_e32 v138, 4, v138
	v_med3_i32 v138, v138, 0, s14
	v_lshl_add_u32 v138, v138, 9, v139
	global_load_dwordx4 v[84:87], v138, s[22:23]
	s_add_i32 s2, s42, -16
	v_add_u32_e32 v138, s2, v164
	v_lshlrev_b32_e32 v138, 2, v138
	v_add_u32_e32 v138, s43, v138
	v_and_b32_e32 v139, 3, v138
	v_lshlrev_b32_e32 v139, s13, v139
	v_bfe_u32 v140, v138, 2, 2
	v_add_u32_e32 v139, v139, v140
	v_lshl_add_u32 v139, v139, 7, v162
	v_ashrrev_i32_e32 v138, 4, v138
	v_med3_i32 v138, v138, 0, s14
	v_lshl_add_u32 v138, v138, 9, v139
	global_load_dwordx4 v[88:91], v138, s[22:23]
	s_add_i32 s2, s42, -8
	v_add_u32_e32 v138, s2, v164
	v_lshlrev_b32_e32 v138, 2, v138
	v_add_u32_e32 v138, s43, v138
	v_and_b32_e32 v139, 3, v138
	v_lshlrev_b32_e32 v139, s13, v139
	v_bfe_u32 v140, v138, 2, 2
	v_add_u32_e32 v139, v139, v140
	v_lshl_add_u32 v139, v139, 7, v162
	v_ashrrev_i32_e32 v138, 4, v138
	v_med3_i32 v138, v138, 0, s14
	v_lshl_add_u32 v138, v138, 9, v139
	global_load_dwordx4 v[92:95], v138, s[22:23]
	s_add_i32 s2, s42, 0
	v_add_u32_e32 v138, s2, v164
	v_lshlrev_b32_e32 v138, 2, v138
	v_add_u32_e32 v138, s43, v138
	v_and_b32_e32 v139, 3, v138
	v_lshlrev_b32_e32 v139, s13, v139
	v_bfe_u32 v140, v138, 2, 2
	v_add_u32_e32 v139, v139, v140
	v_lshl_add_u32 v139, v139, 7, v162
	v_ashrrev_i32_e32 v138, 4, v138
	v_med3_i32 v138, v138, 0, s14
	v_lshl_add_u32 v138, v138, 9, v139
	global_load_dwordx4 v[96:99], v138, s[22:23]
	s_add_i32 s2, s42, 8
	v_add_u32_e32 v138, s2, v164
	v_lshlrev_b32_e32 v138, 2, v138
	v_add_u32_e32 v138, s43, v138
	v_and_b32_e32 v139, 3, v138
	v_lshlrev_b32_e32 v139, s13, v139
	v_bfe_u32 v140, v138, 2, 2
	v_add_u32_e32 v139, v139, v140
	v_lshl_add_u32 v139, v139, 7, v162
	v_ashrrev_i32_e32 v138, 4, v138
	v_med3_i32 v138, v138, 0, s14
	v_lshl_add_u32 v138, v138, 9, v139
	global_load_dwordx4 v[100:103], v138, s[22:23]
	s_add_i32 s2, s42, 16
	v_add_u32_e32 v138, s2, v164
	v_lshlrev_b32_e32 v138, 2, v138
	v_add_u32_e32 v138, s43, v138
	v_and_b32_e32 v139, 3, v138
	v_lshlrev_b32_e32 v139, s13, v139
	v_bfe_u32 v140, v138, 2, 2
	v_add_u32_e32 v139, v139, v140
	v_lshl_add_u32 v139, v139, 7, v162
	v_ashrrev_i32_e32 v138, 4, v138
	v_med3_i32 v138, v138, 0, s14
	v_lshl_add_u32 v138, v138, 9, v139
	global_load_dwordx4 v[104:107], v138, s[22:23]
	s_add_i32 s2, s42, 24
	v_add_u32_e32 v138, s2, v164
	v_lshlrev_b32_e32 v138, 2, v138
	v_add_u32_e32 v138, s43, v138
	v_and_b32_e32 v139, 3, v138
	v_lshlrev_b32_e32 v139, s13, v139
	v_bfe_u32 v140, v138, 2, 2
	v_add_u32_e32 v139, v139, v140
	v_lshl_add_u32 v139, v139, 7, v162
	v_ashrrev_i32_e32 v138, 4, v138
	v_med3_i32 v138, v138, 0, s14
	v_lshl_add_u32 v138, v138, 9, v139
	global_load_dwordx4 v[108:111], v138, s[22:23]
	ds_write_b128 v173, v[204:207] offset:0
	ds_write_b128 v173, v[208:211] offset:64
	ds_write_b128 v173, v[212:215] offset:128
	ds_write_b128 v173, v[216:219] offset:192
	ds_write_b32 v174, v132 offset:0
	ds_write_b128 v173, v[220:223] offset:4624
	ds_write_b128 v173, v[224:227] offset:4688
	ds_write_b128 v173, v[228:231] offset:4752
	ds_write_b128 v173, v[232:235] offset:4816
	ds_write_b32 v174, v133 offset:64
	s_waitcnt lgkmcnt(0)
	s_barrier
	s_mov_b32 s40, s42
	s_mov_b32 s41, s43
	v_mov_b32_e32 v173, v176
	v_mov_b32_e32 v174, v177
	v_mov_b32_e32 v175, v178
	v_mov_b32_e32 v179, v183
	v_mov_b32_e32 v182, v252
	s_lshr_b32 s44, s33, 2
	s_lshr_b32 s42, s15, 4
	s_add_i32 s43, s0, 0
	s_waitcnt vmcnt(12)
	v_mov_b32_e32 v132, 0
	v_mov_b32_e32 v133, 0
	v_mfma_f32_16x16x32_bf16 v[236:239], v[0:3], v[48:51], 0
	v_mfma_f32_16x16x32_bf16 v[236:239], v[4:7], v[52:55], v[236:239]
	v_mfma_f32_16x16x32_bf16 v[240:243], v[8:11], v[48:51], 0
	v_mfma_f32_16x16x32_bf16 v[240:243], v[12:15], v[52:55], v[240:243]
	v_mfma_f32_16x16x32_bf16 v[248:251], v[8:11], v[56:59], 0
	v_mfma_f32_16x16x32_bf16 v[248:251], v[12:15], v[60:63], v[248:251]
	s_nop 7
	v_min_f32_e32 v152, 0x42a00000, v236
	v_min_f32_e32 v153, 0x42a00000, v237
	v_min_f32_e32 v154, 0x42a00000, v238
	v_min_f32_e32 v155, 0x42a00000, v239
	v_mfma_f32_16x16x32_bf16 v[236:239], v[16:19], v[48:51], 0
	v_mfma_f32_16x16x32_bf16 v[236:239], v[20:23], v[52:55], v[236:239]
	v_mfma_f32_16x16x32_bf16 v[244:247], v[16:19], v[56:59], 0
	v_mfma_f32_16x16x32_bf16 v[244:247], v[20:23], v[60:63], v[244:247]
	v_add_u32_e32 v136, 24, v182
	v_med3_i32 v136, v136, 0, s38
	v_lshl_add_u32 v136, v136, 9, v179
	global_load_dwordx4 v[0:3], v136, s[24:25]
	global_load_dwordx4 v[4:7], v136, s[24:25] offset:64
	v_mul_f32_e32 v152, 0x3fb8aa3b, v152
	v_mul_f32_e32 v153, 0x3fb8aa3b, v153
	v_mul_f32_e32 v154, 0x3fb8aa3b, v154
	v_mul_f32_e32 v155, 0x3fb8aa3b, v155
	v_exp_f32_e32 v152, v152
	v_exp_f32_e32 v153, v153
	v_exp_f32_e32 v154, v154
	v_exp_f32_e32 v155, v155
	v_add_u32_e32 v138, 0, v175
	v_add_u32_e32 v139, 1, v175
	v_add_u32_e32 v140, 2, v175
	v_add_u32_e32 v141, 3, v175
	v_cmp_gt_u32_e64 s[70:71], s44, v138
	v_cmp_gt_u32_e64 s[72:73], s44, v139
	v_cmp_gt_u32_e64 s[74:75], s44, v140
	v_cmp_gt_u32_e64 s[76:77], s44, v141
	v_cndmask_b32_e64 v152, 0, v152, s[54:55]
	v_cndmask_b32_e64 v153, 0, v153, s[56:57]
	v_cndmask_b32_e64 v154, 0, v154, s[58:59]
	v_cndmask_b32_e64 v155, 0, v155, s[60:61]
	v_cndmask_b32_e64 v152, 0, v152, s[70:71]
	v_cndmask_b32_e64 v153, 0, v153, s[72:73]
	v_cndmask_b32_e64 v154, 0, v154, s[74:75]
	v_cndmask_b32_e64 v155, 0, v155, s[76:77]
	v_add_f32_e32 v132, v132, v152
	v_add_f32_e32 v132, v132, v153
	v_add_f32_e32 v132, v132, v154
	v_add_f32_e32 v132, v132, v155
	v_cvt_pk_bf16_f32 v112, v152, v153
	v_cvt_pk_bf16_f32 v113, v154, v155
	v_min_f32_e32 v152, 0x42a00000, v240
	v_min_f32_e32 v153, 0x42a00000, v241
	v_min_f32_e32 v154, 0x42a00000, v242
	v_min_f32_e32 v155, 0x42a00000, v243
	v_min_f32_e32 v156, 0x42a00000, v248
	v_min_f32_e32 v157, 0x42a00000, v249
	v_min_f32_e32 v158, 0x42a00000, v250
	v_min_f32_e32 v159, 0x42a00000, v251
	v_mfma_f32_16x16x32_bf16 v[240:243], v[24:27], v[48:51], 0
	v_mfma_f32_16x16x32_bf16 v[240:243], v[28:31], v[52:55], v[240:243]
	v_mfma_f32_16x16x32_bf16 v[248:251], v[24:27], v[56:59], 0
	v_mfma_f32_16x16x32_bf16 v[248:251], v[28:31], v[60:63], v[248:251]
	v_add_u32_e32 v135, 28, v182
	v_med3_i32 v135, v135, 0, s38
	v_lshl_add_u32 v135, v135, 9, v179
	global_load_dwordx4 v[8:11], v135, s[24:25]
	global_load_dwordx4 v[12:15], v135, s[24:25] offset:64
	v_mul_f32_e32 v152, 0x3fb8aa3b, v152
	v_mul_f32_e32 v153, 0x3fb8aa3b, v153
	v_mul_f32_e32 v154, 0x3fb8aa3b, v154
	v_mul_f32_e32 v155, 0x3fb8aa3b, v155
	v_exp_f32_e32 v152, v152
	v_exp_f32_e32 v153, v153
	v_exp_f32_e32 v154, v154
	v_exp_f32_e32 v155, v155
	v_add_u32_e32 v138, 16, v175
	v_add_u32_e32 v139, 17, v175
	v_add_u32_e32 v140, 18, v175
	v_add_u32_e32 v141, 19, v175
	v_cmp_gt_u32_e64 s[70:71], s44, v138
	v_cmp_gt_u32_e64 s[72:73], s44, v139
	v_cmp_gt_u32_e64 s[74:75], s44, v140
	v_cmp_gt_u32_e64 s[76:77], s44, v141
	v_cndmask_b32_e64 v152, 0, v152, s[70:71]
	v_cndmask_b32_e64 v153, 0, v153, s[72:73]
	v_cndmask_b32_e64 v154, 0, v154, s[74:75]
	v_cndmask_b32_e64 v155, 0, v155, s[76:77]
	v_add_f32_e32 v132, v132, v152
	v_add_f32_e32 v132, v132, v153
	v_add_f32_e32 v132, v132, v154
	v_add_f32_e32 v132, v132, v155
	v_cvt_pk_bf16_f32 v114, v152, v153
	v_cvt_pk_bf16_f32 v115, v154, v155
	v_mul_f32_e32 v156, 0x3fb8aa3b, v156
	v_mul_f32_e32 v157, 0x3fb8aa3b, v157
	v_mul_f32_e32 v158, 0x3fb8aa3b, v158
	v_mul_f32_e32 v159, 0x3fb8aa3b, v159
	v_exp_f32_e32 v156, v156
	v_exp_f32_e32 v157, v157
	v_exp_f32_e32 v158, v158
	v_exp_f32_e32 v159, v159
	v_add_u32_e32 v138, 16, v175
	v_add_u32_e32 v139, 17, v175
	v_add_u32_e32 v140, 18, v175
	v_add_u32_e32 v141, 19, v175
	v_cmp_gt_u32_e64 s[70:71], s44, v138
	v_cmp_gt_u32_e64 s[72:73], s44, v139
	v_cmp_gt_u32_e64 s[74:75], s44, v140
	v_cmp_gt_u32_e64 s[76:77], s44, v141
	v_cndmask_b32_e64 v156, 0, v156, s[54:55]
	v_cndmask_b32_e64 v157, 0, v157, s[56:57]
	v_cndmask_b32_e64 v158, 0, v158, s[58:59]
	v_cndmask_b32_e64 v159, 0, v159, s[60:61]
	v_cndmask_b32_e64 v156, 0, v156, s[70:71]
	v_cndmask_b32_e64 v157, 0, v157, s[72:73]
	v_cndmask_b32_e64 v158, 0, v158, s[74:75]
	v_cndmask_b32_e64 v159, 0, v159, s[76:77]
	v_add_f32_e32 v133, v133, v156
	v_add_f32_e32 v133, v133, v157
	v_add_f32_e32 v133, v133, v158
	v_add_f32_e32 v133, v133, v159
	v_cvt_pk_bf16_f32 v186, v156, v157
	v_cvt_pk_bf16_f32 v187, v158, v159
	v_min_f32_e32 v152, 0x42a00000, v236
	v_min_f32_e32 v153, 0x42a00000, v237
	v_min_f32_e32 v154, 0x42a00000, v238
	v_min_f32_e32 v155, 0x42a00000, v239
	v_min_f32_e32 v156, 0x42a00000, v244
	v_min_f32_e32 v157, 0x42a00000, v245
	v_min_f32_e32 v158, 0x42a00000, v246
	v_min_f32_e32 v159, 0x42a00000, v247
	v_mfma_f32_16x16x32_bf16 v[236:239], v[32:35], v[48:51], 0
	v_mfma_f32_16x16x32_bf16 v[236:239], v[36:39], v[52:55], v[236:239]
	v_mfma_f32_16x16x32_bf16 v[244:247], v[32:35], v[56:59], 0
	v_mfma_f32_16x16x32_bf16 v[244:247], v[36:39], v[60:63], v[244:247]
	v_add_u32_e32 v136, 32, v182
	v_med3_i32 v136, v136, 0, s38
	v_lshl_add_u32 v136, v136, 9, v179
	global_load_dwordx4 v[16:19], v136, s[24:25]
	global_load_dwordx4 v[20:23], v136, s[24:25] offset:64
	v_mul_f32_e32 v152, 0x3fb8aa3b, v152
	v_mul_f32_e32 v153, 0x3fb8aa3b, v153
	v_mul_f32_e32 v154, 0x3fb8aa3b, v154
	v_mul_f32_e32 v155, 0x3fb8aa3b, v155
	v_exp_f32_e32 v152, v152
	v_exp_f32_e32 v153, v153
	v_exp_f32_e32 v154, v154
	v_exp_f32_e32 v155, v155
	v_add_u32_e32 v138, 32, v175
	v_add_u32_e32 v139, 33, v175
	v_add_u32_e32 v140, 34, v175
	v_add_u32_e32 v141, 35, v175
	v_cmp_gt_u32_e64 s[70:71], s44, v138
	v_cmp_gt_u32_e64 s[72:73], s44, v139
	v_cmp_gt_u32_e64 s[74:75], s44, v140
	v_cmp_gt_u32_e64 s[76:77], s44, v141
	v_cndmask_b32_e64 v152, 0, v152, s[70:71]
	v_cndmask_b32_e64 v153, 0, v153, s[72:73]
	v_cndmask_b32_e64 v154, 0, v154, s[74:75]
	v_cndmask_b32_e64 v155, 0, v155, s[76:77]
	v_add_f32_e32 v132, v132, v152
	v_add_f32_e32 v132, v132, v153
	v_add_f32_e32 v132, v132, v154
	v_add_f32_e32 v132, v132, v155
	v_cvt_pk_bf16_f32 v116, v152, v153
	v_cvt_pk_bf16_f32 v117, v154, v155
	v_mul_f32_e32 v156, 0x3fb8aa3b, v156
	v_mul_f32_e32 v157, 0x3fb8aa3b, v157
	v_mul_f32_e32 v158, 0x3fb8aa3b, v158
	v_mul_f32_e32 v159, 0x3fb8aa3b, v159
	v_exp_f32_e32 v156, v156
	v_exp_f32_e32 v157, v157
	v_exp_f32_e32 v158, v158
	v_exp_f32_e32 v159, v159
	v_add_u32_e32 v138, 32, v175
	v_add_u32_e32 v139, 33, v175
	v_add_u32_e32 v140, 34, v175
	v_add_u32_e32 v141, 35, v175
	v_cmp_gt_u32_e64 s[70:71], s44, v138
	v_cmp_gt_u32_e64 s[72:73], s44, v139
	v_cmp_gt_u32_e64 s[74:75], s44, v140
	v_cmp_gt_u32_e64 s[76:77], s44, v141
	v_cndmask_b32_e64 v156, 0, v156, s[70:71]
	v_cndmask_b32_e64 v157, 0, v157, s[72:73]
	v_cndmask_b32_e64 v158, 0, v158, s[74:75]
	v_cndmask_b32_e64 v159, 0, v159, s[76:77]
	v_add_f32_e32 v133, v133, v156
	v_add_f32_e32 v133, v133, v157
	v_add_f32_e32 v133, v133, v158
	v_add_f32_e32 v133, v133, v159
	v_cvt_pk_bf16_f32 v188, v156, v157
	v_cvt_pk_bf16_f32 v189, v158, v159
	v_min_f32_e32 v152, 0x42a00000, v240
	v_min_f32_e32 v153, 0x42a00000, v241
	v_min_f32_e32 v154, 0x42a00000, v242
	v_min_f32_e32 v155, 0x42a00000, v243
	v_min_f32_e32 v156, 0x42a00000, v248
	v_min_f32_e32 v157, 0x42a00000, v249
	v_min_f32_e32 v158, 0x42a00000, v250
	v_min_f32_e32 v159, 0x42a00000, v251
	v_mfma_f32_16x16x32_bf16 v[240:243], v[40:43], v[48:51], 0
	v_mfma_f32_16x16x32_bf16 v[240:243], v[44:47], v[52:55], v[240:243]
	v_mfma_f32_16x16x32_bf16 v[248:251], v[40:43], v[56:59], 0
	v_mfma_f32_16x16x32_bf16 v[248:251], v[44:47], v[60:63], v[248:251]
	v_add_u32_e32 v135, 36, v182
	v_med3_i32 v135, v135, 0, s38
	v_lshl_add_u32 v135, v135, 9, v179
	global_load_dwordx4 v[24:27], v135, s[24:25]
	global_load_dwordx4 v[28:31], v135, s[24:25] offset:64
	v_mul_f32_e32 v152, 0x3fb8aa3b, v152
	v_mul_f32_e32 v153, 0x3fb8aa3b, v153
	v_mul_f32_e32 v154, 0x3fb8aa3b, v154
	v_mul_f32_e32 v155, 0x3fb8aa3b, v155
	v_exp_f32_e32 v152, v152
	v_exp_f32_e32 v153, v153
	v_exp_f32_e32 v154, v154
	v_exp_f32_e32 v155, v155
	v_add_u32_e32 v138, 48, v175
	v_add_u32_e32 v139, 49, v175
	v_add_u32_e32 v140, 50, v175
	v_add_u32_e32 v141, 51, v175
	v_cmp_gt_u32_e64 s[70:71], s44, v138
	v_cmp_gt_u32_e64 s[72:73], s44, v139
	v_cmp_gt_u32_e64 s[74:75], s44, v140
	v_cmp_gt_u32_e64 s[76:77], s44, v141
	v_cndmask_b32_e64 v152, 0, v152, s[70:71]
	v_cndmask_b32_e64 v153, 0, v153, s[72:73]
	v_cndmask_b32_e64 v154, 0, v154, s[74:75]
	v_cndmask_b32_e64 v155, 0, v155, s[76:77]
	v_add_f32_e32 v132, v132, v152
	v_add_f32_e32 v132, v132, v153
	v_add_f32_e32 v132, v132, v154
	v_add_f32_e32 v132, v132, v155
	v_cvt_pk_bf16_f32 v118, v152, v153
	v_cvt_pk_bf16_f32 v119, v154, v155
	v_mul_f32_e32 v156, 0x3fb8aa3b, v156
	v_mul_f32_e32 v157, 0x3fb8aa3b, v157
	v_mul_f32_e32 v158, 0x3fb8aa3b, v158
	v_mul_f32_e32 v159, 0x3fb8aa3b, v159
	v_exp_f32_e32 v156, v156
	v_exp_f32_e32 v157, v157
	v_exp_f32_e32 v158, v158
	v_exp_f32_e32 v159, v159
	v_add_u32_e32 v138, 48, v175
	v_add_u32_e32 v139, 49, v175
	v_add_u32_e32 v140, 50, v175
	v_add_u32_e32 v141, 51, v175
	v_cmp_gt_u32_e64 s[70:71], s44, v138
	v_cmp_gt_u32_e64 s[72:73], s44, v139
	v_cmp_gt_u32_e64 s[74:75], s44, v140
	v_cmp_gt_u32_e64 s[76:77], s44, v141
	v_cndmask_b32_e64 v156, 0, v156, s[70:71]
	v_cndmask_b32_e64 v157, 0, v157, s[72:73]
	v_cndmask_b32_e64 v158, 0, v158, s[74:75]
	v_cndmask_b32_e64 v159, 0, v159, s[76:77]
	v_add_f32_e32 v133, v133, v156
	v_add_f32_e32 v133, v133, v157
	v_add_f32_e32 v133, v133, v158
	v_add_f32_e32 v133, v133, v159
	v_cvt_pk_bf16_f32 v190, v156, v157
	v_cvt_pk_bf16_f32 v191, v158, v159
	v_min_f32_e32 v152, 0x42a00000, v236
	v_min_f32_e32 v153, 0x42a00000, v237
	v_min_f32_e32 v154, 0x42a00000, v238
	v_min_f32_e32 v155, 0x42a00000, v239
	v_min_f32_e32 v156, 0x42a00000, v244
	v_min_f32_e32 v157, 0x42a00000, v245
	v_min_f32_e32 v158, 0x42a00000, v246
	v_min_f32_e32 v159, 0x42a00000, v247
	s_waitcnt vmcnt(6)
	v_mfma_f32_16x16x32_bf16 v[236:239], v[0:3], v[48:51], 0
	v_mfma_f32_16x16x32_bf16 v[236:239], v[4:7], v[52:55], v[236:239]
	v_mfma_f32_16x16x32_bf16 v[244:247], v[0:3], v[56:59], 0
	v_mfma_f32_16x16x32_bf16 v[244:247], v[4:7], v[60:63], v[244:247]
	v_mul_f32_e32 v152, 0x3fb8aa3b, v152
	v_mul_f32_e32 v153, 0x3fb8aa3b, v153
	v_mul_f32_e32 v154, 0x3fb8aa3b, v154
	v_mul_f32_e32 v155, 0x3fb8aa3b, v155
	v_exp_f32_e32 v152, v152
	v_exp_f32_e32 v153, v153
	v_exp_f32_e32 v154, v154
	v_exp_f32_e32 v155, v155
	v_add_u32_e32 v138, 64, v175
	v_add_u32_e32 v139, 0x41, v175
	v_add_u32_e32 v140, 0x42, v175
	v_add_u32_e32 v141, 0x43, v175
	v_cmp_gt_u32_e64 s[70:71], s44, v138
	v_cmp_gt_u32_e64 s[72:73], s44, v139
	v_cmp_gt_u32_e64 s[74:75], s44, v140
	v_cmp_gt_u32_e64 s[76:77], s44, v141
	v_cndmask_b32_e64 v152, 0, v152, s[70:71]
	v_cndmask_b32_e64 v153, 0, v153, s[72:73]
	v_cndmask_b32_e64 v154, 0, v154, s[74:75]
	v_cndmask_b32_e64 v155, 0, v155, s[76:77]
	v_add_f32_e32 v132, v132, v152
	v_add_f32_e32 v132, v132, v153
	v_add_f32_e32 v132, v132, v154
	v_add_f32_e32 v132, v132, v155
	v_cvt_pk_bf16_f32 v120, v152, v153
	v_cvt_pk_bf16_f32 v121, v154, v155
	v_mul_f32_e32 v156, 0x3fb8aa3b, v156
	v_mul_f32_e32 v157, 0x3fb8aa3b, v157
	v_mul_f32_e32 v158, 0x3fb8aa3b, v158
	v_mul_f32_e32 v159, 0x3fb8aa3b, v159
	v_exp_f32_e32 v156, v156
	v_exp_f32_e32 v157, v157
	v_exp_f32_e32 v158, v158
	v_exp_f32_e32 v159, v159
	v_add_u32_e32 v138, 64, v175
	v_add_u32_e32 v139, 0x41, v175
	v_add_u32_e32 v140, 0x42, v175
	v_add_u32_e32 v141, 0x43, v175
	v_cmp_gt_u32_e64 s[70:71], s44, v138
	v_cmp_gt_u32_e64 s[72:73], s44, v139
	v_cmp_gt_u32_e64 s[74:75], s44, v140
	v_cmp_gt_u32_e64 s[76:77], s44, v141
	v_cndmask_b32_e64 v156, 0, v156, s[70:71]
	v_cndmask_b32_e64 v157, 0, v157, s[72:73]
	v_cndmask_b32_e64 v158, 0, v158, s[74:75]
	v_cndmask_b32_e64 v159, 0, v159, s[76:77]
	v_add_f32_e32 v133, v133, v156
	v_add_f32_e32 v133, v133, v157
	v_add_f32_e32 v133, v133, v158
	v_add_f32_e32 v133, v133, v159
	v_cvt_pk_bf16_f32 v192, v156, v157
	v_cvt_pk_bf16_f32 v193, v158, v159
	v_min_f32_e32 v152, 0x42a00000, v240
	v_min_f32_e32 v153, 0x42a00000, v241
	v_min_f32_e32 v154, 0x42a00000, v242
	v_min_f32_e32 v155, 0x42a00000, v243
	v_min_f32_e32 v156, 0x42a00000, v248
	v_min_f32_e32 v157, 0x42a00000, v249
	v_min_f32_e32 v158, 0x42a00000, v250
	v_min_f32_e32 v159, 0x42a00000, v251
	s_waitcnt vmcnt(4)
	v_mfma_f32_16x16x32_bf16 v[240:243], v[8:11], v[48:51], 0
	v_mfma_f32_16x16x32_bf16 v[240:243], v[12:15], v[52:55], v[240:243]
	v_mfma_f32_16x16x32_bf16 v[248:251], v[8:11], v[56:59], 0
	v_mfma_f32_16x16x32_bf16 v[248:251], v[12:15], v[60:63], v[248:251]
	v_mul_f32_e32 v152, 0x3fb8aa3b, v152
	v_mul_f32_e32 v153, 0x3fb8aa3b, v153
	v_mul_f32_e32 v154, 0x3fb8aa3b, v154
	v_mul_f32_e32 v155, 0x3fb8aa3b, v155
	v_exp_f32_e32 v152, v152
	v_exp_f32_e32 v153, v153
	v_exp_f32_e32 v154, v154
	v_exp_f32_e32 v155, v155
	v_add_u32_e32 v138, 0x50, v175
	v_add_u32_e32 v139, 0x51, v175
	v_add_u32_e32 v140, 0x52, v175
	v_add_u32_e32 v141, 0x53, v175
	v_cmp_gt_u32_e64 s[70:71], s44, v138
	v_cmp_gt_u32_e64 s[72:73], s44, v139
	v_cmp_gt_u32_e64 s[74:75], s44, v140
	v_cmp_gt_u32_e64 s[76:77], s44, v141
	v_cndmask_b32_e64 v152, 0, v152, s[70:71]
	v_cndmask_b32_e64 v153, 0, v153, s[72:73]
	v_cndmask_b32_e64 v154, 0, v154, s[74:75]
	v_cndmask_b32_e64 v155, 0, v155, s[76:77]
	v_add_f32_e32 v132, v132, v152
	v_add_f32_e32 v132, v132, v153
	v_add_f32_e32 v132, v132, v154
	v_add_f32_e32 v132, v132, v155
	v_cvt_pk_bf16_f32 v122, v152, v153
	v_cvt_pk_bf16_f32 v123, v154, v155
	v_mul_f32_e32 v156, 0x3fb8aa3b, v156
	v_mul_f32_e32 v157, 0x3fb8aa3b, v157
	v_mul_f32_e32 v158, 0x3fb8aa3b, v158
	v_mul_f32_e32 v159, 0x3fb8aa3b, v159
	v_exp_f32_e32 v156, v156
	v_exp_f32_e32 v157, v157
	v_exp_f32_e32 v158, v158
	v_exp_f32_e32 v159, v159
	v_add_u32_e32 v138, 0x50, v175
	v_add_u32_e32 v139, 0x51, v175
	v_add_u32_e32 v140, 0x52, v175
	v_add_u32_e32 v141, 0x53, v175
	v_cmp_gt_u32_e64 s[70:71], s44, v138
	v_cmp_gt_u32_e64 s[72:73], s44, v139
	v_cmp_gt_u32_e64 s[74:75], s44, v140
	v_cmp_gt_u32_e64 s[76:77], s44, v141
	v_cndmask_b32_e64 v156, 0, v156, s[70:71]
	v_cndmask_b32_e64 v157, 0, v157, s[72:73]
	v_cndmask_b32_e64 v158, 0, v158, s[74:75]
	v_cndmask_b32_e64 v159, 0, v159, s[76:77]
	v_add_f32_e32 v133, v133, v156
	v_add_f32_e32 v133, v133, v157
	v_add_f32_e32 v133, v133, v158
	v_add_f32_e32 v133, v133, v159
	v_cvt_pk_bf16_f32 v194, v156, v157
	v_cvt_pk_bf16_f32 v195, v158, v159
	v_min_f32_e32 v152, 0x42a00000, v236
	v_min_f32_e32 v153, 0x42a00000, v237
	v_min_f32_e32 v154, 0x42a00000, v238
	v_min_f32_e32 v155, 0x42a00000, v239
	v_min_f32_e32 v156, 0x42a00000, v244
	v_min_f32_e32 v157, 0x42a00000, v245
	v_min_f32_e32 v158, 0x42a00000, v246
	v_min_f32_e32 v159, 0x42a00000, v247
	s_waitcnt vmcnt(2)
	v_mfma_f32_16x16x32_bf16 v[236:239], v[16:19], v[48:51], 0
	v_mfma_f32_16x16x32_bf16 v[236:239], v[20:23], v[52:55], v[236:239]
	v_mfma_f32_16x16x32_bf16 v[244:247], v[16:19], v[56:59], 0
	v_mfma_f32_16x16x32_bf16 v[244:247], v[20:23], v[60:63], v[244:247]
	v_mul_f32_e32 v152, 0x3fb8aa3b, v152
	v_mul_f32_e32 v153, 0x3fb8aa3b, v153
	v_mul_f32_e32 v154, 0x3fb8aa3b, v154
	v_mul_f32_e32 v155, 0x3fb8aa3b, v155
	v_exp_f32_e32 v152, v152
	v_exp_f32_e32 v153, v153
	v_exp_f32_e32 v154, v154
	v_exp_f32_e32 v155, v155
	v_add_u32_e32 v138, 0x60, v175
	v_add_u32_e32 v139, 0x61, v175
	v_add_u32_e32 v140, 0x62, v175
	v_add_u32_e32 v141, 0x63, v175
	v_cmp_gt_u32_e64 s[70:71], s44, v138
	v_cmp_gt_u32_e64 s[72:73], s44, v139
	v_cmp_gt_u32_e64 s[74:75], s44, v140
	v_cmp_gt_u32_e64 s[76:77], s44, v141
	v_cndmask_b32_e64 v152, 0, v152, s[70:71]
	v_cndmask_b32_e64 v153, 0, v153, s[72:73]
	v_cndmask_b32_e64 v154, 0, v154, s[74:75]
	v_cndmask_b32_e64 v155, 0, v155, s[76:77]
	v_add_f32_e32 v132, v132, v152
	v_add_f32_e32 v132, v132, v153
	v_add_f32_e32 v132, v132, v154
	v_add_f32_e32 v132, v132, v155
	v_cvt_pk_bf16_f32 v124, v152, v153
	v_cvt_pk_bf16_f32 v125, v154, v155
	v_mul_f32_e32 v156, 0x3fb8aa3b, v156
	v_mul_f32_e32 v157, 0x3fb8aa3b, v157
	v_mul_f32_e32 v158, 0x3fb8aa3b, v158
	v_mul_f32_e32 v159, 0x3fb8aa3b, v159
	v_exp_f32_e32 v156, v156
	v_exp_f32_e32 v157, v157
	v_exp_f32_e32 v158, v158
	v_exp_f32_e32 v159, v159
	v_add_u32_e32 v138, 0x60, v175
	v_add_u32_e32 v139, 0x61, v175
	v_add_u32_e32 v140, 0x62, v175
	v_add_u32_e32 v141, 0x63, v175
	v_cmp_gt_u32_e64 s[70:71], s44, v138
	v_cmp_gt_u32_e64 s[72:73], s44, v139
	v_cmp_gt_u32_e64 s[74:75], s44, v140
	v_cmp_gt_u32_e64 s[76:77], s44, v141
	v_cndmask_b32_e64 v156, 0, v156, s[70:71]
	v_cndmask_b32_e64 v157, 0, v157, s[72:73]
	v_cndmask_b32_e64 v158, 0, v158, s[74:75]
	v_cndmask_b32_e64 v159, 0, v159, s[76:77]
	v_add_f32_e32 v133, v133, v156
	v_add_f32_e32 v133, v133, v157
	v_add_f32_e32 v133, v133, v158
	v_add_f32_e32 v133, v133, v159
	v_cvt_pk_bf16_f32 v196, v156, v157
	v_cvt_pk_bf16_f32 v197, v158, v159
	v_min_f32_e32 v152, 0x42a00000, v240
	v_min_f32_e32 v153, 0x42a00000, v241
	v_min_f32_e32 v154, 0x42a00000, v242
	v_min_f32_e32 v155, 0x42a00000, v243
	v_min_f32_e32 v156, 0x42a00000, v248
	v_min_f32_e32 v157, 0x42a00000, v249
	v_min_f32_e32 v158, 0x42a00000, v250
	v_min_f32_e32 v159, 0x42a00000, v251
	s_waitcnt vmcnt(0)
	v_mfma_f32_16x16x32_bf16 v[248:251], v[24:27], v[56:59], 0
	v_mfma_f32_16x16x32_bf16 v[248:251], v[28:31], v[60:63], v[248:251]
	v_mul_f32_e32 v152, 0x3fb8aa3b, v152
	v_mul_f32_e32 v153, 0x3fb8aa3b, v153
	v_mul_f32_e32 v154, 0x3fb8aa3b, v154
	v_mul_f32_e32 v155, 0x3fb8aa3b, v155
	v_exp_f32_e32 v152, v152
	v_exp_f32_e32 v153, v153
	v_exp_f32_e32 v154, v154
	v_exp_f32_e32 v155, v155
	v_add_u32_e32 v138, 0x70, v175
	v_add_u32_e32 v139, 0x71, v175
	v_add_u32_e32 v140, 0x72, v175
	v_add_u32_e32 v141, 0x73, v175
	v_cmp_gt_u32_e64 s[70:71], s44, v138
	v_cmp_gt_u32_e64 s[72:73], s44, v139
	v_cmp_gt_u32_e64 s[74:75], s44, v140
	v_cmp_gt_u32_e64 s[76:77], s44, v141
	v_cndmask_b32_e64 v152, 0, v152, s[70:71]
	v_cndmask_b32_e64 v153, 0, v153, s[72:73]
	v_cndmask_b32_e64 v154, 0, v154, s[74:75]
	v_cndmask_b32_e64 v155, 0, v155, s[76:77]
	v_add_f32_e32 v132, v132, v152
	v_add_f32_e32 v132, v132, v153
	v_add_f32_e32 v132, v132, v154
	v_add_f32_e32 v132, v132, v155
	v_cvt_pk_bf16_f32 v126, v152, v153
	v_cvt_pk_bf16_f32 v127, v154, v155
	v_mul_f32_e32 v156, 0x3fb8aa3b, v156
	v_mul_f32_e32 v157, 0x3fb8aa3b, v157
	v_mul_f32_e32 v158, 0x3fb8aa3b, v158
	v_mul_f32_e32 v159, 0x3fb8aa3b, v159
	v_exp_f32_e32 v156, v156
	v_exp_f32_e32 v157, v157
	v_exp_f32_e32 v158, v158
	v_exp_f32_e32 v159, v159
	v_add_u32_e32 v138, 0x70, v175
	v_add_u32_e32 v139, 0x71, v175
	v_add_u32_e32 v140, 0x72, v175
	v_add_u32_e32 v141, 0x73, v175
	v_cmp_gt_u32_e64 s[70:71], s44, v138
	v_cmp_gt_u32_e64 s[72:73], s44, v139
	v_cmp_gt_u32_e64 s[74:75], s44, v140
	v_cmp_gt_u32_e64 s[76:77], s44, v141
	v_cndmask_b32_e64 v156, 0, v156, s[70:71]
	v_cndmask_b32_e64 v157, 0, v157, s[72:73]
	v_cndmask_b32_e64 v158, 0, v158, s[74:75]
	v_cndmask_b32_e64 v159, 0, v159, s[76:77]
	v_add_f32_e32 v133, v133, v156
	v_add_f32_e32 v133, v133, v157
	v_add_f32_e32 v133, v133, v158
	v_add_f32_e32 v133, v133, v159
	v_cvt_pk_bf16_f32 v198, v156, v157
	v_cvt_pk_bf16_f32 v199, v158, v159
	v_min_f32_e32 v152, 0x42a00000, v236
	v_min_f32_e32 v153, 0x42a00000, v237
	v_min_f32_e32 v154, 0x42a00000, v238
	v_min_f32_e32 v155, 0x42a00000, v239
	v_min_f32_e32 v156, 0x42a00000, v244
	v_min_f32_e32 v157, 0x42a00000, v245
	v_min_f32_e32 v158, 0x42a00000, v246
	v_min_f32_e32 v159, 0x42a00000, v247
	v_mul_f32_e32 v152, 0x3fb8aa3b, v152
	v_mul_f32_e32 v153, 0x3fb8aa3b, v153
	v_mul_f32_e32 v154, 0x3fb8aa3b, v154
	v_mul_f32_e32 v155, 0x3fb8aa3b, v155
	v_exp_f32_e32 v152, v152
	v_exp_f32_e32 v153, v153
	v_exp_f32_e32 v154, v154
	v_exp_f32_e32 v155, v155
	v_add_u32_e32 v138, 0x80, v175
	v_add_u32_e32 v139, 0x81, v175
	v_add_u32_e32 v140, 0x82, v175
	v_add_u32_e32 v141, 0x83, v175
	v_cmp_gt_u32_e64 s[70:71], s44, v138
	v_cmp_gt_u32_e64 s[72:73], s44, v139
	v_cmp_gt_u32_e64 s[74:75], s44, v140
	v_cmp_gt_u32_e64 s[76:77], s44, v141
	v_cndmask_b32_e64 v152, 0, v152, s[62:63]
	v_cndmask_b32_e64 v153, 0, v153, s[64:65]
	v_cndmask_b32_e64 v154, 0, v154, s[66:67]
	v_cndmask_b32_e64 v155, 0, v155, s[68:69]
	v_cndmask_b32_e64 v152, 0, v152, s[70:71]
	v_cndmask_b32_e64 v153, 0, v153, s[72:73]
	v_cndmask_b32_e64 v154, 0, v154, s[74:75]
	v_cndmask_b32_e64 v155, 0, v155, s[76:77]
	v_add_f32_e32 v132, v132, v152
	v_add_f32_e32 v132, v132, v153
	v_add_f32_e32 v132, v132, v154
	v_add_f32_e32 v132, v132, v155
	v_cvt_pk_bf16_f32 v128, v152, v153
	v_cvt_pk_bf16_f32 v129, v154, v155
	v_mul_f32_e32 v156, 0x3fb8aa3b, v156
	v_mul_f32_e32 v157, 0x3fb8aa3b, v157
	v_mul_f32_e32 v158, 0x3fb8aa3b, v158
	v_mul_f32_e32 v159, 0x3fb8aa3b, v159
	v_exp_f32_e32 v156, v156
	v_exp_f32_e32 v157, v157
	v_exp_f32_e32 v158, v158
	v_exp_f32_e32 v159, v159
	v_add_u32_e32 v138, 0x80, v175
	v_add_u32_e32 v139, 0x81, v175
	v_add_u32_e32 v140, 0x82, v175
	v_add_u32_e32 v141, 0x83, v175
	v_cmp_gt_u32_e64 s[70:71], s44, v138
	v_cmp_gt_u32_e64 s[72:73], s44, v139
	v_cmp_gt_u32_e64 s[74:75], s44, v140
	v_cmp_gt_u32_e64 s[76:77], s44, v141
	v_cndmask_b32_e64 v156, 0, v156, s[70:71]
	v_cndmask_b32_e64 v157, 0, v157, s[72:73]
	v_cndmask_b32_e64 v158, 0, v158, s[74:75]
	v_cndmask_b32_e64 v159, 0, v159, s[76:77]
	v_add_f32_e32 v133, v133, v156
	v_add_f32_e32 v133, v133, v157
	v_add_f32_e32 v133, v133, v158
	v_add_f32_e32 v133, v133, v159
	v_cvt_pk_bf16_f32 v200, v156, v157
	v_cvt_pk_bf16_f32 v201, v158, v159
	v_min_f32_e32 v156, 0x42a00000, v248
	v_min_f32_e32 v157, 0x42a00000, v249
	v_min_f32_e32 v158, 0x42a00000, v250
	v_min_f32_e32 v159, 0x42a00000, v251
	v_mul_f32_e32 v156, 0x3fb8aa3b, v156
	v_mul_f32_e32 v157, 0x3fb8aa3b, v157
	v_mul_f32_e32 v158, 0x3fb8aa3b, v158
	v_mul_f32_e32 v159, 0x3fb8aa3b, v159
	v_exp_f32_e32 v156, v156
	v_exp_f32_e32 v157, v157
	v_exp_f32_e32 v158, v158
	v_exp_f32_e32 v159, v159
	v_add_u32_e32 v138, 0x90, v175
	v_add_u32_e32 v139, 0x91, v175
	v_add_u32_e32 v140, 0x92, v175
	v_add_u32_e32 v141, 0x93, v175
	v_cmp_gt_u32_e64 s[70:71], s44, v138
	v_cmp_gt_u32_e64 s[72:73], s44, v139
	v_cmp_gt_u32_e64 s[74:75], s44, v140
	v_cmp_gt_u32_e64 s[76:77], s44, v141
	v_cndmask_b32_e64 v156, 0, v156, s[62:63]
	v_cndmask_b32_e64 v157, 0, v157, s[64:65]
	v_cndmask_b32_e64 v158, 0, v158, s[66:67]
	v_cndmask_b32_e64 v159, 0, v159, s[68:69]
	v_cndmask_b32_e64 v156, 0, v156, s[70:71]
	v_cndmask_b32_e64 v157, 0, v157, s[72:73]
	v_cndmask_b32_e64 v158, 0, v158, s[74:75]
	v_cndmask_b32_e64 v159, 0, v159, s[76:77]
	v_add_f32_e32 v133, v133, v156
	v_add_f32_e32 v133, v133, v157
	v_add_f32_e32 v133, v133, v158
	v_add_f32_e32 v133, v133, v159
	v_cvt_pk_bf16_f32 v202, v156, v157
	v_cvt_pk_bf16_f32 v203, v158, v159
	v_add_u32_e32 v134, s42, v160
	v_lshlrev_b32_e32 v134, 4, v134
	v_add_u32_e32 v134, s43, v134
	v_subrev_u32_e32 v135, s15, v134
	v_lshrrev_b32_e32 v136, 4, v135
	v_add_u32_e32 v136, v136, v135
	v_mad_u32_u24 v176, v136, s79, v161
	v_lshl_add_u32 v177, v135, 2, s80
	s_sub_i32 s2, s42, 64
	v_add_u32_e32 v178, s2, v169
	v_and_b32_e32 v135, 3, v134
	v_lshlrev_b32_e32 v135, s13, v135
	v_lshrrev_b32_e32 v136, 2, v134
	v_add_u32_e32 v135, v135, v136
	v_lshl_add_u32 v135, v135, 7, v161
	global_load_dwordx4 v[48:51], v135, s[18:19]
	global_load_dwordx4 v[52:55], v135, s[18:19] offset:64
	v_subrev_u32_e32 v134, 0x400, v134
	v_and_b32_e32 v137, 3, v134
	v_lshlrev_b32_e32 v137, s13, v137
	v_bfe_u32 v135, v134, 2, 2
	v_add_u32_e32 v137, v137, v135
	v_lshl_add_u32 v183, v137, 7, v161
	v_ashrrev_i32_e32 v252, 4, v134
	v_med3_i32 v136, v252, 0, s14
	v_lshl_add_u32 v136, v136, 9, v183
	global_load_dwordx4 v[0:3], v136, s[20:21]
	global_load_dwordx4 v[4:7], v136, s[20:21] offset:64
	v_add_u32_e32 v135, 16, v252
	v_med3_i32 v135, v135, 0, s14
	v_lshl_add_u32 v135, v135, 9, v183
	global_load_dwordx4 v[8:11], v135, s[20:21]
	global_load_dwordx4 v[12:15], v135, s[20:21] offset:64
	v_add_u32_e32 v136, 32, v252
	v_med3_i32 v136, v136, 0, s14
	v_lshl_add_u32 v136, v136, 9, v183
	global_load_dwordx4 v[16:19], v136, s[20:21]
	global_load_dwordx4 v[20:23], v136, s[20:21] offset:64
	v_add_u32_e32 v135, 48, v252
	v_med3_i32 v135, v135, 0, s14
	v_lshl_add_u32 v135, v135, 9, v183
	global_load_dwordx4 v[24:27], v135, s[20:21]
	global_load_dwordx4 v[28:31], v135, s[20:21] offset:64
	v_add_u32_e32 v136, 64, v252
	v_med3_i32 v136, v136, 0, s14
	v_lshl_add_u32 v136, v136, 9, v183
	global_load_dwordx4 v[32:35], v136, s[20:21]
	global_load_dwordx4 v[36:39], v136, s[20:21] offset:64
	v_add_u32_e32 v135, 0x50, v252
	v_med3_i32 v135, v135, 0, s14
	v_lshl_add_u32 v135, v135, 9, v183
	global_load_dwordx4 v[40:43], v135, s[20:21]
	global_load_dwordx4 v[44:47], v135, s[20:21] offset:64
	ds_bpermute_b32 v142, v167, v132
	s_waitcnt lgkmcnt(0)
	v_add_f32_e32 v132, v132, v142
	ds_bpermute_b32 v142, v168, v132
	s_waitcnt lgkmcnt(0)
	v_add_f32_e32 v132, v132, v142
	ds_bpermute_b32 v142, v167, v133
	s_waitcnt lgkmcnt(0)
	v_add_f32_e32 v133, v133, v142
	ds_bpermute_b32 v142, v168, v133
	s_waitcnt lgkmcnt(0)
	v_add_f32_e32 v133, v133, v142
	s_waitcnt vmcnt(14)
	ds_write_b128 v165, v[64:67]
	ds_write_b128 v165, v[68:71] offset:1152
	ds_write_b128 v165, v[72:75] offset:2304
	ds_write_b128 v165, v[76:79] offset:3456
	s_waitcnt lgkmcnt(0)
	ds_read_b64_tr_b16 v[236:237], v166
	ds_read_b64_tr_b16 v[238:239], v166 offset:2304
	ds_read_b64_tr_b16 v[240:241], v166 offset:32
	ds_read_b64_tr_b16 v[242:243], v166 offset:2336
	ds_read_b64_tr_b16 v[244:245], v166 offset:64
	ds_read_b64_tr_b16 v[246:247], v166 offset:2368
	ds_read_b64_tr_b16 v[248:249], v166 offset:96
	ds_read_b64_tr_b16 v[250:251], v166 offset:2400
	s_waitcnt lgkmcnt(0)
	s_add_i32 s2, s40, 32
	v_add_u32_e32 v138, s2, v164
	v_lshlrev_b32_e32 v138, 2, v138
	v_add_u32_e32 v138, s41, v138
	v_and_b32_e32 v139, 3, v138
	v_lshlrev_b32_e32 v139, s39, v139
	v_bfe_u32 v140, v138, 2, 2
	v_add_u32_e32 v139, v139, v140
	v_lshl_add_u32 v139, v139, 7, v162
	v_ashrrev_i32_e32 v138, 4, v138
	v_med3_i32 v138, v138, 0, s38
	v_lshl_add_u32 v138, v138, 9, v139
	global_load_dwordx4 v[64:67], v138, s[26:27]
	s_add_i32 s2, s40, 40
	v_add_u32_e32 v138, s2, v164
	v_lshlrev_b32_e32 v138, 2, v138
	v_add_u32_e32 v138, s41, v138
	v_and_b32_e32 v139, 3, v138
	v_lshlrev_b32_e32 v139, s39, v139
	v_bfe_u32 v140, v138, 2, 2
	v_add_u32_e32 v139, v139, v140
	v_lshl_add_u32 v139, v139, 7, v162
	v_ashrrev_i32_e32 v138, 4, v138
	v_med3_i32 v138, v138, 0, s38
	v_lshl_add_u32 v138, v138, 9, v139
	global_load_dwordx4 v[68:71], v138, s[26:27]
	s_add_i32 s2, s40, 48
	v_add_u32_e32 v138, s2, v164
	v_lshlrev_b32_e32 v138, 2, v138
	v_add_u32_e32 v138, s41, v138
	v_and_b32_e32 v139, 3, v138
	v_lshlrev_b32_e32 v139, s39, v139
	v_bfe_u32 v140, v138, 2, 2
	v_add_u32_e32 v139, v139, v140
	v_lshl_add_u32 v139, v139, 7, v162
	v_ashrrev_i32_e32 v138, 4, v138
	v_med3_i32 v138, v138, 0, s38
	v_lshl_add_u32 v138, v138, 9, v139
	global_load_dwordx4 v[72:75], v138, s[26:27]
	s_add_i32 s2, s40, 56
	v_add_u32_e32 v138, s2, v164
	v_lshlrev_b32_e32 v138, 2, v138
	v_add_u32_e32 v138, s41, v138
	v_and_b32_e32 v139, 3, v138
	v_lshlrev_b32_e32 v139, s39, v139
	v_bfe_u32 v140, v138, 2, 2
	v_add_u32_e32 v139, v139, v140
	v_lshl_add_u32 v139, v139, 7, v162
	v_ashrrev_i32_e32 v138, 4, v138
	v_med3_i32 v138, v138, 0, s38
	v_lshl_add_u32 v138, v138, 9, v139
	global_load_dwordx4 v[76:79], v138, s[26:27]
	ds_write_b128 v165, v[80:83]
	ds_write_b128 v165, v[84:87] offset:1152
	ds_write_b128 v165, v[88:91] offset:2304
	ds_write_b128 v165, v[92:95] offset:3456
	v_mfma_f32_16x16x32_bf16 v[204:207], v[236:239], v[112:115], 0
	v_mfma_f32_16x16x32_bf16 v[208:211], v[240:243], v[112:115], 0
	v_mfma_f32_16x16x32_bf16 v[212:215], v[244:247], v[112:115], 0
	v_mfma_f32_16x16x32_bf16 v[216:219], v[248:251], v[112:115], 0
	v_mfma_f32_16x16x32_bf16 v[220:223], v[236:239], v[184:187], 0
	v_mfma_f32_16x16x32_bf16 v[224:227], v[240:243], v[184:187], 0
	v_mfma_f32_16x16x32_bf16 v[228:231], v[244:247], v[184:187], 0
	v_mfma_f32_16x16x32_bf16 v[232:235], v[248:251], v[184:187], 0
	s_waitcnt lgkmcnt(0)
	ds_read_b64_tr_b16 v[236:237], v166
	ds_read_b64_tr_b16 v[238:239], v166 offset:2304
	ds_read_b64_tr_b16 v[240:241], v166 offset:32
	ds_read_b64_tr_b16 v[242:243], v166 offset:2336
	ds_read_b64_tr_b16 v[244:245], v166 offset:64
	ds_read_b64_tr_b16 v[246:247], v166 offset:2368
	ds_read_b64_tr_b16 v[248:249], v166 offset:96
	ds_read_b64_tr_b16 v[250:251], v166 offset:2400
	s_waitcnt lgkmcnt(0)
	s_add_i32 s2, s40, 64
	v_add_u32_e32 v138, s2, v164
	v_lshlrev_b32_e32 v138, 2, v138
	v_add_u32_e32 v138, s41, v138
	v_and_b32_e32 v139, 3, v138
	v_lshlrev_b32_e32 v139, s39, v139
	v_bfe_u32 v140, v138, 2, 2
	v_add_u32_e32 v139, v139, v140
	v_lshl_add_u32 v139, v139, 7, v162
	v_ashrrev_i32_e32 v138, 4, v138
	v_med3_i32 v138, v138, 0, s38
	v_lshl_add_u32 v138, v138, 9, v139
	global_load_dwordx4 v[80:83], v138, s[26:27]
	s_add_i32 s2, s40, 72
	v_add_u32_e32 v138, s2, v164
	v_lshlrev_b32_e32 v138, 2, v138
	v_add_u32_e32 v138, s41, v138
	v_and_b32_e32 v139, 3, v138
	v_lshlrev_b32_e32 v139, s39, v139
	v_bfe_u32 v140, v138, 2, 2
	v_add_u32_e32 v139, v139, v140
	v_lshl_add_u32 v139, v139, 7, v162
	v_ashrrev_i32_e32 v138, 4, v138
	v_med3_i32 v138, v138, 0, s38
	v_lshl_add_u32 v138, v138, 9, v139
	global_load_dwordx4 v[84:87], v138, s[26:27]
	s_add_i32 s2, s40, 80
	v_add_u32_e32 v138, s2, v164
	v_lshlrev_b32_e32 v138, 2, v138
	v_add_u32_e32 v138, s41, v138
	v_and_b32_e32 v139, 3, v138
	v_lshlrev_b32_e32 v139, s39, v139
	v_bfe_u32 v140, v138, 2, 2
	v_add_u32_e32 v139, v139, v140
	v_lshl_add_u32 v139, v139, 7, v162
	v_ashrrev_i32_e32 v138, 4, v138
	v_med3_i32 v138, v138, 0, s38
	v_lshl_add_u32 v138, v138, 9, v139
	global_load_dwordx4 v[88:91], v138, s[26:27]
	s_add_i32 s2, s40, 88
	v_add_u32_e32 v138, s2, v164
	v_lshlrev_b32_e32 v138, 2, v138
	v_add_u32_e32 v138, s41, v138
	v_and_b32_e32 v139, 3, v138
	v_lshlrev_b32_e32 v139, s39, v139
	v_bfe_u32 v140, v138, 2, 2
	v_add_u32_e32 v139, v139, v140
	v_lshl_add_u32 v139, v139, 7, v162
	v_ashrrev_i32_e32 v138, 4, v138
	v_med3_i32 v138, v138, 0, s38
	v_lshl_add_u32 v138, v138, 9, v139
	global_load_dwordx4 v[92:95], v138, s[26:27]
	ds_write_b128 v165, v[96:99]
	ds_write_b128 v165, v[100:103] offset:1152
	ds_write_b128 v165, v[104:107] offset:2304
	ds_write_b128 v165, v[108:111] offset:3456
	v_mfma_f32_16x16x32_bf16 v[204:207], v[236:239], v[116:119], v[204:207]
	v_mfma_f32_16x16x32_bf16 v[208:211], v[240:243], v[116:119], v[208:211]
	v_mfma_f32_16x16x32_bf16 v[212:215], v[244:247], v[116:119], v[212:215]
	v_mfma_f32_16x16x32_bf16 v[216:219], v[248:251], v[116:119], v[216:219]
	v_mfma_f32_16x16x32_bf16 v[220:223], v[236:239], v[188:191], v[220:223]
	v_mfma_f32_16x16x32_bf16 v[224:227], v[240:243], v[188:191], v[224:227]
	v_mfma_f32_16x16x32_bf16 v[228:231], v[244:247], v[188:191], v[228:231]
	v_mfma_f32_16x16x32_bf16 v[232:235], v[248:251], v[188:191], v[232:235]
	s_waitcnt lgkmcnt(0)
	ds_read_b64_tr_b16 v[236:237], v166
	ds_read_b64_tr_b16 v[238:239], v166 offset:2304
	ds_read_b64_tr_b16 v[240:241], v166 offset:32
	ds_read_b64_tr_b16 v[242:243], v166 offset:2336
	ds_read_b64_tr_b16 v[244:245], v166 offset:64
	ds_read_b64_tr_b16 v[246:247], v166 offset:2368
	ds_read_b64_tr_b16 v[248:249], v166 offset:96
	ds_read_b64_tr_b16 v[250:251], v166 offset:2400
	s_waitcnt lgkmcnt(0)
	s_waitcnt vmcnt(4)
	ds_write_b128 v165, v[64:67]
	ds_write_b128 v165, v[68:71] offset:1152
	ds_write_b128 v165, v[72:75] offset:2304
	ds_write_b128 v165, v[76:79] offset:3456
	v_mfma_f32_16x16x32_bf16 v[204:207], v[236:239], v[120:123], v[204:207]
	v_mfma_f32_16x16x32_bf16 v[208:211], v[240:243], v[120:123], v[208:211]
	v_mfma_f32_16x16x32_bf16 v[212:215], v[244:247], v[120:123], v[212:215]
	v_mfma_f32_16x16x32_bf16 v[216:219], v[248:251], v[120:123], v[216:219]
	v_mfma_f32_16x16x32_bf16 v[220:223], v[236:239], v[192:195], v[220:223]
	v_mfma_f32_16x16x32_bf16 v[224:227], v[240:243], v[192:195], v[224:227]
	v_mfma_f32_16x16x32_bf16 v[228:231], v[244:247], v[192:195], v[228:231]
	v_mfma_f32_16x16x32_bf16 v[232:235], v[248:251], v[192:195], v[232:235]
	s_waitcnt lgkmcnt(0)
	ds_read_b64_tr_b16 v[236:237], v166
	ds_read_b64_tr_b16 v[238:239], v166 offset:2304
	ds_read_b64_tr_b16 v[240:241], v166 offset:32
	ds_read_b64_tr_b16 v[242:243], v166 offset:2336
	ds_read_b64_tr_b16 v[244:245], v166 offset:64
	ds_read_b64_tr_b16 v[246:247], v166 offset:2368
	ds_read_b64_tr_b16 v[248:249], v166 offset:96
	ds_read_b64_tr_b16 v[250:251], v166 offset:2400
	s_waitcnt lgkmcnt(0)
	s_waitcnt vmcnt(0)
	ds_write_b128 v165, v[80:83]
	ds_write_b128 v165, v[84:87] offset:1152
	ds_write_b128 v165, v[88:91] offset:2304
	ds_write_b128 v165, v[92:95] offset:3456
	v_mfma_f32_16x16x32_bf16 v[204:207], v[236:239], v[124:127], v[204:207]
	v_mfma_f32_16x16x32_bf16 v[208:211], v[240:243], v[124:127], v[208:211]
	v_mfma_f32_16x16x32_bf16 v[212:215], v[244:247], v[124:127], v[212:215]
	v_mfma_f32_16x16x32_bf16 v[216:219], v[248:251], v[124:127], v[216:219]
	v_mfma_f32_16x16x32_bf16 v[220:223], v[236:239], v[196:199], v[220:223]
	v_mfma_f32_16x16x32_bf16 v[224:227], v[240:243], v[196:199], v[224:227]
	v_mfma_f32_16x16x32_bf16 v[228:231], v[244:247], v[196:199], v[228:231]
	v_mfma_f32_16x16x32_bf16 v[232:235], v[248:251], v[196:199], v[232:235]
	s_waitcnt lgkmcnt(0)
	ds_read_b64_tr_b16 v[236:237], v166
	ds_read_b64_tr_b16 v[238:239], v166 offset:2304
	ds_read_b64_tr_b16 v[240:241], v166 offset:32
	ds_read_b64_tr_b16 v[242:243], v166 offset:2336
	ds_read_b64_tr_b16 v[244:245], v166 offset:64
	ds_read_b64_tr_b16 v[246:247], v166 offset:2368
	ds_read_b64_tr_b16 v[248:249], v166 offset:96
	ds_read_b64_tr_b16 v[250:251], v166 offset:2400
	s_waitcnt lgkmcnt(0)
	v_mfma_f32_16x16x32_bf16 v[204:207], v[236:239], v[128:131], v[204:207]
	v_mfma_f32_16x16x32_bf16 v[208:211], v[240:243], v[128:131], v[208:211]
	v_mfma_f32_16x16x32_bf16 v[212:215], v[244:247], v[128:131], v[212:215]
	v_mfma_f32_16x16x32_bf16 v[216:219], v[248:251], v[128:131], v[216:219]
	v_mfma_f32_16x16x32_bf16 v[220:223], v[236:239], v[200:203], v[220:223]
	v_mfma_f32_16x16x32_bf16 v[224:227], v[240:243], v[200:203], v[224:227]
	v_mfma_f32_16x16x32_bf16 v[228:231], v[244:247], v[200:203], v[228:231]
	v_mfma_f32_16x16x32_bf16 v[232:235], v[248:251], v[200:203], v[232:235]
	s_add_i32 s2, s42, -64
	v_add_u32_e32 v138, s2, v164
	v_lshlrev_b32_e32 v138, 4, v138
	v_add_u32_e32 v138, s43, v138
	v_and_b32_e32 v139, 3, v138
	v_lshlrev_b32_e32 v139, s13, v139
	v_bfe_u32 v140, v138, 2, 2
	v_add_u32_e32 v139, v139, v140
	v_lshl_add_u32 v139, v139, 7, v162
	v_ashrrev_i32_e32 v138, 4, v138
	v_med3_i32 v138, v138, 0, s14
	v_lshl_add_u32 v138, v138, 9, v139
	global_load_dwordx4 v[64:67], v138, s[22:23]
	s_add_i32 s2, s42, -56
	v_add_u32_e32 v138, s2, v164
	v_lshlrev_b32_e32 v138, 4, v138
	v_add_u32_e32 v138, s43, v138
	v_and_b32_e32 v139, 3, v138
	v_lshlrev_b32_e32 v139, s13, v139
	v_bfe_u32 v140, v138, 2, 2
	v_add_u32_e32 v139, v139, v140
	v_lshl_add_u32 v139, v139, 7, v162
	v_ashrrev_i32_e32 v138, 4, v138
	v_med3_i32 v138, v138, 0, s14
	v_lshl_add_u32 v138, v138, 9, v139
	global_load_dwordx4 v[68:71], v138, s[22:23]
	s_add_i32 s2, s42, -48
	v_add_u32_e32 v138, s2, v164
	v_lshlrev_b32_e32 v138, 4, v138
	v_add_u32_e32 v138, s43, v138
	v_and_b32_e32 v139, 3, v138
	v_lshlrev_b32_e32 v139, s13, v139
	v_bfe_u32 v140, v138, 2, 2
	v_add_u32_e32 v139, v139, v140
	v_lshl_add_u32 v139, v139, 7, v162
	v_ashrrev_i32_e32 v138, 4, v138
	v_med3_i32 v138, v138, 0, s14
	v_lshl_add_u32 v138, v138, 9, v139
	global_load_dwordx4 v[72:75], v138, s[22:23]
	s_add_i32 s2, s42, -40
	v_add_u32_e32 v138, s2, v164
	v_lshlrev_b32_e32 v138, 4, v138
	v_add_u32_e32 v138, s43, v138
	v_and_b32_e32 v139, 3, v138
	v_lshlrev_b32_e32 v139, s13, v139
	v_bfe_u32 v140, v138, 2, 2
	v_add_u32_e32 v139, v139, v140
	v_lshl_add_u32 v139, v139, 7, v162
	v_ashrrev_i32_e32 v138, 4, v138
	v_med3_i32 v138, v138, 0, s14
	v_lshl_add_u32 v138, v138, 9, v139
	global_load_dwordx4 v[76:79], v138, s[22:23]
	s_add_i32 s2, s42, -32
	v_add_u32_e32 v138, s2, v164
	v_lshlrev_b32_e32 v138, 4, v138
	v_add_u32_e32 v138, s43, v138
	v_and_b32_e32 v139, 3, v138
	v_lshlrev_b32_e32 v139, s13, v139
	v_bfe_u32 v140, v138, 2, 2
	v_add_u32_e32 v139, v139, v140
	v_lshl_add_u32 v139, v139, 7, v162
	v_ashrrev_i32_e32 v138, 4, v138
	v_med3_i32 v138, v138, 0, s14
	v_lshl_add_u32 v138, v138, 9, v139
	global_load_dwordx4 v[80:83], v138, s[22:23]
	s_add_i32 s2, s42, -24
	v_add_u32_e32 v138, s2, v164
	v_lshlrev_b32_e32 v138, 4, v138
	v_add_u32_e32 v138, s43, v138
	v_and_b32_e32 v139, 3, v138
	v_lshlrev_b32_e32 v139, s13, v139
	v_bfe_u32 v140, v138, 2, 2
	v_add_u32_e32 v139, v139, v140
	v_lshl_add_u32 v139, v139, 7, v162
	v_ashrrev_i32_e32 v138, 4, v138
	v_med3_i32 v138, v138, 0, s14
	v_lshl_add_u32 v138, v138, 9, v139
	global_load_dwordx4 v[84:87], v138, s[22:23]
	s_add_i32 s2, s42, -16
	v_add_u32_e32 v138, s2, v164
	v_lshlrev_b32_e32 v138, 4, v138
	v_add_u32_e32 v138, s43, v138
	v_and_b32_e32 v139, 3, v138
	v_lshlrev_b32_e32 v139, s13, v139
	v_bfe_u32 v140, v138, 2, 2
	v_add_u32_e32 v139, v139, v140
	v_lshl_add_u32 v139, v139, 7, v162
	v_ashrrev_i32_e32 v138, 4, v138
	v_med3_i32 v138, v138, 0, s14
	v_lshl_add_u32 v138, v138, 9, v139
	global_load_dwordx4 v[88:91], v138, s[22:23]
	s_add_i32 s2, s42, -8
	v_add_u32_e32 v138, s2, v164
	v_lshlrev_b32_e32 v138, 4, v138
	v_add_u32_e32 v138, s43, v138
	v_and_b32_e32 v139, 3, v138
	v_lshlrev_b32_e32 v139, s13, v139
	v_bfe_u32 v140, v138, 2, 2
	v_add_u32_e32 v139, v139, v140
	v_lshl_add_u32 v139, v139, 7, v162
	v_ashrrev_i32_e32 v138, 4, v138
	v_med3_i32 v138, v138, 0, s14
	v_lshl_add_u32 v138, v138, 9, v139
	global_load_dwordx4 v[92:95], v138, s[22:23]
	s_add_i32 s2, s42, 0
	v_add_u32_e32 v138, s2, v164
	v_lshlrev_b32_e32 v138, 4, v138
	v_add_u32_e32 v138, s43, v138
	v_and_b32_e32 v139, 3, v138
	v_lshlrev_b32_e32 v139, s13, v139
	v_bfe_u32 v140, v138, 2, 2
	v_add_u32_e32 v139, v139, v140
	v_lshl_add_u32 v139, v139, 7, v162
	v_ashrrev_i32_e32 v138, 4, v138
	v_med3_i32 v138, v138, 0, s14
	v_lshl_add_u32 v138, v138, 9, v139
	global_load_dwordx4 v[96:99], v138, s[22:23]
	s_add_i32 s2, s42, 8
	v_add_u32_e32 v138, s2, v164
	v_lshlrev_b32_e32 v138, 4, v138
	v_add_u32_e32 v138, s43, v138
	v_and_b32_e32 v139, 3, v138
	v_lshlrev_b32_e32 v139, s13, v139
	v_bfe_u32 v140, v138, 2, 2
	v_add_u32_e32 v139, v139, v140
	v_lshl_add_u32 v139, v139, 7, v162
	v_ashrrev_i32_e32 v138, 4, v138
	v_med3_i32 v138, v138, 0, s14
	v_lshl_add_u32 v138, v138, 9, v139
	global_load_dwordx4 v[100:103], v138, s[22:23]
	s_add_i32 s2, s42, 16
	v_add_u32_e32 v138, s2, v164
	v_lshlrev_b32_e32 v138, 4, v138
	v_add_u32_e32 v138, s43, v138
	v_and_b32_e32 v139, 3, v138
	v_lshlrev_b32_e32 v139, s13, v139
	v_bfe_u32 v140, v138, 2, 2
	v_add_u32_e32 v139, v139, v140
	v_lshl_add_u32 v139, v139, 7, v162
	v_ashrrev_i32_e32 v138, 4, v138
	v_med3_i32 v138, v138, 0, s14
	v_lshl_add_u32 v138, v138, 9, v139
	global_load_dwordx4 v[104:107], v138, s[22:23]
	s_add_i32 s2, s42, 24
	v_add_u32_e32 v138, s2, v164
	v_lshlrev_b32_e32 v138, 4, v138
	v_add_u32_e32 v138, s43, v138
	v_and_b32_e32 v139, 3, v138
	v_lshlrev_b32_e32 v139, s13, v139
	v_bfe_u32 v140, v138, 2, 2
	v_add_u32_e32 v139, v139, v140
	v_lshl_add_u32 v139, v139, 7, v162
	v_ashrrev_i32_e32 v138, 4, v138
	v_med3_i32 v138, v138, 0, s14
	v_lshl_add_u32 v138, v138, 9, v139
	global_load_dwordx4 v[108:111], v138, s[22:23]
	ds_read_b128 v[236:239], v173 offset:0
	ds_read_b128 v[240:243], v173 offset:64
	ds_read_b128 v[244:247], v173 offset:128
	ds_read_b128 v[248:251], v173 offset:192
	ds_read_b32 v142, v174 offset:0
	s_waitcnt lgkmcnt(0)
	v_add_f32_e32 v204, v236, v204
	v_add_f32_e32 v205, v237, v205
	v_add_f32_e32 v206, v238, v206
	v_add_f32_e32 v207, v239, v207
	v_add_f32_e32 v208, v240, v208
	v_add_f32_e32 v209, v241, v209
	v_add_f32_e32 v210, v242, v210
	v_add_f32_e32 v211, v243, v211
	v_add_f32_e32 v212, v244, v212
	v_add_f32_e32 v213, v245, v213
	v_add_f32_e32 v214, v246, v214
	v_add_f32_e32 v215, v247, v215
	v_add_f32_e32 v216, v248, v216
	v_add_f32_e32 v217, v249, v217
	v_add_f32_e32 v218, v250, v218
	v_add_f32_e32 v219, v251, v219
	v_add_f32_e32 v132, v142, v132
	ds_write_b128 v173, v[204:207] offset:0
	ds_write_b128 v173, v[208:211] offset:64
	ds_write_b128 v173, v[212:215] offset:128
	ds_write_b128 v173, v[216:219] offset:192
	ds_write_b32 v174, v132 offset:0
	ds_read_b128 v[236:239], v173 offset:18496
	ds_read_b128 v[240:243], v173 offset:18560
	ds_read_b128 v[244:247], v173 offset:18624
	ds_read_b128 v[248:251], v173 offset:18688
	ds_read_b32 v142, v174 offset:256
	s_waitcnt lgkmcnt(0)
	v_add_f32_e32 v220, v236, v220
	v_add_f32_e32 v221, v237, v221
	v_add_f32_e32 v222, v238, v222
	v_add_f32_e32 v223, v239, v223
	v_add_f32_e32 v224, v240, v224
	v_add_f32_e32 v225, v241, v225
	v_add_f32_e32 v226, v242, v226
	v_add_f32_e32 v227, v243, v227
	v_add_f32_e32 v228, v244, v228
	v_add_f32_e32 v229, v245, v229
	v_add_f32_e32 v230, v246, v230
	v_add_f32_e32 v231, v247, v231
	v_add_f32_e32 v232, v248, v232
	v_add_f32_e32 v233, v249, v233
	v_add_f32_e32 v234, v250, v234
	v_add_f32_e32 v235, v251, v235
	v_add_f32_e32 v133, v142, v133
	ds_write_b128 v173, v[220:223] offset:18496
	ds_write_b128 v173, v[224:227] offset:18560
	ds_write_b128 v173, v[228:231] offset:18624
	ds_write_b128 v173, v[232:235] offset:18688
	ds_write_b32 v174, v133 offset:256
	s_waitcnt lgkmcnt(0)
	s_barrier
	s_mov_b32 s40, s42
	s_mov_b32 s41, s43
	v_mov_b32_e32 v173, v176
	v_mov_b32_e32 v174, v177
	v_mov_b32_e32 v175, v178
	v_mov_b32_e32 v179, v183
	v_mov_b32_e32 v182, v252
	s_lshr_b32 s44, s33, 4
	s_lshr_b32 s42, s15, 4
	s_add_i32 s43, s0, 8
	s_waitcnt vmcnt(12)
	v_mov_b32_e32 v132, 0
	v_mfma_f32_16x16x32_bf16 v[236:239], v[0:3], v[48:51], 0
	v_mfma_f32_16x16x32_bf16 v[236:239], v[4:7], v[52:55], v[236:239]
	v_mfma_f32_16x16x32_bf16 v[240:243], v[8:11], v[48:51], 0
	v_mfma_f32_16x16x32_bf16 v[240:243], v[12:15], v[52:55], v[240:243]
	s_nop 7
	v_min_f32_e32 v152, 0x42a00000, v236
	v_min_f32_e32 v153, 0x42a00000, v237
	v_min_f32_e32 v154, 0x42a00000, v238
	v_min_f32_e32 v155, 0x42a00000, v239
	v_mfma_f32_16x16x32_bf16 v[236:239], v[16:19], v[48:51], 0
	v_mfma_f32_16x16x32_bf16 v[236:239], v[20:23], v[52:55], v[236:239]
	v_add_u32_e32 v136, 0x60, v182
	v_med3_i32 v136, v136, 0, s38
	v_lshl_add_u32 v136, v136, 9, v179
	global_load_dwordx4 v[0:3], v136, s[24:25]
	global_load_dwordx4 v[4:7], v136, s[24:25] offset:64
	v_mul_f32_e32 v152, 0x3fb8aa3b, v152
	v_mul_f32_e32 v153, 0x3fb8aa3b, v153
	v_mul_f32_e32 v154, 0x3fb8aa3b, v154
	v_mul_f32_e32 v155, 0x3fb8aa3b, v155
	v_exp_f32_e32 v152, v152
	v_exp_f32_e32 v153, v153
	v_exp_f32_e32 v154, v154
	v_exp_f32_e32 v155, v155
	v_add_u32_e32 v138, 0, v175
	v_add_u32_e32 v139, 1, v175
	v_add_u32_e32 v140, 2, v175
	v_add_u32_e32 v141, 3, v175
	v_cmp_gt_u32_e64 s[70:71], s44, v138
	v_cmp_gt_u32_e64 s[72:73], s44, v139
	v_cmp_gt_u32_e64 s[74:75], s44, v140
	v_cmp_gt_u32_e64 s[76:77], s44, v141
	v_cndmask_b32_e64 v152, 0, v152, s[54:55]
	v_cndmask_b32_e64 v153, 0, v153, s[56:57]
	v_cndmask_b32_e64 v154, 0, v154, s[58:59]
	v_cndmask_b32_e64 v155, 0, v155, s[60:61]
	v_cndmask_b32_e64 v152, 0, v152, s[70:71]
	v_cndmask_b32_e64 v153, 0, v153, s[72:73]
	v_cndmask_b32_e64 v154, 0, v154, s[74:75]
	v_cndmask_b32_e64 v155, 0, v155, s[76:77]
	v_add_f32_e32 v132, v132, v152
	v_add_f32_e32 v132, v132, v153
	v_add_f32_e32 v132, v132, v154
	v_add_f32_e32 v132, v132, v155
	v_cvt_pk_bf16_f32 v112, v152, v153
	v_cvt_pk_bf16_f32 v113, v154, v155
	v_min_f32_e32 v152, 0x42a00000, v240
	v_min_f32_e32 v153, 0x42a00000, v241
	v_min_f32_e32 v154, 0x42a00000, v242
	v_min_f32_e32 v155, 0x42a00000, v243
	v_mfma_f32_16x16x32_bf16 v[240:243], v[24:27], v[48:51], 0
	v_mfma_f32_16x16x32_bf16 v[240:243], v[28:31], v[52:55], v[240:243]
	v_add_u32_e32 v135, 0x70, v182
	v_med3_i32 v135, v135, 0, s38
	v_lshl_add_u32 v135, v135, 9, v179
	global_load_dwordx4 v[8:11], v135, s[24:25]
	global_load_dwordx4 v[12:15], v135, s[24:25] offset:64
	v_mul_f32_e32 v152, 0x3fb8aa3b, v152
	v_mul_f32_e32 v153, 0x3fb8aa3b, v153
	v_mul_f32_e32 v154, 0x3fb8aa3b, v154
	v_mul_f32_e32 v155, 0x3fb8aa3b, v155
	v_exp_f32_e32 v152, v152
	v_exp_f32_e32 v153, v153
	v_exp_f32_e32 v154, v154
	v_exp_f32_e32 v155, v155
	v_add_u32_e32 v138, 16, v175
	v_add_u32_e32 v139, 17, v175
	v_add_u32_e32 v140, 18, v175
	v_add_u32_e32 v141, 19, v175
	v_cmp_gt_u32_e64 s[70:71], s44, v138
	v_cmp_gt_u32_e64 s[72:73], s44, v139
	v_cmp_gt_u32_e64 s[74:75], s44, v140
	v_cmp_gt_u32_e64 s[76:77], s44, v141
	v_cndmask_b32_e64 v152, 0, v152, s[70:71]
	v_cndmask_b32_e64 v153, 0, v153, s[72:73]
	v_cndmask_b32_e64 v154, 0, v154, s[74:75]
	v_cndmask_b32_e64 v155, 0, v155, s[76:77]
	v_add_f32_e32 v132, v132, v152
	v_add_f32_e32 v132, v132, v153
	v_add_f32_e32 v132, v132, v154
	v_add_f32_e32 v132, v132, v155
	v_cvt_pk_bf16_f32 v114, v152, v153
	v_cvt_pk_bf16_f32 v115, v154, v155
	v_min_f32_e32 v152, 0x42a00000, v236
	v_min_f32_e32 v153, 0x42a00000, v237
	v_min_f32_e32 v154, 0x42a00000, v238
	v_min_f32_e32 v155, 0x42a00000, v239
	v_mfma_f32_16x16x32_bf16 v[236:239], v[32:35], v[48:51], 0
	v_mfma_f32_16x16x32_bf16 v[236:239], v[36:39], v[52:55], v[236:239]
	v_add_u32_e32 v136, 0x80, v182
	v_med3_i32 v136, v136, 0, s38
	v_lshl_add_u32 v136, v136, 9, v179
	global_load_dwordx4 v[16:19], v136, s[24:25]
	global_load_dwordx4 v[20:23], v136, s[24:25] offset:64
	v_mul_f32_e32 v152, 0x3fb8aa3b, v152
	v_mul_f32_e32 v153, 0x3fb8aa3b, v153
	v_mul_f32_e32 v154, 0x3fb8aa3b, v154
	v_mul_f32_e32 v155, 0x3fb8aa3b, v155
	v_exp_f32_e32 v152, v152
	v_exp_f32_e32 v153, v153
	v_exp_f32_e32 v154, v154
	v_exp_f32_e32 v155, v155
	v_add_u32_e32 v138, 32, v175
	v_add_u32_e32 v139, 33, v175
	v_add_u32_e32 v140, 34, v175
	v_add_u32_e32 v141, 35, v175
	v_cmp_gt_u32_e64 s[70:71], s44, v138
	v_cmp_gt_u32_e64 s[72:73], s44, v139
	v_cmp_gt_u32_e64 s[74:75], s44, v140
	v_cmp_gt_u32_e64 s[76:77], s44, v141
	v_cndmask_b32_e64 v152, 0, v152, s[70:71]
	v_cndmask_b32_e64 v153, 0, v153, s[72:73]
	v_cndmask_b32_e64 v154, 0, v154, s[74:75]
	v_cndmask_b32_e64 v155, 0, v155, s[76:77]
	v_add_f32_e32 v132, v132, v152
	v_add_f32_e32 v132, v132, v153
	v_add_f32_e32 v132, v132, v154
	v_add_f32_e32 v132, v132, v155
	v_cvt_pk_bf16_f32 v116, v152, v153
	v_cvt_pk_bf16_f32 v117, v154, v155
	v_min_f32_e32 v152, 0x42a00000, v240
	v_min_f32_e32 v153, 0x42a00000, v241
	v_min_f32_e32 v154, 0x42a00000, v242
	v_min_f32_e32 v155, 0x42a00000, v243
	v_mfma_f32_16x16x32_bf16 v[240:243], v[40:43], v[48:51], 0
	v_mfma_f32_16x16x32_bf16 v[240:243], v[44:47], v[52:55], v[240:243]
	v_mul_f32_e32 v152, 0x3fb8aa3b, v152
	v_mul_f32_e32 v153, 0x3fb8aa3b, v153
	v_mul_f32_e32 v154, 0x3fb8aa3b, v154
	v_mul_f32_e32 v155, 0x3fb8aa3b, v155
	v_exp_f32_e32 v152, v152
	v_exp_f32_e32 v153, v153
	v_exp_f32_e32 v154, v154
	v_exp_f32_e32 v155, v155
	v_add_u32_e32 v138, 48, v175
	v_add_u32_e32 v139, 49, v175
	v_add_u32_e32 v140, 50, v175
	v_add_u32_e32 v141, 51, v175
	v_cmp_gt_u32_e64 s[70:71], s44, v138
	v_cmp_gt_u32_e64 s[72:73], s44, v139
	v_cmp_gt_u32_e64 s[74:75], s44, v140
	v_cmp_gt_u32_e64 s[76:77], s44, v141
	v_cndmask_b32_e64 v152, 0, v152, s[70:71]
	v_cndmask_b32_e64 v153, 0, v153, s[72:73]
	v_cndmask_b32_e64 v154, 0, v154, s[74:75]
	v_cndmask_b32_e64 v155, 0, v155, s[76:77]
	v_add_f32_e32 v132, v132, v152
	v_add_f32_e32 v132, v132, v153
	v_add_f32_e32 v132, v132, v154
	v_add_f32_e32 v132, v132, v155
	v_cvt_pk_bf16_f32 v118, v152, v153
	v_cvt_pk_bf16_f32 v119, v154, v155
	v_min_f32_e32 v152, 0x42a00000, v236
	v_min_f32_e32 v153, 0x42a00000, v237
	v_min_f32_e32 v154, 0x42a00000, v238
	v_min_f32_e32 v155, 0x42a00000, v239
	s_waitcnt vmcnt(4)
	v_mfma_f32_16x16x32_bf16 v[236:239], v[0:3], v[48:51], 0
	v_mfma_f32_16x16x32_bf16 v[236:239], v[4:7], v[52:55], v[236:239]
	v_mul_f32_e32 v152, 0x3fb8aa3b, v152
	v_mul_f32_e32 v153, 0x3fb8aa3b, v153
	v_mul_f32_e32 v154, 0x3fb8aa3b, v154
	v_mul_f32_e32 v155, 0x3fb8aa3b, v155
	v_exp_f32_e32 v152, v152
	v_exp_f32_e32 v153, v153
	v_exp_f32_e32 v154, v154
	v_exp_f32_e32 v155, v155
	v_add_u32_e32 v138, 64, v175
	v_add_u32_e32 v139, 0x41, v175
	v_add_u32_e32 v140, 0x42, v175
	v_add_u32_e32 v141, 0x43, v175
	v_cmp_gt_u32_e64 s[70:71], s44, v138
	v_cmp_gt_u32_e64 s[72:73], s44, v139
	v_cmp_gt_u32_e64 s[74:75], s44, v140
	v_cmp_gt_u32_e64 s[76:77], s44, v141
	v_cndmask_b32_e64 v152, 0, v152, s[70:71]
	v_cndmask_b32_e64 v153, 0, v153, s[72:73]
	v_cndmask_b32_e64 v154, 0, v154, s[74:75]
	v_cndmask_b32_e64 v155, 0, v155, s[76:77]
	v_add_f32_e32 v132, v132, v152
	v_add_f32_e32 v132, v132, v153
	v_add_f32_e32 v132, v132, v154
	v_add_f32_e32 v132, v132, v155
	v_cvt_pk_bf16_f32 v120, v152, v153
	v_cvt_pk_bf16_f32 v121, v154, v155
	v_min_f32_e32 v152, 0x42a00000, v240
	v_min_f32_e32 v153, 0x42a00000, v241
	v_min_f32_e32 v154, 0x42a00000, v242
	v_min_f32_e32 v155, 0x42a00000, v243
	s_waitcnt vmcnt(2)
	v_mfma_f32_16x16x32_bf16 v[240:243], v[8:11], v[48:51], 0
	v_mfma_f32_16x16x32_bf16 v[240:243], v[12:15], v[52:55], v[240:243]
	v_mul_f32_e32 v152, 0x3fb8aa3b, v152
	v_mul_f32_e32 v153, 0x3fb8aa3b, v153
	v_mul_f32_e32 v154, 0x3fb8aa3b, v154
	v_mul_f32_e32 v155, 0x3fb8aa3b, v155
	v_exp_f32_e32 v152, v152
	v_exp_f32_e32 v153, v153
	v_exp_f32_e32 v154, v154
	v_exp_f32_e32 v155, v155
	v_add_u32_e32 v138, 0x50, v175
	v_add_u32_e32 v139, 0x51, v175
	v_add_u32_e32 v140, 0x52, v175
	v_add_u32_e32 v141, 0x53, v175
	v_cmp_gt_u32_e64 s[70:71], s44, v138
	v_cmp_gt_u32_e64 s[72:73], s44, v139
	v_cmp_gt_u32_e64 s[74:75], s44, v140
	v_cmp_gt_u32_e64 s[76:77], s44, v141
	v_cndmask_b32_e64 v152, 0, v152, s[70:71]
	v_cndmask_b32_e64 v153, 0, v153, s[72:73]
	v_cndmask_b32_e64 v154, 0, v154, s[74:75]
	v_cndmask_b32_e64 v155, 0, v155, s[76:77]
	v_add_f32_e32 v132, v132, v152
	v_add_f32_e32 v132, v132, v153
	v_add_f32_e32 v132, v132, v154
	v_add_f32_e32 v132, v132, v155
	v_cvt_pk_bf16_f32 v122, v152, v153
	v_cvt_pk_bf16_f32 v123, v154, v155
	v_min_f32_e32 v152, 0x42a00000, v236
	v_min_f32_e32 v153, 0x42a00000, v237
	v_min_f32_e32 v154, 0x42a00000, v238
	v_min_f32_e32 v155, 0x42a00000, v239
	s_waitcnt vmcnt(0)
	v_mfma_f32_16x16x32_bf16 v[236:239], v[16:19], v[48:51], 0
	v_mfma_f32_16x16x32_bf16 v[236:239], v[20:23], v[52:55], v[236:239]
	v_mul_f32_e32 v152, 0x3fb8aa3b, v152
	v_mul_f32_e32 v153, 0x3fb8aa3b, v153
	v_mul_f32_e32 v154, 0x3fb8aa3b, v154
	v_mul_f32_e32 v155, 0x3fb8aa3b, v155
	v_exp_f32_e32 v152, v152
	v_exp_f32_e32 v153, v153
	v_exp_f32_e32 v154, v154
	v_exp_f32_e32 v155, v155
	v_add_u32_e32 v138, 0x60, v175
	v_add_u32_e32 v139, 0x61, v175
	v_add_u32_e32 v140, 0x62, v175
	v_add_u32_e32 v141, 0x63, v175
	v_cmp_gt_u32_e64 s[70:71], s44, v138
	v_cmp_gt_u32_e64 s[72:73], s44, v139
	v_cmp_gt_u32_e64 s[74:75], s44, v140
	v_cmp_gt_u32_e64 s[76:77], s44, v141
	v_cndmask_b32_e64 v152, 0, v152, s[70:71]
	v_cndmask_b32_e64 v153, 0, v153, s[72:73]
	v_cndmask_b32_e64 v154, 0, v154, s[74:75]
	v_cndmask_b32_e64 v155, 0, v155, s[76:77]
	v_add_f32_e32 v132, v132, v152
	v_add_f32_e32 v132, v132, v153
	v_add_f32_e32 v132, v132, v154
	v_add_f32_e32 v132, v132, v155
	v_cvt_pk_bf16_f32 v124, v152, v153
	v_cvt_pk_bf16_f32 v125, v154, v155
	v_min_f32_e32 v152, 0x42a00000, v240
	v_min_f32_e32 v153, 0x42a00000, v241
	v_min_f32_e32 v154, 0x42a00000, v242
	v_min_f32_e32 v155, 0x42a00000, v243
	v_mul_f32_e32 v152, 0x3fb8aa3b, v152
	v_mul_f32_e32 v153, 0x3fb8aa3b, v153
	v_mul_f32_e32 v154, 0x3fb8aa3b, v154
	v_mul_f32_e32 v155, 0x3fb8aa3b, v155
	v_exp_f32_e32 v152, v152
	v_exp_f32_e32 v153, v153
	v_exp_f32_e32 v154, v154
	v_exp_f32_e32 v155, v155
	v_add_u32_e32 v138, 0x70, v175
	v_add_u32_e32 v139, 0x71, v175
	v_add_u32_e32 v140, 0x72, v175
	v_add_u32_e32 v141, 0x73, v175
	v_cmp_gt_u32_e64 s[70:71], s44, v138
	v_cmp_gt_u32_e64 s[72:73], s44, v139
	v_cmp_gt_u32_e64 s[74:75], s44, v140
	v_cmp_gt_u32_e64 s[76:77], s44, v141
	v_cndmask_b32_e64 v152, 0, v152, s[70:71]
	v_cndmask_b32_e64 v153, 0, v153, s[72:73]
	v_cndmask_b32_e64 v154, 0, v154, s[74:75]
	v_cndmask_b32_e64 v155, 0, v155, s[76:77]
	v_add_f32_e32 v132, v132, v152
	v_add_f32_e32 v132, v132, v153
	v_add_f32_e32 v132, v132, v154
	v_add_f32_e32 v132, v132, v155
	v_cvt_pk_bf16_f32 v126, v152, v153
	v_cvt_pk_bf16_f32 v127, v154, v155
	v_min_f32_e32 v152, 0x42a00000, v236
	v_min_f32_e32 v153, 0x42a00000, v237
	v_min_f32_e32 v154, 0x42a00000, v238
	v_min_f32_e32 v155, 0x42a00000, v239
	v_mul_f32_e32 v152, 0x3fb8aa3b, v152
	v_mul_f32_e32 v153, 0x3fb8aa3b, v153
	v_mul_f32_e32 v154, 0x3fb8aa3b, v154
	v_mul_f32_e32 v155, 0x3fb8aa3b, v155
	v_exp_f32_e32 v152, v152
	v_exp_f32_e32 v153, v153
	v_exp_f32_e32 v154, v154
	v_exp_f32_e32 v155, v155
	v_add_u32_e32 v138, 0x80, v175
	v_add_u32_e32 v139, 0x81, v175
	v_add_u32_e32 v140, 0x82, v175
	v_add_u32_e32 v141, 0x83, v175
	v_cmp_gt_u32_e64 s[70:71], s44, v138
	v_cmp_gt_u32_e64 s[72:73], s44, v139
	v_cmp_gt_u32_e64 s[74:75], s44, v140
	v_cmp_gt_u32_e64 s[76:77], s44, v141
	v_cndmask_b32_e64 v152, 0, v152, s[62:63]
	v_cndmask_b32_e64 v153, 0, v153, s[64:65]
	v_cndmask_b32_e64 v154, 0, v154, s[66:67]
	v_cndmask_b32_e64 v155, 0, v155, s[68:69]
	v_cndmask_b32_e64 v152, 0, v152, s[70:71]
	v_cndmask_b32_e64 v153, 0, v153, s[72:73]
	v_cndmask_b32_e64 v154, 0, v154, s[74:75]
	v_cndmask_b32_e64 v155, 0, v155, s[76:77]
	v_add_f32_e32 v132, v132, v152
	v_add_f32_e32 v132, v132, v153
	v_add_f32_e32 v132, v132, v154
	v_add_f32_e32 v132, v132, v155
	v_cvt_pk_bf16_f32 v128, v152, v153
	v_cvt_pk_bf16_f32 v129, v154, v155
	v_add_u32_e32 v134, s42, v160
	v_lshlrev_b32_e32 v134, 4, v134
	v_add_u32_e32 v134, s43, v134
	v_subrev_u32_e32 v135, s15, v134
	v_lshrrev_b32_e32 v136, 4, v135
	v_add_u32_e32 v136, v136, v135
	v_mad_u32_u24 v176, v136, s79, v161
	v_lshl_add_u32 v177, v135, 2, s80
	s_sub_i32 s2, s42, 64
	v_add_u32_e32 v178, s2, v169
	v_and_b32_e32 v135, 3, v134
	v_lshlrev_b32_e32 v135, s13, v135
	v_lshrrev_b32_e32 v136, 2, v134
	v_add_u32_e32 v135, v135, v136
	v_lshl_add_u32 v135, v135, 7, v161
	global_load_dwordx4 v[48:51], v135, s[18:19]
	global_load_dwordx4 v[52:55], v135, s[18:19] offset:64
	v_subrev_u32_e32 v134, 0x400, v134
	v_and_b32_e32 v137, 3, v134
	v_lshlrev_b32_e32 v137, s13, v137
	v_bfe_u32 v135, v134, 2, 2
	v_add_u32_e32 v137, v137, v135
	v_lshl_add_u32 v183, v137, 7, v161
	v_ashrrev_i32_e32 v252, 4, v134
	v_med3_i32 v136, v252, 0, s14
	v_lshl_add_u32 v136, v136, 9, v183
	global_load_dwordx4 v[0:3], v136, s[20:21]
	global_load_dwordx4 v[4:7], v136, s[20:21] offset:64
	v_add_u32_e32 v135, 16, v252
	v_med3_i32 v135, v135, 0, s14
	v_lshl_add_u32 v135, v135, 9, v183
	global_load_dwordx4 v[8:11], v135, s[20:21]
	global_load_dwordx4 v[12:15], v135, s[20:21] offset:64
	v_add_u32_e32 v136, 32, v252
	v_med3_i32 v136, v136, 0, s14
	v_lshl_add_u32 v136, v136, 9, v183
	global_load_dwordx4 v[16:19], v136, s[20:21]
	global_load_dwordx4 v[20:23], v136, s[20:21] offset:64
	v_add_u32_e32 v135, 48, v252
	v_med3_i32 v135, v135, 0, s14
	v_lshl_add_u32 v135, v135, 9, v183
	global_load_dwordx4 v[24:27], v135, s[20:21]
	global_load_dwordx4 v[28:31], v135, s[20:21] offset:64
	v_add_u32_e32 v136, 64, v252
	v_med3_i32 v136, v136, 0, s14
	v_lshl_add_u32 v136, v136, 9, v183
	global_load_dwordx4 v[32:35], v136, s[20:21]
	global_load_dwordx4 v[36:39], v136, s[20:21] offset:64
	v_add_u32_e32 v135, 0x50, v252
	v_med3_i32 v135, v135, 0, s14
	v_lshl_add_u32 v135, v135, 9, v183
	global_load_dwordx4 v[40:43], v135, s[20:21]
	global_load_dwordx4 v[44:47], v135, s[20:21] offset:64
	ds_bpermute_b32 v142, v167, v132
	s_waitcnt lgkmcnt(0)
	v_add_f32_e32 v132, v132, v142
	ds_bpermute_b32 v142, v168, v132
	s_waitcnt lgkmcnt(0)
	v_add_f32_e32 v132, v132, v142
	s_waitcnt vmcnt(14)
	ds_write_b128 v165, v[64:67]
	ds_write_b128 v165, v[68:71] offset:1152
	ds_write_b128 v165, v[72:75] offset:2304
	ds_write_b128 v165, v[76:79] offset:3456
	s_waitcnt lgkmcnt(0)
	ds_read_b64_tr_b16 v[236:237], v166
	ds_read_b64_tr_b16 v[238:239], v166 offset:2304
	ds_read_b64_tr_b16 v[240:241], v166 offset:32
	ds_read_b64_tr_b16 v[242:243], v166 offset:2336
	ds_read_b64_tr_b16 v[244:245], v166 offset:64
	ds_read_b64_tr_b16 v[246:247], v166 offset:2368
	ds_read_b64_tr_b16 v[248:249], v166 offset:96
	ds_read_b64_tr_b16 v[250:251], v166 offset:2400
	s_waitcnt lgkmcnt(0)
	s_add_i32 s2, s40, 32
	v_add_u32_e32 v138, s2, v164
	v_lshlrev_b32_e32 v138, 4, v138
	v_add_u32_e32 v138, s41, v138
	v_and_b32_e32 v139, 3, v138
	v_lshlrev_b32_e32 v139, s39, v139
	v_bfe_u32 v140, v138, 2, 2
	v_add_u32_e32 v139, v139, v140
	v_lshl_add_u32 v139, v139, 7, v162
	v_ashrrev_i32_e32 v138, 4, v138
	v_med3_i32 v138, v138, 0, s38
	v_lshl_add_u32 v138, v138, 9, v139
	global_load_dwordx4 v[64:67], v138, s[26:27]
	s_add_i32 s2, s40, 40
	v_add_u32_e32 v138, s2, v164
	v_lshlrev_b32_e32 v138, 4, v138
	v_add_u32_e32 v138, s41, v138
	v_and_b32_e32 v139, 3, v138
	v_lshlrev_b32_e32 v139, s39, v139
	v_bfe_u32 v140, v138, 2, 2
	v_add_u32_e32 v139, v139, v140
	v_lshl_add_u32 v139, v139, 7, v162
	v_ashrrev_i32_e32 v138, 4, v138
	v_med3_i32 v138, v138, 0, s38
	v_lshl_add_u32 v138, v138, 9, v139
	global_load_dwordx4 v[68:71], v138, s[26:27]
	s_add_i32 s2, s40, 48
	v_add_u32_e32 v138, s2, v164
	v_lshlrev_b32_e32 v138, 4, v138
	v_add_u32_e32 v138, s41, v138
	v_and_b32_e32 v139, 3, v138
	v_lshlrev_b32_e32 v139, s39, v139
	v_bfe_u32 v140, v138, 2, 2
	v_add_u32_e32 v139, v139, v140
	v_lshl_add_u32 v139, v139, 7, v162
	v_ashrrev_i32_e32 v138, 4, v138
	v_med3_i32 v138, v138, 0, s38
	v_lshl_add_u32 v138, v138, 9, v139
	global_load_dwordx4 v[72:75], v138, s[26:27]
	s_add_i32 s2, s40, 56
	v_add_u32_e32 v138, s2, v164
	v_lshlrev_b32_e32 v138, 4, v138
	v_add_u32_e32 v138, s41, v138
	v_and_b32_e32 v139, 3, v138
	v_lshlrev_b32_e32 v139, s39, v139
	v_bfe_u32 v140, v138, 2, 2
	v_add_u32_e32 v139, v139, v140
	v_lshl_add_u32 v139, v139, 7, v162
	v_ashrrev_i32_e32 v138, 4, v138
	v_med3_i32 v138, v138, 0, s38
	v_lshl_add_u32 v138, v138, 9, v139
	global_load_dwordx4 v[76:79], v138, s[26:27]
	ds_write_b128 v165, v[80:83]
	ds_write_b128 v165, v[84:87] offset:1152
	ds_write_b128 v165, v[88:91] offset:2304
	ds_write_b128 v165, v[92:95] offset:3456
	v_mfma_f32_16x16x32_bf16 v[204:207], v[236:239], v[112:115], 0
	v_mfma_f32_16x16x32_bf16 v[208:211], v[240:243], v[112:115], 0
	v_mfma_f32_16x16x32_bf16 v[212:215], v[244:247], v[112:115], 0
	v_mfma_f32_16x16x32_bf16 v[216:219], v[248:251], v[112:115], 0
	s_waitcnt lgkmcnt(0)
	ds_read_b64_tr_b16 v[236:237], v166
	ds_read_b64_tr_b16 v[238:239], v166 offset:2304
	ds_read_b64_tr_b16 v[240:241], v166 offset:32
	ds_read_b64_tr_b16 v[242:243], v166 offset:2336
	ds_read_b64_tr_b16 v[244:245], v166 offset:64
	ds_read_b64_tr_b16 v[246:247], v166 offset:2368
	ds_read_b64_tr_b16 v[248:249], v166 offset:96
	ds_read_b64_tr_b16 v[250:251], v166 offset:2400
	s_waitcnt lgkmcnt(0)
	s_add_i32 s2, s40, 64
	v_add_u32_e32 v138, s2, v164
	v_lshlrev_b32_e32 v138, 4, v138
	v_add_u32_e32 v138, s41, v138
	v_and_b32_e32 v139, 3, v138
	v_lshlrev_b32_e32 v139, s39, v139
	v_bfe_u32 v140, v138, 2, 2
	v_add_u32_e32 v139, v139, v140
	v_lshl_add_u32 v139, v139, 7, v162
	v_ashrrev_i32_e32 v138, 4, v138
	v_med3_i32 v138, v138, 0, s38
	v_lshl_add_u32 v138, v138, 9, v139
	global_load_dwordx4 v[80:83], v138, s[26:27]
	s_add_i32 s2, s40, 72
	v_add_u32_e32 v138, s2, v164
	v_lshlrev_b32_e32 v138, 4, v138
	v_add_u32_e32 v138, s41, v138
	v_and_b32_e32 v139, 3, v138
	v_lshlrev_b32_e32 v139, s39, v139
	v_bfe_u32 v140, v138, 2, 2
	v_add_u32_e32 v139, v139, v140
	v_lshl_add_u32 v139, v139, 7, v162
	v_ashrrev_i32_e32 v138, 4, v138
	v_med3_i32 v138, v138, 0, s38
	v_lshl_add_u32 v138, v138, 9, v139
	global_load_dwordx4 v[84:87], v138, s[26:27]
	ds_write_b128 v165, v[96:99]
	ds_write_b128 v165, v[100:103] offset:1152
	ds_write_b128 v165, v[104:107] offset:2304
	ds_write_b128 v165, v[108:111] offset:3456
	v_mfma_f32_16x16x32_bf16 v[204:207], v[236:239], v[116:119], v[204:207]
	v_mfma_f32_16x16x32_bf16 v[208:211], v[240:243], v[116:119], v[208:211]
	v_mfma_f32_16x16x32_bf16 v[212:215], v[244:247], v[116:119], v[212:215]
	v_mfma_f32_16x16x32_bf16 v[216:219], v[248:251], v[116:119], v[216:219]
	s_waitcnt lgkmcnt(0)
	ds_read_b64_tr_b16 v[236:237], v166
	ds_read_b64_tr_b16 v[238:239], v166 offset:2304
	ds_read_b64_tr_b16 v[240:241], v166 offset:32
	ds_read_b64_tr_b16 v[242:243], v166 offset:2336
	ds_read_b64_tr_b16 v[244:245], v166 offset:64
	ds_read_b64_tr_b16 v[246:247], v166 offset:2368
	ds_read_b64_tr_b16 v[248:249], v166 offset:96
	ds_read_b64_tr_b16 v[250:251], v166 offset:2400
	s_waitcnt lgkmcnt(0)
	s_waitcnt vmcnt(2)
	ds_write_b128 v165, v[64:67]
	ds_write_b128 v165, v[68:71] offset:1152
	ds_write_b128 v165, v[72:75] offset:2304
	ds_write_b128 v165, v[76:79] offset:3456
	v_mfma_f32_16x16x32_bf16 v[204:207], v[236:239], v[120:123], v[204:207]
	v_mfma_f32_16x16x32_bf16 v[208:211], v[240:243], v[120:123], v[208:211]
	v_mfma_f32_16x16x32_bf16 v[212:215], v[244:247], v[120:123], v[212:215]
	v_mfma_f32_16x16x32_bf16 v[216:219], v[248:251], v[120:123], v[216:219]
	s_waitcnt lgkmcnt(0)
	ds_read_b64_tr_b16 v[236:237], v166
	ds_read_b64_tr_b16 v[238:239], v166 offset:2304
	ds_read_b64_tr_b16 v[240:241], v166 offset:32
	ds_read_b64_tr_b16 v[242:243], v166 offset:2336
	ds_read_b64_tr_b16 v[244:245], v166 offset:64
	ds_read_b64_tr_b16 v[246:247], v166 offset:2368
	ds_read_b64_tr_b16 v[248:249], v166 offset:96
	ds_read_b64_tr_b16 v[250:251], v166 offset:2400
	s_waitcnt lgkmcnt(0)
	s_waitcnt vmcnt(0)
	ds_write_b128 v165, v[80:83]
	ds_write_b128 v165, v[84:87] offset:1152
	v_mfma_f32_16x16x32_bf16 v[204:207], v[236:239], v[124:127], v[204:207]
	v_mfma_f32_16x16x32_bf16 v[208:211], v[240:243], v[124:127], v[208:211]
	v_mfma_f32_16x16x32_bf16 v[212:215], v[244:247], v[124:127], v[212:215]
	v_mfma_f32_16x16x32_bf16 v[216:219], v[248:251], v[124:127], v[216:219]
	s_waitcnt lgkmcnt(0)
	ds_read_b64_tr_b16 v[236:237], v166
	ds_read_b64_tr_b16 v[238:239], v166 offset:2304
	ds_read_b64_tr_b16 v[240:241], v166 offset:32
	ds_read_b64_tr_b16 v[242:243], v166 offset:2336
	ds_read_b64_tr_b16 v[244:245], v166 offset:64
	ds_read_b64_tr_b16 v[246:247], v166 offset:2368
	ds_read_b64_tr_b16 v[248:249], v166 offset:96
	ds_read_b64_tr_b16 v[250:251], v166 offset:2400
	s_waitcnt lgkmcnt(0)
	v_mfma_f32_16x16x32_bf16 v[204:207], v[236:239], v[128:131], v[204:207]
	v_mfma_f32_16x16x32_bf16 v[208:211], v[240:243], v[128:131], v[208:211]
	v_mfma_f32_16x16x32_bf16 v[212:215], v[244:247], v[128:131], v[212:215]
	v_mfma_f32_16x16x32_bf16 v[216:219], v[248:251], v[128:131], v[216:219]
	s_add_i32 s2, s42, -64
	v_add_u32_e32 v138, s2, v164
	v_lshlrev_b32_e32 v138, 4, v138
	v_add_u32_e32 v138, s43, v138
	v_and_b32_e32 v139, 3, v138
	v_lshlrev_b32_e32 v139, s13, v139
	v_bfe_u32 v140, v138, 2, 2
	v_add_u32_e32 v139, v139, v140
	v_lshl_add_u32 v139, v139, 7, v162
	v_ashrrev_i32_e32 v138, 4, v138
	v_med3_i32 v138, v138, 0, s14
	v_lshl_add_u32 v138, v138, 9, v139
	global_load_dwordx4 v[64:67], v138, s[22:23]
	s_add_i32 s2, s42, -56
	v_add_u32_e32 v138, s2, v164
	v_lshlrev_b32_e32 v138, 4, v138
	v_add_u32_e32 v138, s43, v138
	v_and_b32_e32 v139, 3, v138
	v_lshlrev_b32_e32 v139, s13, v139
	v_bfe_u32 v140, v138, 2, 2
	v_add_u32_e32 v139, v139, v140
	v_lshl_add_u32 v139, v139, 7, v162
	v_ashrrev_i32_e32 v138, 4, v138
	v_med3_i32 v138, v138, 0, s14
	v_lshl_add_u32 v138, v138, 9, v139
	global_load_dwordx4 v[68:71], v138, s[22:23]
	s_add_i32 s2, s42, -48
	v_add_u32_e32 v138, s2, v164
	v_lshlrev_b32_e32 v138, 4, v138
	v_add_u32_e32 v138, s43, v138
	v_and_b32_e32 v139, 3, v138
	v_lshlrev_b32_e32 v139, s13, v139
	v_bfe_u32 v140, v138, 2, 2
	v_add_u32_e32 v139, v139, v140
	v_lshl_add_u32 v139, v139, 7, v162
	v_ashrrev_i32_e32 v138, 4, v138
	v_med3_i32 v138, v138, 0, s14
	v_lshl_add_u32 v138, v138, 9, v139
	global_load_dwordx4 v[72:75], v138, s[22:23]
	s_add_i32 s2, s42, -40
	v_add_u32_e32 v138, s2, v164
	v_lshlrev_b32_e32 v138, 4, v138
	v_add_u32_e32 v138, s43, v138
	v_and_b32_e32 v139, 3, v138
	v_lshlrev_b32_e32 v139, s13, v139
	v_bfe_u32 v140, v138, 2, 2
	v_add_u32_e32 v139, v139, v140
	v_lshl_add_u32 v139, v139, 7, v162
	v_ashrrev_i32_e32 v138, 4, v138
	v_med3_i32 v138, v138, 0, s14
	v_lshl_add_u32 v138, v138, 9, v139
	global_load_dwordx4 v[76:79], v138, s[22:23]
	s_add_i32 s2, s42, -32
	v_add_u32_e32 v138, s2, v164
	v_lshlrev_b32_e32 v138, 4, v138
	v_add_u32_e32 v138, s43, v138
	v_and_b32_e32 v139, 3, v138
	v_lshlrev_b32_e32 v139, s13, v139
	v_bfe_u32 v140, v138, 2, 2
	v_add_u32_e32 v139, v139, v140
	v_lshl_add_u32 v139, v139, 7, v162
	v_ashrrev_i32_e32 v138, 4, v138
	v_med3_i32 v138, v138, 0, s14
	v_lshl_add_u32 v138, v138, 9, v139
	global_load_dwordx4 v[80:83], v138, s[22:23]
	s_add_i32 s2, s42, -24
	v_add_u32_e32 v138, s2, v164
	v_lshlrev_b32_e32 v138, 4, v138
	v_add_u32_e32 v138, s43, v138
	v_and_b32_e32 v139, 3, v138
	v_lshlrev_b32_e32 v139, s13, v139
	v_bfe_u32 v140, v138, 2, 2
	v_add_u32_e32 v139, v139, v140
	v_lshl_add_u32 v139, v139, 7, v162
	v_ashrrev_i32_e32 v138, 4, v138
	v_med3_i32 v138, v138, 0, s14
	v_lshl_add_u32 v138, v138, 9, v139
	global_load_dwordx4 v[84:87], v138, s[22:23]
	s_add_i32 s2, s42, -16
	v_add_u32_e32 v138, s2, v164
	v_lshlrev_b32_e32 v138, 4, v138
	v_add_u32_e32 v138, s43, v138
	v_and_b32_e32 v139, 3, v138
	v_lshlrev_b32_e32 v139, s13, v139
	v_bfe_u32 v140, v138, 2, 2
	v_add_u32_e32 v139, v139, v140
	v_lshl_add_u32 v139, v139, 7, v162
	v_ashrrev_i32_e32 v138, 4, v138
	v_med3_i32 v138, v138, 0, s14
	v_lshl_add_u32 v138, v138, 9, v139
	global_load_dwordx4 v[88:91], v138, s[22:23]
	s_add_i32 s2, s42, -8
	v_add_u32_e32 v138, s2, v164
	v_lshlrev_b32_e32 v138, 4, v138
	v_add_u32_e32 v138, s43, v138
	v_and_b32_e32 v139, 3, v138
	v_lshlrev_b32_e32 v139, s13, v139
	v_bfe_u32 v140, v138, 2, 2
	v_add_u32_e32 v139, v139, v140
	v_lshl_add_u32 v139, v139, 7, v162
	v_ashrrev_i32_e32 v138, 4, v138
	v_med3_i32 v138, v138, 0, s14
	v_lshl_add_u32 v138, v138, 9, v139
	global_load_dwordx4 v[92:95], v138, s[22:23]
	s_add_i32 s2, s42, 0
	v_add_u32_e32 v138, s2, v164
	v_lshlrev_b32_e32 v138, 4, v138
	v_add_u32_e32 v138, s43, v138
	v_and_b32_e32 v139, 3, v138
	v_lshlrev_b32_e32 v139, s13, v139
	v_bfe_u32 v140, v138, 2, 2
	v_add_u32_e32 v139, v139, v140
	v_lshl_add_u32 v139, v139, 7, v162
	v_ashrrev_i32_e32 v138, 4, v138
	v_med3_i32 v138, v138, 0, s14
	v_lshl_add_u32 v138, v138, 9, v139
	global_load_dwordx4 v[96:99], v138, s[22:23]
	s_add_i32 s2, s42, 8
	v_add_u32_e32 v138, s2, v164
	v_lshlrev_b32_e32 v138, 4, v138
	v_add_u32_e32 v138, s43, v138
	v_and_b32_e32 v139, 3, v138
	v_lshlrev_b32_e32 v139, s13, v139
	v_bfe_u32 v140, v138, 2, 2
	v_add_u32_e32 v139, v139, v140
	v_lshl_add_u32 v139, v139, 7, v162
	v_ashrrev_i32_e32 v138, 4, v138
	v_med3_i32 v138, v138, 0, s14
	v_lshl_add_u32 v138, v138, 9, v139
	global_load_dwordx4 v[100:103], v138, s[22:23]
	s_add_i32 s2, s42, 16
	v_add_u32_e32 v138, s2, v164
	v_lshlrev_b32_e32 v138, 4, v138
	v_add_u32_e32 v138, s43, v138
	v_and_b32_e32 v139, 3, v138
	v_lshlrev_b32_e32 v139, s13, v139
	v_bfe_u32 v140, v138, 2, 2
	v_add_u32_e32 v139, v139, v140
	v_lshl_add_u32 v139, v139, 7, v162
	v_ashrrev_i32_e32 v138, 4, v138
	v_med3_i32 v138, v138, 0, s14
	v_lshl_add_u32 v138, v138, 9, v139
	global_load_dwordx4 v[104:107], v138, s[22:23]
	s_add_i32 s2, s42, 24
	v_add_u32_e32 v138, s2, v164
	v_lshlrev_b32_e32 v138, 4, v138
	v_add_u32_e32 v138, s43, v138
	v_and_b32_e32 v139, 3, v138
	v_lshlrev_b32_e32 v139, s13, v139
	v_bfe_u32 v140, v138, 2, 2
	v_add_u32_e32 v139, v139, v140
	v_lshl_add_u32 v139, v139, 7, v162
	v_ashrrev_i32_e32 v138, 4, v138
	v_med3_i32 v138, v138, 0, s14
	v_lshl_add_u32 v138, v138, 9, v139
	global_load_dwordx4 v[108:111], v138, s[22:23]
	ds_read_b128 v[236:239], v173 offset:0
	ds_read_b128 v[240:243], v173 offset:64
	ds_read_b128 v[244:247], v173 offset:128
	ds_read_b128 v[248:251], v173 offset:192
	ds_read_b32 v142, v174 offset:0
	s_waitcnt lgkmcnt(0)
	v_add_f32_e32 v204, v236, v204
	v_add_f32_e32 v205, v237, v205
	v_add_f32_e32 v206, v238, v206
	v_add_f32_e32 v207, v239, v207
	v_add_f32_e32 v208, v240, v208
	v_add_f32_e32 v209, v241, v209
	v_add_f32_e32 v210, v242, v210
	v_add_f32_e32 v211, v243, v211
	v_add_f32_e32 v212, v244, v212
	v_add_f32_e32 v213, v245, v213
	v_add_f32_e32 v214, v246, v214
	v_add_f32_e32 v215, v247, v215
	v_add_f32_e32 v216, v248, v216
	v_add_f32_e32 v217, v249, v217
	v_add_f32_e32 v218, v250, v218
	v_add_f32_e32 v219, v251, v219
	v_add_f32_e32 v132, v142, v132
	ds_write_b128 v173, v[204:207] offset:0
	ds_write_b128 v173, v[208:211] offset:64
	ds_write_b128 v173, v[212:215] offset:128
	ds_write_b128 v173, v[216:219] offset:192
	ds_write_b32 v174, v132 offset:0
	s_mov_b32 s40, s42
	s_mov_b32 s41, s43
	v_mov_b32_e32 v173, v176
	v_mov_b32_e32 v174, v177
	v_mov_b32_e32 v175, v178
	v_mov_b32_e32 v179, v183
	v_mov_b32_e32 v182, v252
	s_lshr_b32 s44, s33, 4
	s_add_i32 s45, s10, s8
	s_cmp_lt_u32 s45, 0x800
	s_cbranch_scc1 .Latt_newunit
	s_mov_b32 s37, 1
	s_branch .Latt_ud_done
.Latt_newunit:
	s_mov_b32 s10, s45
	s_lshr_b32 s2, s10, 3
	s_and_b32 s3, s10, 7
	s_and_b32 s30, s2, 31
	s_lshl_b32 s31, s3, 5
	s_or_b32 s31, s31, s30
	s_lshr_b32 s30, s10, 8
	s_cmp_eq_u32 s8, 0x100
	s_cselect_b32 s2, s31, s2
	s_cselect_b32 s17, s30, s3
	s_lshl_b32 s16, s2, 8
	s_cmp_lt_u32 s2, 0x80
	s_cselect_b32 s12, s82, s83
	s_cselect_b32 s13, 12, 10
	s_cselect_b32 s3, s84, s85
	s_and_b32 s3, s16, s3
	s_sub_i32 s15, s16, s3
	s_lshr_b32 s30, s12, 4
	s_add_i32 s14, s30, -1
	s_lshl_b32 s30, s17, 23
	s_lshl_b32 s3, s3, 7
	s_add_u32 s30, s30, s3
	s_add_u32 s18, s4, s30
	s_addc_u32 s19, s5, 0
	s_add_u32 s20, s18, 0x4000000
	s_addc_u32 s21, s19, 0
	s_add_u32 s22, s18, 0x8000000
	s_addc_u32 s23, s19, 0
.Latt_ud_done:
	s_lshl_b32 s2, s0, 5
	s_add_i32 s42, s15, s2
	s_mov_b32 s43, 0
	s_waitcnt vmcnt(12)
	v_mov_b32_e32 v132, 0
	v_mfma_f32_16x16x32_bf16 v[236:239], v[0:3], v[48:51], 0
	v_mfma_f32_16x16x32_bf16 v[236:239], v[4:7], v[52:55], v[236:239]
	v_mfma_f32_16x16x32_bf16 v[240:243], v[8:11], v[48:51], 0
	v_mfma_f32_16x16x32_bf16 v[240:243], v[12:15], v[52:55], v[240:243]
	s_nop 7
	v_min_f32_e32 v152, 0x42a00000, v236
	v_min_f32_e32 v153, 0x42a00000, v237
	v_min_f32_e32 v154, 0x42a00000, v238
	v_min_f32_e32 v155, 0x42a00000, v239
	v_mfma_f32_16x16x32_bf16 v[236:239], v[16:19], v[48:51], 0
	v_mfma_f32_16x16x32_bf16 v[236:239], v[20:23], v[52:55], v[236:239]
	v_add_u32_e32 v136, 0x60, v182
	v_med3_i32 v136, v136, 0, s38
	v_lshl_add_u32 v136, v136, 9, v179
	global_load_dwordx4 v[0:3], v136, s[24:25]
	global_load_dwordx4 v[4:7], v136, s[24:25] offset:64
	v_mul_f32_e32 v152, 0x3fb8aa3b, v152
	v_mul_f32_e32 v153, 0x3fb8aa3b, v153
	v_mul_f32_e32 v154, 0x3fb8aa3b, v154
	v_mul_f32_e32 v155, 0x3fb8aa3b, v155
	v_exp_f32_e32 v152, v152
	v_exp_f32_e32 v153, v153
	v_exp_f32_e32 v154, v154
	v_exp_f32_e32 v155, v155
	v_add_u32_e32 v138, 0, v175
	v_add_u32_e32 v139, 1, v175
	v_add_u32_e32 v140, 2, v175
	v_add_u32_e32 v141, 3, v175
	v_cmp_gt_u32_e64 s[70:71], s44, v138
	v_cmp_gt_u32_e64 s[72:73], s44, v139
	v_cmp_gt_u32_e64 s[74:75], s44, v140
	v_cmp_gt_u32_e64 s[76:77], s44, v141
	v_cndmask_b32_e64 v152, 0, v152, s[54:55]
	v_cndmask_b32_e64 v153, 0, v153, s[56:57]
	v_cndmask_b32_e64 v154, 0, v154, s[58:59]
	v_cndmask_b32_e64 v155, 0, v155, s[60:61]
	v_cndmask_b32_e64 v152, 0, v152, s[70:71]
	v_cndmask_b32_e64 v153, 0, v153, s[72:73]
	v_cndmask_b32_e64 v154, 0, v154, s[74:75]
	v_cndmask_b32_e64 v155, 0, v155, s[76:77]
	v_add_f32_e32 v132, v132, v152
	v_add_f32_e32 v132, v132, v153
	v_add_f32_e32 v132, v132, v154
	v_add_f32_e32 v132, v132, v155
	v_cvt_pk_bf16_f32 v112, v152, v153
	v_cvt_pk_bf16_f32 v113, v154, v155
	v_min_f32_e32 v152, 0x42a00000, v240
	v_min_f32_e32 v153, 0x42a00000, v241
	v_min_f32_e32 v154, 0x42a00000, v242
	v_min_f32_e32 v155, 0x42a00000, v243
	v_mfma_f32_16x16x32_bf16 v[240:243], v[24:27], v[48:51], 0
	v_mfma_f32_16x16x32_bf16 v[240:243], v[28:31], v[52:55], v[240:243]
	v_add_u32_e32 v135, 0x70, v182
	v_med3_i32 v135, v135, 0, s38
	v_lshl_add_u32 v135, v135, 9, v179
	global_load_dwordx4 v[8:11], v135, s[24:25]
	global_load_dwordx4 v[12:15], v135, s[24:25] offset:64
	v_mul_f32_e32 v152, 0x3fb8aa3b, v152
	v_mul_f32_e32 v153, 0x3fb8aa3b, v153
	v_mul_f32_e32 v154, 0x3fb8aa3b, v154
	v_mul_f32_e32 v155, 0x3fb8aa3b, v155
	v_exp_f32_e32 v152, v152
	v_exp_f32_e32 v153, v153
	v_exp_f32_e32 v154, v154
	v_exp_f32_e32 v155, v155
	v_add_u32_e32 v138, 16, v175
	v_add_u32_e32 v139, 17, v175
	v_add_u32_e32 v140, 18, v175
	v_add_u32_e32 v141, 19, v175
	v_cmp_gt_u32_e64 s[70:71], s44, v138
	v_cmp_gt_u32_e64 s[72:73], s44, v139
	v_cmp_gt_u32_e64 s[74:75], s44, v140
	v_cmp_gt_u32_e64 s[76:77], s44, v141
	v_cndmask_b32_e64 v152, 0, v152, s[70:71]
	v_cndmask_b32_e64 v153, 0, v153, s[72:73]
	v_cndmask_b32_e64 v154, 0, v154, s[74:75]
	v_cndmask_b32_e64 v155, 0, v155, s[76:77]
	v_add_f32_e32 v132, v132, v152
	v_add_f32_e32 v132, v132, v153
	v_add_f32_e32 v132, v132, v154
	v_add_f32_e32 v132, v132, v155
	v_cvt_pk_bf16_f32 v114, v152, v153
	v_cvt_pk_bf16_f32 v115, v154, v155
	v_min_f32_e32 v152, 0x42a00000, v236
	v_min_f32_e32 v153, 0x42a00000, v237
	v_min_f32_e32 v154, 0x42a00000, v238
	v_min_f32_e32 v155, 0x42a00000, v239
	v_mfma_f32_16x16x32_bf16 v[236:239], v[32:35], v[48:51], 0
	v_mfma_f32_16x16x32_bf16 v[236:239], v[36:39], v[52:55], v[236:239]
	v_add_u32_e32 v136, 0x80, v182
	v_med3_i32 v136, v136, 0, s38
	v_lshl_add_u32 v136, v136, 9, v179
	global_load_dwordx4 v[16:19], v136, s[24:25]
	global_load_dwordx4 v[20:23], v136, s[24:25] offset:64
	v_mul_f32_e32 v152, 0x3fb8aa3b, v152
	v_mul_f32_e32 v153, 0x3fb8aa3b, v153
	v_mul_f32_e32 v154, 0x3fb8aa3b, v154
	v_mul_f32_e32 v155, 0x3fb8aa3b, v155
	v_exp_f32_e32 v152, v152
	v_exp_f32_e32 v153, v153
	v_exp_f32_e32 v154, v154
	v_exp_f32_e32 v155, v155
	v_add_u32_e32 v138, 32, v175
	v_add_u32_e32 v139, 33, v175
	v_add_u32_e32 v140, 34, v175
	v_add_u32_e32 v141, 35, v175
	v_cmp_gt_u32_e64 s[70:71], s44, v138
	v_cmp_gt_u32_e64 s[72:73], s44, v139
	v_cmp_gt_u32_e64 s[74:75], s44, v140
	v_cmp_gt_u32_e64 s[76:77], s44, v141
	v_cndmask_b32_e64 v152, 0, v152, s[70:71]
	v_cndmask_b32_e64 v153, 0, v153, s[72:73]
	v_cndmask_b32_e64 v154, 0, v154, s[74:75]
	v_cndmask_b32_e64 v155, 0, v155, s[76:77]
	v_add_f32_e32 v132, v132, v152
	v_add_f32_e32 v132, v132, v153
	v_add_f32_e32 v132, v132, v154
	v_add_f32_e32 v132, v132, v155
	v_cvt_pk_bf16_f32 v116, v152, v153
	v_cvt_pk_bf16_f32 v117, v154, v155
	v_min_f32_e32 v152, 0x42a00000, v240
	v_min_f32_e32 v153, 0x42a00000, v241
	v_min_f32_e32 v154, 0x42a00000, v242
	v_min_f32_e32 v155, 0x42a00000, v243
	v_mfma_f32_16x16x32_bf16 v[240:243], v[40:43], v[48:51], 0
	v_mfma_f32_16x16x32_bf16 v[240:243], v[44:47], v[52:55], v[240:243]
	v_mul_f32_e32 v152, 0x3fb8aa3b, v152
	v_mul_f32_e32 v153, 0x3fb8aa3b, v153
	v_mul_f32_e32 v154, 0x3fb8aa3b, v154
	v_mul_f32_e32 v155, 0x3fb8aa3b, v155
	v_exp_f32_e32 v152, v152
	v_exp_f32_e32 v153, v153
	v_exp_f32_e32 v154, v154
	v_exp_f32_e32 v155, v155
	v_add_u32_e32 v138, 48, v175
	v_add_u32_e32 v139, 49, v175
	v_add_u32_e32 v140, 50, v175
	v_add_u32_e32 v141, 51, v175
	v_cmp_gt_u32_e64 s[70:71], s44, v138
	v_cmp_gt_u32_e64 s[72:73], s44, v139
	v_cmp_gt_u32_e64 s[74:75], s44, v140
	v_cmp_gt_u32_e64 s[76:77], s44, v141
	v_cndmask_b32_e64 v152, 0, v152, s[70:71]
	v_cndmask_b32_e64 v153, 0, v153, s[72:73]
	v_cndmask_b32_e64 v154, 0, v154, s[74:75]
	v_cndmask_b32_e64 v155, 0, v155, s[76:77]
	v_add_f32_e32 v132, v132, v152
	v_add_f32_e32 v132, v132, v153
	v_add_f32_e32 v132, v132, v154
	v_add_f32_e32 v132, v132, v155
	v_cvt_pk_bf16_f32 v118, v152, v153
	v_cvt_pk_bf16_f32 v119, v154, v155
	v_min_f32_e32 v152, 0x42a00000, v236
	v_min_f32_e32 v153, 0x42a00000, v237
	v_min_f32_e32 v154, 0x42a00000, v238
	v_min_f32_e32 v155, 0x42a00000, v239
	s_waitcnt vmcnt(4)
	v_mfma_f32_16x16x32_bf16 v[236:239], v[0:3], v[48:51], 0
	v_mfma_f32_16x16x32_bf16 v[236:239], v[4:7], v[52:55], v[236:239]
	v_mul_f32_e32 v152, 0x3fb8aa3b, v152
	v_mul_f32_e32 v153, 0x3fb8aa3b, v153
	v_mul_f32_e32 v154, 0x3fb8aa3b, v154
	v_mul_f32_e32 v155, 0x3fb8aa3b, v155
	v_exp_f32_e32 v152, v152
	v_exp_f32_e32 v153, v153
	v_exp_f32_e32 v154, v154
	v_exp_f32_e32 v155, v155
	v_add_u32_e32 v138, 64, v175
	v_add_u32_e32 v139, 0x41, v175
	v_add_u32_e32 v140, 0x42, v175
	v_add_u32_e32 v141, 0x43, v175
	v_cmp_gt_u32_e64 s[70:71], s44, v138
	v_cmp_gt_u32_e64 s[72:73], s44, v139
	v_cmp_gt_u32_e64 s[74:75], s44, v140
	v_cmp_gt_u32_e64 s[76:77], s44, v141
	v_cndmask_b32_e64 v152, 0, v152, s[70:71]
	v_cndmask_b32_e64 v153, 0, v153, s[72:73]
	v_cndmask_b32_e64 v154, 0, v154, s[74:75]
	v_cndmask_b32_e64 v155, 0, v155, s[76:77]
	v_add_f32_e32 v132, v132, v152
	v_add_f32_e32 v132, v132, v153
	v_add_f32_e32 v132, v132, v154
	v_add_f32_e32 v132, v132, v155
	v_cvt_pk_bf16_f32 v120, v152, v153
	v_cvt_pk_bf16_f32 v121, v154, v155
	v_min_f32_e32 v152, 0x42a00000, v240
	v_min_f32_e32 v153, 0x42a00000, v241
	v_min_f32_e32 v154, 0x42a00000, v242
	v_min_f32_e32 v155, 0x42a00000, v243
	s_waitcnt vmcnt(2)
	v_mfma_f32_16x16x32_bf16 v[240:243], v[8:11], v[48:51], 0
	v_mfma_f32_16x16x32_bf16 v[240:243], v[12:15], v[52:55], v[240:243]
	v_mul_f32_e32 v152, 0x3fb8aa3b, v152
	v_mul_f32_e32 v153, 0x3fb8aa3b, v153
	v_mul_f32_e32 v154, 0x3fb8aa3b, v154
	v_mul_f32_e32 v155, 0x3fb8aa3b, v155
	v_exp_f32_e32 v152, v152
	v_exp_f32_e32 v153, v153
	v_exp_f32_e32 v154, v154
	v_exp_f32_e32 v155, v155
	v_add_u32_e32 v138, 0x50, v175
	v_add_u32_e32 v139, 0x51, v175
	v_add_u32_e32 v140, 0x52, v175
	v_add_u32_e32 v141, 0x53, v175
	v_cmp_gt_u32_e64 s[70:71], s44, v138
	v_cmp_gt_u32_e64 s[72:73], s44, v139
	v_cmp_gt_u32_e64 s[74:75], s44, v140
	v_cmp_gt_u32_e64 s[76:77], s44, v141
	v_cndmask_b32_e64 v152, 0, v152, s[70:71]
	v_cndmask_b32_e64 v153, 0, v153, s[72:73]
	v_cndmask_b32_e64 v154, 0, v154, s[74:75]
	v_cndmask_b32_e64 v155, 0, v155, s[76:77]
	v_add_f32_e32 v132, v132, v152
	v_add_f32_e32 v132, v132, v153
	v_add_f32_e32 v132, v132, v154
	v_add_f32_e32 v132, v132, v155
	v_cvt_pk_bf16_f32 v122, v152, v153
	v_cvt_pk_bf16_f32 v123, v154, v155
	v_min_f32_e32 v152, 0x42a00000, v236
	v_min_f32_e32 v153, 0x42a00000, v237
	v_min_f32_e32 v154, 0x42a00000, v238
	v_min_f32_e32 v155, 0x42a00000, v239
	s_waitcnt vmcnt(0)
	v_mfma_f32_16x16x32_bf16 v[236:239], v[16:19], v[48:51], 0
	v_mfma_f32_16x16x32_bf16 v[236:239], v[20:23], v[52:55], v[236:239]
	v_mul_f32_e32 v152, 0x3fb8aa3b, v152
	v_mul_f32_e32 v153, 0x3fb8aa3b, v153
	v_mul_f32_e32 v154, 0x3fb8aa3b, v154
	v_mul_f32_e32 v155, 0x3fb8aa3b, v155
	v_exp_f32_e32 v152, v152
	v_exp_f32_e32 v153, v153
	v_exp_f32_e32 v154, v154
	v_exp_f32_e32 v155, v155
	v_add_u32_e32 v138, 0x60, v175
	v_add_u32_e32 v139, 0x61, v175
	v_add_u32_e32 v140, 0x62, v175
	v_add_u32_e32 v141, 0x63, v175
	v_cmp_gt_u32_e64 s[70:71], s44, v138
	v_cmp_gt_u32_e64 s[72:73], s44, v139
	v_cmp_gt_u32_e64 s[74:75], s44, v140
	v_cmp_gt_u32_e64 s[76:77], s44, v141
	v_cndmask_b32_e64 v152, 0, v152, s[70:71]
	v_cndmask_b32_e64 v153, 0, v153, s[72:73]
	v_cndmask_b32_e64 v154, 0, v154, s[74:75]
	v_cndmask_b32_e64 v155, 0, v155, s[76:77]
	v_add_f32_e32 v132, v132, v152
	v_add_f32_e32 v132, v132, v153
	v_add_f32_e32 v132, v132, v154
	v_add_f32_e32 v132, v132, v155
	v_cvt_pk_bf16_f32 v124, v152, v153
	v_cvt_pk_bf16_f32 v125, v154, v155
	v_min_f32_e32 v152, 0x42a00000, v240
	v_min_f32_e32 v153, 0x42a00000, v241
	v_min_f32_e32 v154, 0x42a00000, v242
	v_min_f32_e32 v155, 0x42a00000, v243
	v_mul_f32_e32 v152, 0x3fb8aa3b, v152
	v_mul_f32_e32 v153, 0x3fb8aa3b, v153
	v_mul_f32_e32 v154, 0x3fb8aa3b, v154
	v_mul_f32_e32 v155, 0x3fb8aa3b, v155
	v_exp_f32_e32 v152, v152
	v_exp_f32_e32 v153, v153
	v_exp_f32_e32 v154, v154
	v_exp_f32_e32 v155, v155
	v_add_u32_e32 v138, 0x70, v175
	v_add_u32_e32 v139, 0x71, v175
	v_add_u32_e32 v140, 0x72, v175
	v_add_u32_e32 v141, 0x73, v175
	v_cmp_gt_u32_e64 s[70:71], s44, v138
	v_cmp_gt_u32_e64 s[72:73], s44, v139
	v_cmp_gt_u32_e64 s[74:75], s44, v140
	v_cmp_gt_u32_e64 s[76:77], s44, v141
	v_cndmask_b32_e64 v152, 0, v152, s[70:71]
	v_cndmask_b32_e64 v153, 0, v153, s[72:73]
	v_cndmask_b32_e64 v154, 0, v154, s[74:75]
	v_cndmask_b32_e64 v155, 0, v155, s[76:77]
	v_add_f32_e32 v132, v132, v152
	v_add_f32_e32 v132, v132, v153
	v_add_f32_e32 v132, v132, v154
	v_add_f32_e32 v132, v132, v155
	v_cvt_pk_bf16_f32 v126, v152, v153
	v_cvt_pk_bf16_f32 v127, v154, v155
	v_min_f32_e32 v152, 0x42a00000, v236
	v_min_f32_e32 v153, 0x42a00000, v237
	v_min_f32_e32 v154, 0x42a00000, v238
	v_min_f32_e32 v155, 0x42a00000, v239
	v_mul_f32_e32 v152, 0x3fb8aa3b, v152
	v_mul_f32_e32 v153, 0x3fb8aa3b, v153
	v_mul_f32_e32 v154, 0x3fb8aa3b, v154
	v_mul_f32_e32 v155, 0x3fb8aa3b, v155
	v_exp_f32_e32 v152, v152
	v_exp_f32_e32 v153, v153
	v_exp_f32_e32 v154, v154
	v_exp_f32_e32 v155, v155
	v_add_u32_e32 v138, 0x80, v175
	v_add_u32_e32 v139, 0x81, v175
	v_add_u32_e32 v140, 0x82, v175
	v_add_u32_e32 v141, 0x83, v175
	v_cmp_gt_u32_e64 s[70:71], s44, v138
	v_cmp_gt_u32_e64 s[72:73], s44, v139
	v_cmp_gt_u32_e64 s[74:75], s44, v140
	v_cmp_gt_u32_e64 s[76:77], s44, v141
	v_cndmask_b32_e64 v152, 0, v152, s[62:63]
	v_cndmask_b32_e64 v153, 0, v153, s[64:65]
	v_cndmask_b32_e64 v154, 0, v154, s[66:67]
	v_cndmask_b32_e64 v155, 0, v155, s[68:69]
	v_cndmask_b32_e64 v152, 0, v152, s[70:71]
	v_cndmask_b32_e64 v153, 0, v153, s[72:73]
	v_cndmask_b32_e64 v154, 0, v154, s[74:75]
	v_cndmask_b32_e64 v155, 0, v155, s[76:77]
	v_add_f32_e32 v132, v132, v152
	v_add_f32_e32 v132, v132, v153
	v_add_f32_e32 v132, v132, v154
	v_add_f32_e32 v132, v132, v155
	v_cvt_pk_bf16_f32 v128, v152, v153
	v_cvt_pk_bf16_f32 v129, v154, v155
	v_add_u32_e32 v134, s42, v160
	v_add_u32_e32 v134, s43, v134
	v_subrev_u32_e32 v135, s15, v134
	v_lshrrev_b32_e32 v136, 4, v135
	v_add_u32_e32 v136, v136, v135
	v_mad_u32_u24 v176, v136, s79, v161
	v_lshl_add_u32 v177, v135, 2, s80
	s_sub_i32 s2, s42, 64
	v_add_u32_e32 v178, s2, v169
	v_and_b32_e32 v135, 3, v134
	v_lshlrev_b32_e32 v135, s13, v135
	v_lshrrev_b32_e32 v136, 2, v134
	v_add_u32_e32 v135, v135, v136
	v_lshl_add_u32 v135, v135, 7, v161
	global_load_dwordx4 v[48:51], v135, s[18:19]
	global_load_dwordx4 v[52:55], v135, s[18:19] offset:64
	v_add_u32_e32 v137, 16, v134
	v_and_b32_e32 v135, 3, v137
	v_lshlrev_b32_e32 v135, s13, v135
	v_lshrrev_b32_e32 v136, 2, v137
	v_add_u32_e32 v135, v135, v136
	v_lshl_add_u32 v135, v135, 7, v161
	global_load_dwordx4 v[56:59], v135, s[18:19]
	global_load_dwordx4 v[60:63], v135, s[18:19] offset:64
	v_subrev_u32_e32 v134, 64, v134
	v_and_b32_e32 v137, 3, v134
	v_lshlrev_b32_e32 v137, s13, v137
	v_bfe_u32 v135, v134, 2, 2
	v_add_u32_e32 v137, v137, v135
	v_lshl_add_u32 v183, v137, 7, v161
	v_ashrrev_i32_e32 v252, 4, v134
	v_med3_i32 v136, v252, 0, s14
	v_lshl_add_u32 v136, v136, 9, v183
	global_load_dwordx4 v[0:3], v136, s[20:21]
	global_load_dwordx4 v[4:7], v136, s[20:21] offset:64
	v_add_u32_e32 v135, 1, v252
	v_med3_i32 v135, v135, 0, s14
	v_lshl_add_u32 v135, v135, 9, v183
	global_load_dwordx4 v[8:11], v135, s[20:21]
	global_load_dwordx4 v[12:15], v135, s[20:21] offset:64
	v_add_u32_e32 v136, 2, v252
	v_med3_i32 v136, v136, 0, s14
	v_lshl_add_u32 v136, v136, 9, v183
	global_load_dwordx4 v[16:19], v136, s[20:21]
	global_load_dwordx4 v[20:23], v136, s[20:21] offset:64
	v_add_u32_e32 v135, 3, v252
	v_med3_i32 v135, v135, 0, s14
	v_lshl_add_u32 v135, v135, 9, v183
	global_load_dwordx4 v[24:27], v135, s[20:21]
	global_load_dwordx4 v[28:31], v135, s[20:21] offset:64
	v_add_u32_e32 v136, 4, v252
	v_med3_i32 v136, v136, 0, s14
	v_lshl_add_u32 v136, v136, 9, v183
	global_load_dwordx4 v[32:35], v136, s[20:21]
	global_load_dwordx4 v[36:39], v136, s[20:21] offset:64
	v_add_u32_e32 v135, 5, v252
	v_med3_i32 v135, v135, 0, s14
	v_lshl_add_u32 v135, v135, 9, v183
	global_load_dwordx4 v[40:43], v135, s[20:21]
	global_load_dwordx4 v[44:47], v135, s[20:21] offset:64
	ds_bpermute_b32 v142, v167, v132
	s_waitcnt lgkmcnt(0)
	v_add_f32_e32 v132, v132, v142
	ds_bpermute_b32 v142, v168, v132
	s_waitcnt lgkmcnt(0)
	v_add_f32_e32 v132, v132, v142
	s_waitcnt vmcnt(16)
	ds_write_b128 v165, v[64:67]
	ds_write_b128 v165, v[68:71] offset:1152
	ds_write_b128 v165, v[72:75] offset:2304
	ds_write_b128 v165, v[76:79] offset:3456
	s_waitcnt lgkmcnt(0)
	ds_read_b64_tr_b16 v[236:237], v166
	ds_read_b64_tr_b16 v[238:239], v166 offset:2304
	ds_read_b64_tr_b16 v[240:241], v166 offset:32
	ds_read_b64_tr_b16 v[242:243], v166 offset:2336
	ds_read_b64_tr_b16 v[244:245], v166 offset:64
	ds_read_b64_tr_b16 v[246:247], v166 offset:2368
	ds_read_b64_tr_b16 v[248:249], v166 offset:96
	ds_read_b64_tr_b16 v[250:251], v166 offset:2400
	s_waitcnt lgkmcnt(0)
	s_add_i32 s2, s40, 32
	v_add_u32_e32 v138, s2, v164
	v_lshlrev_b32_e32 v138, 4, v138
	v_add_u32_e32 v138, s41, v138
	v_and_b32_e32 v139, 3, v138
	v_lshlrev_b32_e32 v139, s39, v139
	v_bfe_u32 v140, v138, 2, 2
	v_add_u32_e32 v139, v139, v140
	v_lshl_add_u32 v139, v139, 7, v162
	v_ashrrev_i32_e32 v138, 4, v138
	v_med3_i32 v138, v138, 0, s38
	v_lshl_add_u32 v138, v138, 9, v139
	global_load_dwordx4 v[64:67], v138, s[26:27]
	s_add_i32 s2, s40, 40
	v_add_u32_e32 v138, s2, v164
	v_lshlrev_b32_e32 v138, 4, v138
	v_add_u32_e32 v138, s41, v138
	v_and_b32_e32 v139, 3, v138
	v_lshlrev_b32_e32 v139, s39, v139
	v_bfe_u32 v140, v138, 2, 2
	v_add_u32_e32 v139, v139, v140
	v_lshl_add_u32 v139, v139, 7, v162
	v_ashrrev_i32_e32 v138, 4, v138
	v_med3_i32 v138, v138, 0, s38
	v_lshl_add_u32 v138, v138, 9, v139
	global_load_dwordx4 v[68:71], v138, s[26:27]
	s_add_i32 s2, s40, 48
	v_add_u32_e32 v138, s2, v164
	v_lshlrev_b32_e32 v138, 4, v138
	v_add_u32_e32 v138, s41, v138
	v_and_b32_e32 v139, 3, v138
	v_lshlrev_b32_e32 v139, s39, v139
	v_bfe_u32 v140, v138, 2, 2
	v_add_u32_e32 v139, v139, v140
	v_lshl_add_u32 v139, v139, 7, v162
	v_ashrrev_i32_e32 v138, 4, v138
	v_med3_i32 v138, v138, 0, s38
	v_lshl_add_u32 v138, v138, 9, v139
	global_load_dwordx4 v[72:75], v138, s[26:27]
	s_add_i32 s2, s40, 56
	v_add_u32_e32 v138, s2, v164
	v_lshlrev_b32_e32 v138, 4, v138
	v_add_u32_e32 v138, s41, v138
	v_and_b32_e32 v139, 3, v138
	v_lshlrev_b32_e32 v139, s39, v139
	v_bfe_u32 v140, v138, 2, 2
	v_add_u32_e32 v139, v139, v140
	v_lshl_add_u32 v139, v139, 7, v162
	v_ashrrev_i32_e32 v138, 4, v138
	v_med3_i32 v138, v138, 0, s38
	v_lshl_add_u32 v138, v138, 9, v139
	global_load_dwordx4 v[76:79], v138, s[26:27]
	ds_write_b128 v165, v[80:83]
	ds_write_b128 v165, v[84:87] offset:1152
	ds_write_b128 v165, v[88:91] offset:2304
	ds_write_b128 v165, v[92:95] offset:3456
	v_mfma_f32_16x16x32_bf16 v[204:207], v[236:239], v[112:115], 0
	v_mfma_f32_16x16x32_bf16 v[208:211], v[240:243], v[112:115], 0
	v_mfma_f32_16x16x32_bf16 v[212:215], v[244:247], v[112:115], 0
	v_mfma_f32_16x16x32_bf16 v[216:219], v[248:251], v[112:115], 0
	s_waitcnt lgkmcnt(0)
	ds_read_b64_tr_b16 v[236:237], v166
	ds_read_b64_tr_b16 v[238:239], v166 offset:2304
	ds_read_b64_tr_b16 v[240:241], v166 offset:32
	ds_read_b64_tr_b16 v[242:243], v166 offset:2336
	ds_read_b64_tr_b16 v[244:245], v166 offset:64
	ds_read_b64_tr_b16 v[246:247], v166 offset:2368
	ds_read_b64_tr_b16 v[248:249], v166 offset:96
	ds_read_b64_tr_b16 v[250:251], v166 offset:2400
	s_waitcnt lgkmcnt(0)
	s_add_i32 s2, s40, 64
	v_add_u32_e32 v138, s2, v164
	v_lshlrev_b32_e32 v138, 4, v138
	v_add_u32_e32 v138, s41, v138
	v_and_b32_e32 v139, 3, v138
	v_lshlrev_b32_e32 v139, s39, v139
	v_bfe_u32 v140, v138, 2, 2
	v_add_u32_e32 v139, v139, v140
	v_lshl_add_u32 v139, v139, 7, v162
	v_ashrrev_i32_e32 v138, 4, v138
	v_med3_i32 v138, v138, 0, s38
	v_lshl_add_u32 v138, v138, 9, v139
	global_load_dwordx4 v[80:83], v138, s[26:27]
	s_add_i32 s2, s40, 72
	v_add_u32_e32 v138, s2, v164
	v_lshlrev_b32_e32 v138, 4, v138
	v_add_u32_e32 v138, s41, v138
	v_and_b32_e32 v139, 3, v138
	v_lshlrev_b32_e32 v139, s39, v139
	v_bfe_u32 v140, v138, 2, 2
	v_add_u32_e32 v139, v139, v140
	v_lshl_add_u32 v139, v139, 7, v162
	v_ashrrev_i32_e32 v138, 4, v138
	v_med3_i32 v138, v138, 0, s38
	v_lshl_add_u32 v138, v138, 9, v139
	global_load_dwordx4 v[84:87], v138, s[26:27]
	ds_write_b128 v165, v[96:99]
	ds_write_b128 v165, v[100:103] offset:1152
	ds_write_b128 v165, v[104:107] offset:2304
	ds_write_b128 v165, v[108:111] offset:3456
	v_mfma_f32_16x16x32_bf16 v[204:207], v[236:239], v[116:119], v[204:207]
	v_mfma_f32_16x16x32_bf16 v[208:211], v[240:243], v[116:119], v[208:211]
	v_mfma_f32_16x16x32_bf16 v[212:215], v[244:247], v[116:119], v[212:215]
	v_mfma_f32_16x16x32_bf16 v[216:219], v[248:251], v[116:119], v[216:219]
	s_waitcnt lgkmcnt(0)
	ds_read_b64_tr_b16 v[236:237], v166
	ds_read_b64_tr_b16 v[238:239], v166 offset:2304
	ds_read_b64_tr_b16 v[240:241], v166 offset:32
	ds_read_b64_tr_b16 v[242:243], v166 offset:2336
	ds_read_b64_tr_b16 v[244:245], v166 offset:64
	ds_read_b64_tr_b16 v[246:247], v166 offset:2368
	ds_read_b64_tr_b16 v[248:249], v166 offset:96
	ds_read_b64_tr_b16 v[250:251], v166 offset:2400
	s_waitcnt lgkmcnt(0)
	s_waitcnt vmcnt(2)
	ds_write_b128 v165, v[64:67]
	ds_write_b128 v165, v[68:71] offset:1152
	ds_write_b128 v165, v[72:75] offset:2304
	ds_write_b128 v165, v[76:79] offset:3456
	v_mfma_f32_16x16x32_bf16 v[204:207], v[236:239], v[120:123], v[204:207]
	v_mfma_f32_16x16x32_bf16 v[208:211], v[240:243], v[120:123], v[208:211]
	v_mfma_f32_16x16x32_bf16 v[212:215], v[244:247], v[120:123], v[212:215]
	v_mfma_f32_16x16x32_bf16 v[216:219], v[248:251], v[120:123], v[216:219]
	s_waitcnt lgkmcnt(0)
	ds_read_b64_tr_b16 v[236:237], v166
	ds_read_b64_tr_b16 v[238:239], v166 offset:2304
	ds_read_b64_tr_b16 v[240:241], v166 offset:32
	ds_read_b64_tr_b16 v[242:243], v166 offset:2336
	ds_read_b64_tr_b16 v[244:245], v166 offset:64
	ds_read_b64_tr_b16 v[246:247], v166 offset:2368
	ds_read_b64_tr_b16 v[248:249], v166 offset:96
	ds_read_b64_tr_b16 v[250:251], v166 offset:2400
	s_waitcnt lgkmcnt(0)
	s_waitcnt vmcnt(0)
	ds_write_b128 v165, v[80:83]
	ds_write_b128 v165, v[84:87] offset:1152
	v_mfma_f32_16x16x32_bf16 v[204:207], v[236:239], v[124:127], v[204:207]
	v_mfma_f32_16x16x32_bf16 v[208:211], v[240:243], v[124:127], v[208:211]
	v_mfma_f32_16x16x32_bf16 v[212:215], v[244:247], v[124:127], v[212:215]
	v_mfma_f32_16x16x32_bf16 v[216:219], v[248:251], v[124:127], v[216:219]
	s_waitcnt lgkmcnt(0)
	ds_read_b64_tr_b16 v[236:237], v166
	ds_read_b64_tr_b16 v[238:239], v166 offset:2304
	ds_read_b64_tr_b16 v[240:241], v166 offset:32
	ds_read_b64_tr_b16 v[242:243], v166 offset:2336
	ds_read_b64_tr_b16 v[244:245], v166 offset:64
	ds_read_b64_tr_b16 v[246:247], v166 offset:2368
	ds_read_b64_tr_b16 v[248:249], v166 offset:96
	ds_read_b64_tr_b16 v[250:251], v166 offset:2400
	s_waitcnt lgkmcnt(0)
	v_mfma_f32_16x16x32_bf16 v[204:207], v[236:239], v[128:131], v[204:207]
	v_mfma_f32_16x16x32_bf16 v[208:211], v[240:243], v[128:131], v[208:211]
	v_mfma_f32_16x16x32_bf16 v[212:215], v[244:247], v[128:131], v[212:215]
	v_mfma_f32_16x16x32_bf16 v[216:219], v[248:251], v[128:131], v[216:219]
	s_add_i32 s2, s42, -64
	v_add_u32_e32 v138, s2, v164
	v_add_u32_e32 v138, s43, v138
	v_and_b32_e32 v139, 3, v138
	v_lshlrev_b32_e32 v139, s13, v139
	v_bfe_u32 v140, v138, 2, 2
	v_add_u32_e32 v139, v139, v140
	v_lshl_add_u32 v139, v139, 7, v162
	v_ashrrev_i32_e32 v138, 4, v138
	v_med3_i32 v138, v138, 0, s14
	v_lshl_add_u32 v138, v138, 9, v139
	global_load_dwordx4 v[64:67], v138, s[22:23]
	s_add_i32 s2, s42, -56
	v_add_u32_e32 v138, s2, v164
	v_add_u32_e32 v138, s43, v138
	v_and_b32_e32 v139, 3, v138
	v_lshlrev_b32_e32 v139, s13, v139
	v_bfe_u32 v140, v138, 2, 2
	v_add_u32_e32 v139, v139, v140
	v_lshl_add_u32 v139, v139, 7, v162
	v_ashrrev_i32_e32 v138, 4, v138
	v_med3_i32 v138, v138, 0, s14
	v_lshl_add_u32 v138, v138, 9, v139
	global_load_dwordx4 v[68:71], v138, s[22:23]
	s_add_i32 s2, s42, -48
	v_add_u32_e32 v138, s2, v164
	v_add_u32_e32 v138, s43, v138
	v_and_b32_e32 v139, 3, v138
	v_lshlrev_b32_e32 v139, s13, v139
	v_bfe_u32 v140, v138, 2, 2
	v_add_u32_e32 v139, v139, v140
	v_lshl_add_u32 v139, v139, 7, v162
	v_ashrrev_i32_e32 v138, 4, v138
	v_med3_i32 v138, v138, 0, s14
	v_lshl_add_u32 v138, v138, 9, v139
	global_load_dwordx4 v[72:75], v138, s[22:23]
	s_add_i32 s2, s42, -40
	v_add_u32_e32 v138, s2, v164
	v_add_u32_e32 v138, s43, v138
	v_and_b32_e32 v139, 3, v138
	v_lshlrev_b32_e32 v139, s13, v139
	v_bfe_u32 v140, v138, 2, 2
	v_add_u32_e32 v139, v139, v140
	v_lshl_add_u32 v139, v139, 7, v162
	v_ashrrev_i32_e32 v138, 4, v138
	v_med3_i32 v138, v138, 0, s14
	v_lshl_add_u32 v138, v138, 9, v139
	global_load_dwordx4 v[76:79], v138, s[22:23]
	s_add_i32 s2, s42, -32
	v_add_u32_e32 v138, s2, v164
	v_add_u32_e32 v138, s43, v138
	v_and_b32_e32 v139, 3, v138
	v_lshlrev_b32_e32 v139, s13, v139
	v_bfe_u32 v140, v138, 2, 2
	v_add_u32_e32 v139, v139, v140
	v_lshl_add_u32 v139, v139, 7, v162
	v_ashrrev_i32_e32 v138, 4, v138
	v_med3_i32 v138, v138, 0, s14
	v_lshl_add_u32 v138, v138, 9, v139
	global_load_dwordx4 v[80:83], v138, s[22:23]
	s_add_i32 s2, s42, -24
	v_add_u32_e32 v138, s2, v164
	v_add_u32_e32 v138, s43, v138
	v_and_b32_e32 v139, 3, v138
	v_lshlrev_b32_e32 v139, s13, v139
	v_bfe_u32 v140, v138, 2, 2
	v_add_u32_e32 v139, v139, v140
	v_lshl_add_u32 v139, v139, 7, v162
	v_ashrrev_i32_e32 v138, 4, v138
	v_med3_i32 v138, v138, 0, s14
	v_lshl_add_u32 v138, v138, 9, v139
	global_load_dwordx4 v[84:87], v138, s[22:23]
	s_add_i32 s2, s42, -16
	v_add_u32_e32 v138, s2, v164
	v_add_u32_e32 v138, s43, v138
	v_and_b32_e32 v139, 3, v138
	v_lshlrev_b32_e32 v139, s13, v139
	v_bfe_u32 v140, v138, 2, 2
	v_add_u32_e32 v139, v139, v140
	v_lshl_add_u32 v139, v139, 7, v162
	v_ashrrev_i32_e32 v138, 4, v138
	v_med3_i32 v138, v138, 0, s14
	v_lshl_add_u32 v138, v138, 9, v139
	global_load_dwordx4 v[88:91], v138, s[22:23]
	s_add_i32 s2, s42, -8
	v_add_u32_e32 v138, s2, v164
	v_add_u32_e32 v138, s43, v138
	v_and_b32_e32 v139, 3, v138
	v_lshlrev_b32_e32 v139, s13, v139
	v_bfe_u32 v140, v138, 2, 2
	v_add_u32_e32 v139, v139, v140
	v_lshl_add_u32 v139, v139, 7, v162
	v_ashrrev_i32_e32 v138, 4, v138
	v_med3_i32 v138, v138, 0, s14
	v_lshl_add_u32 v138, v138, 9, v139
	global_load_dwordx4 v[92:95], v138, s[22:23]
	s_add_i32 s2, s42, 0
	v_add_u32_e32 v138, s2, v164
	v_add_u32_e32 v138, s43, v138
	v_and_b32_e32 v139, 3, v138
	v_lshlrev_b32_e32 v139, s13, v139
	v_bfe_u32 v140, v138, 2, 2
	v_add_u32_e32 v139, v139, v140
	v_lshl_add_u32 v139, v139, 7, v162
	v_ashrrev_i32_e32 v138, 4, v138
	v_med3_i32 v138, v138, 0, s14
	v_lshl_add_u32 v138, v138, 9, v139
	global_load_dwordx4 v[96:99], v138, s[22:23]
	s_add_i32 s2, s42, 8
	v_add_u32_e32 v138, s2, v164
	v_add_u32_e32 v138, s43, v138
	v_and_b32_e32 v139, 3, v138
	v_lshlrev_b32_e32 v139, s13, v139
	v_bfe_u32 v140, v138, 2, 2
	v_add_u32_e32 v139, v139, v140
	v_lshl_add_u32 v139, v139, 7, v162
	v_ashrrev_i32_e32 v138, 4, v138
	v_med3_i32 v138, v138, 0, s14
	v_lshl_add_u32 v138, v138, 9, v139
	global_load_dwordx4 v[100:103], v138, s[22:23]
	s_add_i32 s2, s42, 16
	v_add_u32_e32 v138, s2, v164
	v_add_u32_e32 v138, s43, v138
	v_and_b32_e32 v139, 3, v138
	v_lshlrev_b32_e32 v139, s13, v139
	v_bfe_u32 v140, v138, 2, 2
	v_add_u32_e32 v139, v139, v140
	v_lshl_add_u32 v139, v139, 7, v162
	v_ashrrev_i32_e32 v138, 4, v138
	v_med3_i32 v138, v138, 0, s14
	v_lshl_add_u32 v138, v138, 9, v139
	global_load_dwordx4 v[104:107], v138, s[22:23]
	s_add_i32 s2, s42, 24
	v_add_u32_e32 v138, s2, v164
	v_add_u32_e32 v138, s43, v138
	v_and_b32_e32 v139, 3, v138
	v_lshlrev_b32_e32 v139, s13, v139
	v_bfe_u32 v140, v138, 2, 2
	v_add_u32_e32 v139, v139, v140
	v_lshl_add_u32 v139, v139, 7, v162
	v_ashrrev_i32_e32 v138, 4, v138
	v_med3_i32 v138, v138, 0, s14
	v_lshl_add_u32 v138, v138, 9, v139
	global_load_dwordx4 v[108:111], v138, s[22:23]
	ds_read_b128 v[236:239], v173 offset:0
	ds_read_b128 v[240:243], v173 offset:64
	ds_read_b128 v[244:247], v173 offset:128
	ds_read_b128 v[248:251], v173 offset:192
	ds_read_b32 v142, v174 offset:0
	s_waitcnt lgkmcnt(0)
	v_add_f32_e32 v204, v236, v204
	v_add_f32_e32 v205, v237, v205
	v_add_f32_e32 v206, v238, v206
	v_add_f32_e32 v207, v239, v207
	v_add_f32_e32 v208, v240, v208
	v_add_f32_e32 v209, v241, v209
	v_add_f32_e32 v210, v242, v210
	v_add_f32_e32 v211, v243, v211
	v_add_f32_e32 v212, v244, v212
	v_add_f32_e32 v213, v245, v213
	v_add_f32_e32 v214, v246, v214
	v_add_f32_e32 v215, v247, v215
	v_add_f32_e32 v216, v248, v216
	v_add_f32_e32 v217, v249, v217
	v_add_f32_e32 v218, v250, v218
	v_add_f32_e32 v219, v251, v219
	v_add_f32_e32 v132, v142, v132
	ds_write_b128 v173, v[204:207] offset:0
	ds_write_b128 v173, v[208:211] offset:64
	ds_write_b128 v173, v[212:215] offset:128
	ds_write_b128 v173, v[216:219] offset:192
	ds_write_b32 v174, v132 offset:0
	s_waitcnt lgkmcnt(0)
	s_barrier
	ds_read_b128 v[204:207], v170
	ds_read_b128 v[208:211], v170 offset:16
	ds_read_b128 v[212:215], v170 offset:32
	ds_read_b128 v[216:219], v170 offset:48
	ds_read_b128 v[220:223], v170 offset:64
	ds_read_b128 v[224:227], v170 offset:80
	ds_read_b128 v[228:231], v170 offset:96
	ds_read_b128 v[232:235], v170 offset:112
	ds_read_b32 v142, v171
	s_lshl_b32 s2, s35, 11
	s_lshl_b32 s3, s36, 7
	s_add_u32 s2, s2, s3
	s_add_u32 s90, s6, s2
	s_addc_u32 s91, s7, 0
	s_waitcnt lgkmcnt(0)
	v_div_scale_f32 v143, s[30:31], v142, v142, 1.0
	v_rcp_f32_e32 v147, v143
	v_div_scale_f32 v134, vcc, 1.0, v142, 1.0
	v_fma_f32 v135, -v143, v147, 1.0
	v_fmac_f32_e32 v147, v135, v147
	v_mul_f32_e32 v135, v134, v147
	v_fma_f32 v136, -v143, v135, v134
	v_fmac_f32_e32 v135, v136, v147
	v_fma_f32 v143, -v143, v135, v134
	v_div_fmas_f32 v143, v143, v147, v135
	v_div_fixup_f32 v142, v143, v142, 1.0
	v_mul_f32_e32 v204, v142, v204
	v_mul_f32_e32 v205, v142, v205
	v_mul_f32_e32 v206, v142, v206
	v_mul_f32_e32 v207, v142, v207
	v_mul_f32_e32 v208, v142, v208
	v_mul_f32_e32 v209, v142, v209
	v_mul_f32_e32 v210, v142, v210
	v_mul_f32_e32 v211, v142, v211
	v_mul_f32_e32 v212, v142, v212
	v_mul_f32_e32 v213, v142, v213
	v_mul_f32_e32 v214, v142, v214
	v_mul_f32_e32 v215, v142, v215
	v_mul_f32_e32 v216, v142, v216
	v_mul_f32_e32 v217, v142, v217
	v_mul_f32_e32 v218, v142, v218
	v_mul_f32_e32 v219, v142, v219
	v_mul_f32_e32 v220, v142, v220
	v_mul_f32_e32 v221, v142, v221
	v_mul_f32_e32 v222, v142, v222
	v_mul_f32_e32 v223, v142, v223
	v_mul_f32_e32 v224, v142, v224
	v_mul_f32_e32 v225, v142, v225
	v_mul_f32_e32 v226, v142, v226
	v_mul_f32_e32 v227, v142, v227
	v_mul_f32_e32 v228, v142, v228
	v_mul_f32_e32 v229, v142, v229
	v_mul_f32_e32 v230, v142, v230
	v_mul_f32_e32 v231, v142, v231
	v_mul_f32_e32 v232, v142, v232
	v_mul_f32_e32 v233, v142, v233
	v_mul_f32_e32 v234, v142, v234
	v_mul_f32_e32 v235, v142, v235
	v_cvt_pk_bf16_f32 v112, v204, v205
	v_cvt_pk_bf16_f32 v113, v206, v207
	v_cvt_pk_bf16_f32 v114, v208, v209
	v_cvt_pk_bf16_f32 v115, v210, v211
	v_cvt_pk_bf16_f32 v116, v212, v213
	v_cvt_pk_bf16_f32 v117, v214, v215
	v_cvt_pk_bf16_f32 v118, v216, v217
	v_cvt_pk_bf16_f32 v119, v218, v219
	v_cvt_pk_bf16_f32 v120, v220, v221
	v_cvt_pk_bf16_f32 v121, v222, v223
	v_cvt_pk_bf16_f32 v122, v224, v225
	v_cvt_pk_bf16_f32 v123, v226, v227
	v_cvt_pk_bf16_f32 v124, v228, v229
	v_cvt_pk_bf16_f32 v125, v230, v231
	v_cvt_pk_bf16_f32 v126, v232, v233
	v_cvt_pk_bf16_f32 v127, v234, v235
	global_store_dwordx4 v172, v[112:115], s[90:91] nt
	global_store_dwordx4 v172, v[116:119], s[90:91] offset:16 nt
	global_store_dwordx4 v172, v[120:123], s[90:91] offset:32 nt
	global_store_dwordx4 v172, v[124:127], s[90:91] offset:48 nt
	s_barrier
	s_cmp_eq_u32 s37, 0
	s_cbranch_scc1 .Latt_unit
	s_waitcnt vmcnt(0)
	s_branch .LBB0_365
